# remove 54 duplicate lgkmcnt(0) waits (compiler copy right after the inline-asm one) in the nine GEMM main loops, on top of v7
# speedup vs baseline: 1.0107x; 1.0107x over previous
; #define PG8_STAGE(bufoff, gbase, voff) do { _Pragma("unroll") for (int _i = 0; _i < 2; ++_i) \
;         __builtin_amdgcn_global_load_lds((const unsigned*)((const char*)(gbase) + (voff)[_i]), (PG8_LAS unsigned*)(lds + (bufoff) + ldsw + _i * 8192), 16, 0, 0); } while (0)
; #define PG8_LDA(dst, b, h) do { _Pragma("unroll") for (int m = 0; m < 4; ++m) _Pragma("unroll") for (int k = 0; k < 2; ++k) dst[m][k] = *(const PG8_LAS bf16x8*)(lds + PG8_SA(b, h) + aoff + m * 2048 + k * 1024); } while (0)
; #define PG8_LDB(dst, b, h) do { _Pragma("unroll") for (int n = 0; n < 2; ++n) _Pragma("unroll") for (int k = 0; k < 2; ++k) dst[n][k] = *(const PG8_LAS bf16x8*)(lds + PG8_SB(b, h) + boff + n * 2048 + k * 1024); } while (0)
; #define PG8_MMA(ai, bj, At, Bt) do { __builtin_amdgcn_s_setprio(1); _Pragma("unroll") for (int m = 0; m < 4; ++m) _Pragma("unroll") for (int n = 0; n < 2; ++n) _Pragma("unroll") for (int k = 0; k < 2; ++k) \
;         acc[ai][bj][m][n] = __builtin_amdgcn_mfma_f32_16x16x32_bf16(Bt[n][k], At[m][k], acc[ai][bj][m][n], 0, 0, 0); __builtin_amdgcn_s_setprio(0); } while (0)
; #define PG8_WAIT_L(n) asm volatile("s_waitcnt lgkmcnt(" #n ")" ::: "memory")
; #define PG8_BAR __builtin_amdgcn_s_barrier()
; #define PG8_SCHED __builtin_amdgcn_sched_barrier(0)
; template <class Epi, class Sched>
; __device__ __forceinline__ void gemm_phase(PG8_LAS unsigned char* lds, const Gemm g, const Sched& S, const Epi& E) {
;     ...
;             const bool last = (t == cnk - 2);
;             const char* a1 = cA + (size_t)(t + 1) * kstep;
;             const char* a2 = last ? nA : cA + (size_t)(t + 2) * kstep; const char* b2 = last ? nB : cB + (size_t)(t + 2) * kstep;
;             const char* a3 = a2 + kstep; const char* b3 = b2 + kstep;
;     ...
;             PG8_LDB(B0, 0, 0); PG8_SCHED; PG8_LDA(At, 0, 0); PG8_STAGE(PG8_SA(1, 1), a1 + hstep, voffA);
;             PG8_WAIT_L(8); PG8_BAR; PG8_WAIT_L(0); PG8_MMA(0, 0, At, B0); PG8_BAR; PG8_SCHED;
;             PG8_LDB(B1, 0, 1); PG8_STAGE(PG8_SB(0, 0), b2, voffB);
;             PG8_BAR; PG8_WAIT_L(0); PG8_MMA(0, 1, At, B1); PG8_BAR;
;             PG8_LDA(At, 0, 1); PG8_STAGE(PG8_SA(0, 0), a2, voffA);
;             PG8_BAR; PG8_WAIT_L(0); PG8_MMA(1, 0, At, B0); PG8_BAR; PG8_SCHED;
.LBB0_194:
	v_add_u32_e32 v14, s6, v155
	ds_read_b128 v[24:27], v14
	ds_read_b128 v[32:35], v14 offset:1024
	ds_read_b128 v[36:39], v14 offset:2048
	ds_read_b128 v[144:147], v14 offset:3072
	s_add_u32 s22, s0, 0xfffc0080
	s_addc_u32 s23, s1, -1
	s_and_b64 s[20:21], s[20:21], exec
	s_cselect_b32 s23, s11, s23
	s_cselect_b32 s22, s15, s22
	s_cselect_b32 s21, s13, s2
	s_cselect_b32 s20, vcc_lo, vcc_hi
	v_lshl_add_u64 v[14:15], s[0:1], 0, v[176:177]
	s_add_i32 m0, s25, 0xc000
	ds_read_b128 v[148:151], v163
	ds_read_b128 v[192:195], v163 offset:1024
	ds_read_b128 v[196:199], v163 offset:2048
	ds_read_b128 v[200:203], v163 offset:3072
	ds_read_b128 v[210:213], v163 offset:4096
	ds_read_b128 v[214:217], v163 offset:5120
	ds_read_b128 v[218:221], v163 offset:6144
	ds_read_b128 v[222:225], v163 offset:7168
	global_load_lds_dwordx4 v[14:15], off
	v_lshl_add_u64 v[14:15], s[0:1], 0, v[178:179]
	s_add_i32 m0, s25, 0xe000
	s_nop 0
	global_load_lds_dwordx4 v[14:15], off
	s_waitcnt lgkmcnt(8)
	s_barrier
	s_waitcnt lgkmcnt(0)
	s_setprio 1
	v_mfma_f32_16x16x32_bf16 v[140:143], v[24:27], v[148:151], v[140:143]
	v_mfma_f32_16x16x32_bf16 v[136:139], v[36:39], v[148:151], v[136:139]
	v_mfma_f32_16x16x32_bf16 v[124:127], v[24:27], v[196:199], v[124:127]
	v_mfma_f32_16x16x32_bf16 v[120:123], v[36:39], v[196:199], v[120:123]
	v_mfma_f32_16x16x32_bf16 v[108:111], v[24:27], v[210:213], v[108:111]
	v_mfma_f32_16x16x32_bf16 v[104:107], v[36:39], v[210:213], v[104:107]
	v_mfma_f32_16x16x32_bf16 v[92:95], v[24:27], v[218:221], v[92:95]
	v_mfma_f32_16x16x32_bf16 v[88:91], v[36:39], v[218:221], v[88:91]
	v_mfma_f32_16x16x32_bf16 v[140:143], v[32:35], v[192:195], v[140:143]
	v_mfma_f32_16x16x32_bf16 v[136:139], v[144:147], v[192:195], v[136:139]
	v_mfma_f32_16x16x32_bf16 v[124:127], v[32:35], v[200:203], v[124:127]
	v_mfma_f32_16x16x32_bf16 v[120:123], v[144:147], v[200:203], v[120:123]
	v_mfma_f32_16x16x32_bf16 v[108:111], v[32:35], v[214:217], v[108:111]
	v_mfma_f32_16x16x32_bf16 v[104:107], v[144:147], v[214:217], v[104:107]
	v_mfma_f32_16x16x32_bf16 v[92:95], v[32:35], v[222:225], v[92:95]
	v_mfma_f32_16x16x32_bf16 v[88:91], v[144:147], v[222:225], v[88:91]
	s_setprio 0
	s_barrier
	s_add_i32 s96, s6, s9
	v_add_u32_e32 v14, s8, v155
	v_lshl_add_u64 v[204:205], s[20:21], 0, v[166:167]
	s_mov_b32 m0, s96
	ds_read_b128 v[226:229], v14
	ds_read_b128 v[230:233], v14 offset:1024
	ds_read_b128 v[234:237], v14 offset:2048
	ds_read_b128 v[238:241], v14 offset:3072
	global_load_lds_dwordx4 v[204:205], off
	v_lshl_add_u64 v[242:243], s[20:21], 0, v[170:171]
	s_add_i32 m0, s96, 0x2000
	s_nop 0
	global_load_lds_dwordx4 v[242:243], off
	s_barrier
	s_waitcnt lgkmcnt(0)
	s_setprio 1
	v_mfma_f32_16x16x32_bf16 v[132:135], v[226:229], v[148:151], v[132:135]
	v_mfma_f32_16x16x32_bf16 v[128:131], v[234:237], v[148:151], v[128:131]
	v_mfma_f32_16x16x32_bf16 v[116:119], v[226:229], v[196:199], v[116:119]
	v_mfma_f32_16x16x32_bf16 v[112:115], v[234:237], v[196:199], v[112:115]
	v_mfma_f32_16x16x32_bf16 v[100:103], v[226:229], v[210:213], v[100:103]
	v_mfma_f32_16x16x32_bf16 v[96:99], v[234:237], v[210:213], v[96:99]
	v_mfma_f32_16x16x32_bf16 v[84:87], v[226:229], v[218:221], v[84:87]
	v_mfma_f32_16x16x32_bf16 v[80:83], v[234:237], v[218:221], v[80:83]
	v_mfma_f32_16x16x32_bf16 v[132:135], v[230:233], v[192:195], v[132:135]
	v_mfma_f32_16x16x32_bf16 v[128:131], v[238:241], v[192:195], v[128:131]
	v_mfma_f32_16x16x32_bf16 v[116:119], v[230:233], v[200:203], v[116:119]
	v_mfma_f32_16x16x32_bf16 v[112:115], v[238:241], v[200:203], v[112:115]
	v_mfma_f32_16x16x32_bf16 v[100:103], v[230:233], v[214:217], v[100:103]
	v_mfma_f32_16x16x32_bf16 v[96:99], v[238:241], v[214:217], v[96:99]
	v_mfma_f32_16x16x32_bf16 v[84:87], v[230:233], v[222:225], v[84:87]
	v_mfma_f32_16x16x32_bf16 v[80:83], v[238:241], v[222:225], v[80:83]
	s_setprio 0
	s_mov_b32 m0, s25
	v_lshl_add_u64 v[244:245], s[22:23], 0, v[164:165]
	s_barrier
	ds_read_b128 v[148:151], v163 offset:16384
	ds_read_b128 v[192:195], v163 offset:17408
	ds_read_b128 v[196:199], v163 offset:18432
	ds_read_b128 v[200:203], v163 offset:19456
	ds_read_b128 v[210:213], v163 offset:20480
	ds_read_b128 v[214:217], v163 offset:21504
	ds_read_b128 v[218:221], v163 offset:22528
	ds_read_b128 v[222:225], v163 offset:23552
	global_load_lds_dwordx4 v[244:245], off
	v_lshl_add_u64 v[246:247], s[22:23], 0, v[168:169]
	s_mov_b32 m0, s26
	s_nop 0
	global_load_lds_dwordx4 v[246:247], off
	s_barrier
	s_waitcnt lgkmcnt(0)
	s_setprio 1
	v_mfma_f32_16x16x32_bf16 v[76:79], v[24:27], v[148:151], v[76:79]
	v_mfma_f32_16x16x32_bf16 v[72:75], v[36:39], v[148:151], v[72:75]
	v_mfma_f32_16x16x32_bf16 v[60:63], v[24:27], v[196:199], v[60:63]
	v_mfma_f32_16x16x32_bf16 v[56:59], v[36:39], v[196:199], v[56:59]
	v_mfma_f32_16x16x32_bf16 v[44:47], v[24:27], v[210:213], v[44:47]
	v_mfma_f32_16x16x32_bf16 v[40:43], v[36:39], v[210:213], v[40:43]
	v_mfma_f32_16x16x32_bf16 v[14:17], v[24:27], v[218:221], v[16:19]
	v_mfma_f32_16x16x32_bf16 v[8:11], v[36:39], v[218:221], v[8:11]
	v_mfma_f32_16x16x32_bf16 v[76:79], v[32:35], v[192:195], v[76:79]
	v_mfma_f32_16x16x32_bf16 v[72:75], v[144:147], v[192:195], v[72:75]
	v_mfma_f32_16x16x32_bf16 v[60:63], v[32:35], v[200:203], v[60:63]
	v_mfma_f32_16x16x32_bf16 v[56:59], v[144:147], v[200:203], v[56:59]
	v_mfma_f32_16x16x32_bf16 v[44:47], v[32:35], v[214:217], v[44:47]
	v_mfma_f32_16x16x32_bf16 v[40:43], v[144:147], v[214:217], v[40:43]
	v_mfma_f32_16x16x32_bf16 v[14:17], v[32:35], v[222:225], v[14:17]
	v_mfma_f32_16x16x32_bf16 v[8:11], v[144:147], v[222:225], v[8:11]
	s_setprio 0
	s_barrier
; #define PG8_STAGE(bufoff, gbase, voff) do { _Pragma("unroll") for (int _i = 0; _i < 2; ++_i) \
;         __builtin_amdgcn_global_load_lds((const unsigned*)((const char*)(gbase) + (voff)[_i]), (PG8_LAS unsigned*)(lds + (bufoff) + ldsw + _i * 8192), 16, 0, 0); } while (0)
; #define PG8_LDA(dst, b, h) do { _Pragma("unroll") for (int m = 0; m < 4; ++m) _Pragma("unroll") for (int k = 0; k < 2; ++k) dst[m][k] = *(const PG8_LAS bf16x8*)(lds + PG8_SA(b, h) + aoff + m * 2048 + k * 1024); } while (0)
; #define PG8_LDB(dst, b, h) do { _Pragma("unroll") for (int n = 0; n < 2; ++n) _Pragma("unroll") for (int k = 0; k < 2; ++k) dst[n][k] = *(const PG8_LAS bf16x8*)(lds + PG8_SB(b, h) + boff + n * 2048 + k * 1024); } while (0)
; #define PG8_MMA(ai, bj, At, Bt) do { __builtin_amdgcn_s_setprio(1); _Pragma("unroll") for (int m = 0; m < 4; ++m) _Pragma("unroll") for (int n = 0; n < 2; ++n) _Pragma("unroll") for (int k = 0; k < 2; ++k) \
;         acc[ai][bj][m][n] = __builtin_amdgcn_mfma_f32_16x16x32_bf16(Bt[n][k], At[m][k], acc[ai][bj][m][n], 0, 0, 0); __builtin_amdgcn_s_setprio(0); } while (0)
; #define PG8_WAIT_V(n) asm volatile("s_waitcnt vmcnt(" #n ")" ::: "memory")
; #define PG8_WAIT_L(n) asm volatile("s_waitcnt lgkmcnt(" #n ")" ::: "memory")
; #define PG8_BAR __builtin_amdgcn_s_barrier()
; #define PG8_SCHED __builtin_amdgcn_sched_barrier(0)
; template <class Epi, class Sched>
; __device__ __forceinline__ void gemm_phase(PG8_LAS unsigned char* lds, const Gemm g, const Sched& S, const Epi& E) {
;     ...
;             PG8_STAGE(PG8_SB(0, 1), b2 + hstep, voffB);
;             PG8_WAIT_V(6); PG8_BAR; PG8_MMA(1, 1, At, B1); PG8_BAR;
;             PG8_LDB(B0, 1, 0); PG8_SCHED; PG8_LDA(At, 1, 0); PG8_STAGE(PG8_SA(0, 1), a2 + hstep, voffA);
;             PG8_WAIT_L(8); PG8_BAR; PG8_WAIT_L(0); PG8_MMA(0, 0, At, B0); PG8_BAR; PG8_SCHED;
;             PG8_LDB(B1, 1, 1); PG8_STAGE(PG8_SB(1, 0), b3, voffB);
	s_add_u32 s96, s20, 0x40000
	s_addc_u32 s97, s21, 0
	s_add_i32 s30, s8, s9
	v_lshl_add_u64 v[18:19], s[96:97], 0, v[166:167]
	s_mov_b32 m0, s30
	s_nop 0
	global_load_lds_dwordx4 v[18:19], off
	v_lshl_add_u64 v[18:19], s[96:97], 0, v[170:171]
	s_add_i32 m0, s30, 0x2000
	s_nop 0
	global_load_lds_dwordx4 v[18:19], off
	s_waitcnt vmcnt(6)
	s_barrier
	s_setprio 1
	v_mfma_f32_16x16x32_bf16 v[48:51], v[234:237], v[196:199], v[48:51]
	v_mfma_f32_16x16x32_bf16 v[28:31], v[226:229], v[210:213], v[28:31]
	v_mfma_f32_16x16x32_bf16 v[18:21], v[234:237], v[210:213], v[20:23]
	v_mfma_f32_16x16x32_bf16 v[4:7], v[226:229], v[218:221], v[4:7]
	v_mfma_f32_16x16x32_bf16 v[0:3], v[234:237], v[218:221], v[0:3]
	v_mfma_f32_16x16x32_bf16 v[24:27], v[226:229], v[148:151], v[68:71]
	v_mfma_f32_16x16x32_bf16 v[32:35], v[234:237], v[148:151], v[64:67]
	v_mfma_f32_16x16x32_bf16 v[36:39], v[226:229], v[196:199], v[52:55]
	v_mfma_f32_16x16x32_bf16 v[48:51], v[238:241], v[200:203], v[48:51]
	v_mfma_f32_16x16x32_bf16 v[28:31], v[230:233], v[214:217], v[28:31]
	v_mfma_f32_16x16x32_bf16 v[20:23], v[238:241], v[214:217], v[18:21]
	v_mfma_f32_16x16x32_bf16 v[4:7], v[230:233], v[222:225], v[4:7]
	v_mfma_f32_16x16x32_bf16 v[0:3], v[238:241], v[222:225], v[0:3]
	v_mfma_f32_16x16x32_bf16 v[24:27], v[230:233], v[192:195], v[24:27]
	v_mfma_f32_16x16x32_bf16 v[32:35], v[238:241], v[192:195], v[32:35]
	v_mfma_f32_16x16x32_bf16 v[36:39], v[230:233], v[200:203], v[36:39]
	s_setprio 0
	s_add_i32 s30, 0, 0x18000
	v_add_u32_e32 v18, s30, v155
	s_barrier
	ds_read_b128 v[52:55], v18
	ds_read_b128 v[64:67], v18 offset:1024
	ds_read_b128 v[68:71], v18 offset:2048
	ds_read_b128 v[144:147], v18 offset:3072
	s_add_u32 s22, s22, 0x40000
	s_addc_u32 s23, s23, 0
	s_mov_b32 m0, s27
	v_lshl_add_u64 v[18:19], s[22:23], 0, v[164:165]
	ds_read_b128 v[148:151], v163 offset:32768
	ds_read_b128 v[192:195], v163 offset:33792
	ds_read_b128 v[196:199], v163 offset:34816
	ds_read_b128 v[200:203], v163 offset:35840
	ds_read_b128 v[210:213], v163 offset:36864
	ds_read_b128 v[214:217], v163 offset:37888
	ds_read_b128 v[218:221], v163 offset:38912
	ds_read_b128 v[222:225], v163 offset:39936
	global_load_lds_dwordx4 v[18:19], off
	v_lshl_add_u64 v[18:19], s[22:23], 0, v[168:169]
	s_mov_b32 m0, s31
	s_nop 0
	global_load_lds_dwordx4 v[18:19], off
	s_waitcnt lgkmcnt(8)
	s_barrier
	s_waitcnt lgkmcnt(0)
	s_setprio 1
	v_mfma_f32_16x16x32_bf16 v[140:143], v[52:55], v[148:151], v[140:143]
	v_mfma_f32_16x16x32_bf16 v[136:139], v[68:71], v[148:151], v[136:139]
	v_mfma_f32_16x16x32_bf16 v[124:127], v[52:55], v[196:199], v[124:127]
	v_mfma_f32_16x16x32_bf16 v[120:123], v[68:71], v[196:199], v[120:123]
	v_mfma_f32_16x16x32_bf16 v[108:111], v[52:55], v[210:213], v[108:111]
	v_mfma_f32_16x16x32_bf16 v[104:107], v[68:71], v[210:213], v[104:107]
	v_mfma_f32_16x16x32_bf16 v[92:95], v[52:55], v[218:221], v[92:95]
	v_mfma_f32_16x16x32_bf16 v[88:91], v[68:71], v[218:221], v[88:91]
	v_mfma_f32_16x16x32_bf16 v[140:143], v[64:67], v[192:195], v[140:143]
	v_mfma_f32_16x16x32_bf16 v[136:139], v[144:147], v[192:195], v[136:139]
	v_mfma_f32_16x16x32_bf16 v[124:127], v[64:67], v[200:203], v[124:127]
	v_mfma_f32_16x16x32_bf16 v[120:123], v[144:147], v[200:203], v[120:123]
	v_mfma_f32_16x16x32_bf16 v[108:111], v[64:67], v[214:217], v[108:111]
	v_mfma_f32_16x16x32_bf16 v[104:107], v[144:147], v[214:217], v[104:107]
	v_mfma_f32_16x16x32_bf16 v[92:95], v[64:67], v[222:225], v[92:95]
	v_mfma_f32_16x16x32_bf16 v[88:91], v[144:147], v[222:225], v[88:91]
	s_setprio 0
	s_barrier
	s_add_i32 s22, 0, 0x1c000
	v_add_u32_e32 v18, s22, v155
	s_add_i32 s23, s30, s9
	ds_read_b128 v[226:229], v18
	ds_read_b128 v[230:233], v18 offset:1024
	ds_read_b128 v[234:237], v18 offset:2048
	ds_read_b128 v[238:241], v18 offset:3072
	v_lshl_add_u64 v[18:19], v[204:205], 0, s[4:5]
	s_mov_b32 m0, s23
	s_nop 0
	global_load_lds_dwordx4 v[18:19], off
	v_lshl_add_u64 v[18:19], v[242:243], 0, s[4:5]
	s_add_i32 m0, s23, 0x2000
	s_nop 0
	global_load_lds_dwordx4 v[18:19], off
	s_barrier
; #define PG8_STAGE(bufoff, gbase, voff) do { _Pragma("unroll") for (int _i = 0; _i < 2; ++_i) \
;         __builtin_amdgcn_global_load_lds((const unsigned*)((const char*)(gbase) + (voff)[_i]), (PG8_LAS unsigned*)(lds + (bufoff) + ldsw + _i * 8192), 16, 0, 0); } while (0)
; #define PG8_LDA(dst, b, h) do { _Pragma("unroll") for (int m = 0; m < 4; ++m) _Pragma("unroll") for (int k = 0; k < 2; ++k) dst[m][k] = *(const PG8_LAS bf16x8*)(lds + PG8_SA(b, h) + aoff + m * 2048 + k * 1024); } while (0)
; #define PG8_MMA(ai, bj, At, Bt) do { __builtin_amdgcn_s_setprio(1); _Pragma("unroll") for (int m = 0; m < 4; ++m) _Pragma("unroll") for (int n = 0; n < 2; ++n) _Pragma("unroll") for (int k = 0; k < 2; ++k) \
;         acc[ai][bj][m][n] = __builtin_amdgcn_mfma_f32_16x16x32_bf16(Bt[n][k], At[m][k], acc[ai][bj][m][n], 0, 0, 0); __builtin_amdgcn_s_setprio(0); } while (0)
; #define PG8_WAIT_V(n) asm volatile("s_waitcnt vmcnt(" #n ")" ::: "memory")
; #define PG8_WAIT_L(n) asm volatile("s_waitcnt lgkmcnt(" #n ")" ::: "memory")
; #define PG8_BAR __builtin_amdgcn_s_barrier()
; #define PG8_SCHED __builtin_amdgcn_sched_barrier(0)
; template <class Epi, class Sched>
; __device__ __forceinline__ void gemm_phase(PG8_LAS unsigned char* lds, const Gemm g, const Sched& S, const Epi& E) {
;     ...
;             PG8_BAR; PG8_WAIT_L(0); PG8_MMA(0, 1, At, B1); PG8_BAR;
;             PG8_LDA(At, 1, 1); PG8_STAGE(PG8_SA(1, 0), a3, voffA);
;             PG8_BAR; PG8_WAIT_L(0); PG8_MMA(1, 0, At, B0); PG8_BAR; PG8_SCHED;
;             PG8_STAGE(PG8_SB(1, 1), b3 + hstep, voffB);
;             PG8_WAIT_V(6); PG8_BAR; PG8_MMA(1, 1, At, B1); PG8_BAR;
	s_waitcnt lgkmcnt(0)
	s_setprio 1
	v_mfma_f32_16x16x32_bf16 v[132:135], v[226:229], v[148:151], v[132:135]
	v_mfma_f32_16x16x32_bf16 v[128:131], v[234:237], v[148:151], v[128:131]
	v_mfma_f32_16x16x32_bf16 v[116:119], v[226:229], v[196:199], v[116:119]
	v_mfma_f32_16x16x32_bf16 v[112:115], v[234:237], v[196:199], v[112:115]
	v_mfma_f32_16x16x32_bf16 v[100:103], v[226:229], v[210:213], v[100:103]
	v_mfma_f32_16x16x32_bf16 v[96:99], v[234:237], v[210:213], v[96:99]
	v_mfma_f32_16x16x32_bf16 v[84:87], v[226:229], v[218:221], v[84:87]
	v_mfma_f32_16x16x32_bf16 v[80:83], v[234:237], v[218:221], v[80:83]
	v_mfma_f32_16x16x32_bf16 v[132:135], v[230:233], v[192:195], v[132:135]
	v_mfma_f32_16x16x32_bf16 v[128:131], v[238:241], v[192:195], v[128:131]
	v_mfma_f32_16x16x32_bf16 v[116:119], v[230:233], v[200:203], v[116:119]
	v_mfma_f32_16x16x32_bf16 v[112:115], v[238:241], v[200:203], v[112:115]
	v_mfma_f32_16x16x32_bf16 v[100:103], v[230:233], v[214:217], v[100:103]
	v_mfma_f32_16x16x32_bf16 v[96:99], v[238:241], v[214:217], v[96:99]
	v_mfma_f32_16x16x32_bf16 v[84:87], v[230:233], v[222:225], v[84:87]
	v_mfma_f32_16x16x32_bf16 v[80:83], v[238:241], v[222:225], v[80:83]
	s_setprio 0
	s_mov_b32 m0, s33
	v_lshl_add_u64 v[18:19], v[244:245], 0, s[4:5]
	s_barrier
	ds_read_b128 v[148:151], v163 offset:49152
	ds_read_b128 v[192:195], v163 offset:50176
	ds_read_b128 v[196:199], v163 offset:51200
	ds_read_b128 v[200:203], v163 offset:52224
	ds_read_b128 v[210:213], v163 offset:53248
	ds_read_b128 v[214:217], v163 offset:54272
	ds_read_b128 v[218:221], v163 offset:55296
	ds_read_b128 v[222:225], v163 offset:56320
	global_load_lds_dwordx4 v[18:19], off
	v_lshl_add_u64 v[18:19], v[246:247], 0, s[4:5]
	s_mov_b32 m0, s7
	s_nop 0
	global_load_lds_dwordx4 v[18:19], off
	s_barrier
	s_waitcnt lgkmcnt(0)
	s_setprio 1
	v_mfma_f32_16x16x32_bf16 v[76:79], v[52:55], v[148:151], v[76:79]
	v_mfma_f32_16x16x32_bf16 v[72:75], v[68:71], v[148:151], v[72:75]
	v_mfma_f32_16x16x32_bf16 v[60:63], v[52:55], v[196:199], v[60:63]
	v_mfma_f32_16x16x32_bf16 v[56:59], v[68:71], v[196:199], v[56:59]
	v_mfma_f32_16x16x32_bf16 v[44:47], v[52:55], v[210:213], v[44:47]
	v_mfma_f32_16x16x32_bf16 v[40:43], v[68:71], v[210:213], v[40:43]
	v_mfma_f32_16x16x32_bf16 v[14:17], v[52:55], v[218:221], v[14:17]
	v_mfma_f32_16x16x32_bf16 v[8:11], v[68:71], v[218:221], v[8:11]
	v_mfma_f32_16x16x32_bf16 v[76:79], v[64:67], v[192:195], v[76:79]
	v_mfma_f32_16x16x32_bf16 v[72:75], v[144:147], v[192:195], v[72:75]
	v_mfma_f32_16x16x32_bf16 v[60:63], v[64:67], v[200:203], v[60:63]
	v_mfma_f32_16x16x32_bf16 v[56:59], v[144:147], v[200:203], v[56:59]
	v_mfma_f32_16x16x32_bf16 v[44:47], v[64:67], v[214:217], v[44:47]
	v_mfma_f32_16x16x32_bf16 v[40:43], v[144:147], v[214:217], v[40:43]
	v_mfma_f32_16x16x32_bf16 v[16:19], v[64:67], v[222:225], v[14:17]
	v_mfma_f32_16x16x32_bf16 v[8:11], v[144:147], v[222:225], v[8:11]
	s_setprio 0
	s_barrier
	s_add_u32 s20, s20, 0x40080
	s_addc_u32 s21, s21, 0
	s_add_i32 s22, s22, s9
	v_lshl_add_u64 v[14:15], s[20:21], 0, v[166:167]
	s_mov_b32 m0, s22
	s_nop 0
	global_load_lds_dwordx4 v[14:15], off
	v_lshl_add_u64 v[14:15], s[20:21], 0, v[170:171]
	s_add_i32 m0, s22, 0x2000
	s_nop 0
	global_load_lds_dwordx4 v[14:15], off
	s_waitcnt vmcnt(6)
	s_barrier
	s_setprio 1
	v_mfma_f32_16x16x32_bf16 v[24:27], v[226:229], v[148:151], v[24:27]
	v_mfma_f32_16x16x32_bf16 v[68:71], v[230:233], v[192:195], v[24:27]
	v_mfma_f32_16x16x32_bf16 v[24:27], v[234:237], v[148:151], v[32:35]
	v_mfma_f32_16x16x32_bf16 v[64:67], v[238:241], v[192:195], v[24:27]
	v_mfma_f32_16x16x32_bf16 v[24:27], v[226:229], v[196:199], v[36:39]
	v_mfma_f32_16x16x32_bf16 v[52:55], v[230:233], v[200:203], v[24:27]
	v_mfma_f32_16x16x32_bf16 v[24:27], v[234:237], v[196:199], v[48:51]
	v_mfma_f32_16x16x32_bf16 v[48:51], v[238:241], v[200:203], v[24:27]
	v_mfma_f32_16x16x32_bf16 v[24:27], v[226:229], v[210:213], v[28:31]
	v_mfma_f32_16x16x32_bf16 v[20:23], v[234:237], v[210:213], v[20:23]
	v_mfma_f32_16x16x32_bf16 v[4:7], v[226:229], v[218:221], v[4:7]
	v_mfma_f32_16x16x32_bf16 v[0:3], v[234:237], v[218:221], v[0:3]
	v_mfma_f32_16x16x32_bf16 v[28:31], v[230:233], v[214:217], v[24:27]
	v_mfma_f32_16x16x32_bf16 v[20:23], v[238:241], v[214:217], v[20:23]
	v_mfma_f32_16x16x32_bf16 v[4:7], v[230:233], v[222:225], v[4:7]
	v_mfma_f32_16x16x32_bf16 v[0:3], v[238:241], v[222:225], v[0:3]
	s_setprio 0
	s_add_i32 s3, s3, 2
	s_add_u32 s0, s0, 0x100
	s_addc_u32 s1, s1, 0
	s_add_u32 vcc_hi, vcc_hi, 0x100
	s_addc_u32 s2, s2, 0
	s_cmp_lt_u32 s3, 14
	s_barrier
	s_cbranch_scc0 .LBB0_197

; #define PG8_STAGE(bufoff, gbase, voff) do { _Pragma("unroll") for (int _i = 0; _i < 2; ++_i) \
;         __builtin_amdgcn_global_load_lds((const unsigned*)((const char*)(gbase) + (voff)[_i]), (PG8_LAS unsigned*)(lds + (bufoff) + ldsw + _i * 8192), 16, 0, 0); } while (0)
; #define PG8_LDA(dst, b, h) do { _Pragma("unroll") for (int m = 0; m < 4; ++m) _Pragma("unroll") for (int k = 0; k < 2; ++k) dst[m][k] = *(const PG8_LAS bf16x8*)(lds + PG8_SA(b, h) + aoff + m * 2048 + k * 1024); } while (0)
; #define PG8_LDB(dst, b, h) do { _Pragma("unroll") for (int n = 0; n < 2; ++n) _Pragma("unroll") for (int k = 0; k < 2; ++k) dst[n][k] = *(const PG8_LAS bf16x8*)(lds + PG8_SB(b, h) + boff + n * 2048 + k * 1024); } while (0)
; #define PG8_MMA(ai, bj, At, Bt) do { __builtin_amdgcn_s_setprio(1); _Pragma("unroll") for (int m = 0; m < 4; ++m) _Pragma("unroll") for (int n = 0; n < 2; ++n) _Pragma("unroll") for (int k = 0; k < 2; ++k) \
;         acc[ai][bj][m][n] = __builtin_amdgcn_mfma_f32_16x16x32_bf16(Bt[n][k], At[m][k], acc[ai][bj][m][n], 0, 0, 0); __builtin_amdgcn_s_setprio(0); } while (0)
; #define PG8_WAIT_L(n) asm volatile("s_waitcnt lgkmcnt(" #n ")" ::: "memory")
; #define PG8_BAR __builtin_amdgcn_s_barrier()
; #define PG8_SCHED __builtin_amdgcn_sched_barrier(0)
; template <class Epi, class Sched>
; __device__ __forceinline__ void gemm_phase(PG8_LAS unsigned char* lds, const Gemm g, const Sched& S, const Epi& E) {
;     ...
;             PG8_LDB(B0, 0, 0); PG8_SCHED; PG8_LDA(At, 0, 0); PG8_STAGE(PG8_SA(1, 1), a1 + hstep, voffA);
;             PG8_WAIT_L(8); PG8_BAR; PG8_WAIT_L(0); PG8_MMA(0, 0, At, B0); PG8_BAR; PG8_SCHED;
;             PG8_LDB(B1, 0, 1); PG8_STAGE(PG8_SB(0, 0), b2, voffB);
;             PG8_BAR; PG8_WAIT_L(0); PG8_MMA(0, 1, At, B1); PG8_BAR;
;             PG8_LDA(At, 0, 1); PG8_STAGE(PG8_SA(0, 0), a2, voffA);
;             PG8_BAR; PG8_WAIT_L(0); PG8_MMA(1, 0, At, B0); PG8_BAR; PG8_SCHED;
.LBB0_1191:
	ds_read_b128 v[128:131], v163
	ds_read_b128 v[132:135], v163 offset:1024
	ds_read_b128 v[136:139], v163 offset:2048
	ds_read_b128 v[168:171], v163 offset:3072
	s_add_u32 s16, s14, 0xfffe0080
	s_addc_u32 s17, s15, -1
	s_cmp_eq_u32 s41, 4
	s_cselect_b32 s19, s7, s17
	s_cselect_b32 s18, s37, s16
	s_cselect_b32 s17, s5, s40
	s_cselect_b32 s16, s38, s39
	v_lshl_add_u64 v[206:207], s[14:15], 0, v[148:149]
	s_add_i32 m0, s13, 0xc000
	ds_read_b128 v[172:175], v176
	ds_read_b128 v[178:181], v176 offset:1024
	ds_read_b128 v[182:185], v176 offset:2048
	ds_read_b128 v[186:189], v176 offset:3072
	ds_read_b128 v[190:193], v176 offset:4096
	ds_read_b128 v[194:197], v176 offset:5120
	ds_read_b128 v[198:201], v176 offset:6144
	ds_read_b128 v[202:205], v176 offset:7168
	global_load_lds_dwordx4 v[206:207], off
	v_lshl_add_u64 v[206:207], s[14:15], 0, v[150:151]
	s_add_i32 m0, s13, 0xe000
	s_nop 0
	global_load_lds_dwordx4 v[206:207], off
	s_waitcnt lgkmcnt(8)
	s_barrier
	s_waitcnt lgkmcnt(0)
	s_setprio 1
	v_mfma_f32_16x16x32_bf16 v[124:127], v[128:131], v[172:175], v[124:127]
	v_mfma_f32_16x16x32_bf16 v[120:123], v[136:139], v[172:175], v[120:123]
	v_mfma_f32_16x16x32_bf16 v[108:111], v[128:131], v[182:185], v[108:111]
	v_mfma_f32_16x16x32_bf16 v[104:107], v[136:139], v[182:185], v[104:107]
	v_mfma_f32_16x16x32_bf16 v[92:95], v[128:131], v[190:193], v[92:95]
	v_mfma_f32_16x16x32_bf16 v[88:91], v[136:139], v[190:193], v[88:91]
	v_mfma_f32_16x16x32_bf16 v[76:79], v[128:131], v[198:201], v[76:79]
	v_mfma_f32_16x16x32_bf16 v[72:75], v[136:139], v[198:201], v[72:75]
	v_mfma_f32_16x16x32_bf16 v[124:127], v[132:135], v[178:181], v[124:127]
	v_mfma_f32_16x16x32_bf16 v[120:123], v[168:171], v[178:181], v[120:123]
	v_mfma_f32_16x16x32_bf16 v[108:111], v[132:135], v[186:189], v[108:111]
	v_mfma_f32_16x16x32_bf16 v[104:107], v[168:171], v[186:189], v[104:107]
	v_mfma_f32_16x16x32_bf16 v[92:95], v[132:135], v[194:197], v[92:95]
	v_mfma_f32_16x16x32_bf16 v[88:91], v[168:171], v[194:197], v[88:91]
	v_mfma_f32_16x16x32_bf16 v[76:79], v[132:135], v[202:205], v[76:79]
	v_mfma_f32_16x16x32_bf16 v[72:75], v[168:171], v[202:205], v[72:75]
	s_setprio 0
	s_barrier
	s_add_i32 s30, s34, s22
	v_lshl_add_u64 v[222:223], s[16:17], 0, v[142:143]
	s_mov_b32 m0, s30
	ds_read_b128 v[206:209], v177
	ds_read_b128 v[210:213], v177 offset:1024
	ds_read_b128 v[214:217], v177 offset:2048
	ds_read_b128 v[218:221], v177 offset:3072
	global_load_lds_dwordx4 v[222:223], off
	v_lshl_add_u64 v[224:225], s[16:17], 0, v[146:147]
	s_add_i32 m0, s30, 0x2000
	s_nop 0
	global_load_lds_dwordx4 v[224:225], off
	s_barrier
	s_waitcnt lgkmcnt(0)
	s_setprio 1
	v_mfma_f32_16x16x32_bf16 v[116:119], v[206:209], v[172:175], v[116:119]
	v_mfma_f32_16x16x32_bf16 v[112:115], v[214:217], v[172:175], v[112:115]
	v_mfma_f32_16x16x32_bf16 v[100:103], v[206:209], v[182:185], v[100:103]
	v_mfma_f32_16x16x32_bf16 v[96:99], v[214:217], v[182:185], v[96:99]
	v_mfma_f32_16x16x32_bf16 v[84:87], v[206:209], v[190:193], v[84:87]
	v_mfma_f32_16x16x32_bf16 v[80:83], v[214:217], v[190:193], v[80:83]
	v_mfma_f32_16x16x32_bf16 v[68:71], v[206:209], v[198:201], v[68:71]
	v_mfma_f32_16x16x32_bf16 v[64:67], v[214:217], v[198:201], v[64:67]
	v_mfma_f32_16x16x32_bf16 v[116:119], v[210:213], v[178:181], v[116:119]
	v_mfma_f32_16x16x32_bf16 v[112:115], v[218:221], v[178:181], v[112:115]
	v_mfma_f32_16x16x32_bf16 v[100:103], v[210:213], v[186:189], v[100:103]
	v_mfma_f32_16x16x32_bf16 v[96:99], v[218:221], v[186:189], v[96:99]
	v_mfma_f32_16x16x32_bf16 v[84:87], v[210:213], v[194:197], v[84:87]
	v_mfma_f32_16x16x32_bf16 v[80:83], v[218:221], v[194:197], v[80:83]
	v_mfma_f32_16x16x32_bf16 v[68:71], v[210:213], v[202:205], v[68:71]
	v_mfma_f32_16x16x32_bf16 v[64:67], v[218:221], v[202:205], v[64:67]
	s_setprio 0
	s_mov_b32 m0, s13
	v_lshl_add_u64 v[226:227], s[18:19], 0, v[140:141]
	s_barrier
	ds_read_b128 v[172:175], v176 offset:16384
	ds_read_b128 v[178:181], v176 offset:17408
	ds_read_b128 v[182:185], v176 offset:18432
	ds_read_b128 v[186:189], v176 offset:19456
	ds_read_b128 v[190:193], v176 offset:20480
	ds_read_b128 v[194:197], v176 offset:21504
	ds_read_b128 v[198:201], v176 offset:22528
	ds_read_b128 v[202:205], v176 offset:23552
	global_load_lds_dwordx4 v[226:227], off
	v_lshl_add_u64 v[228:229], s[18:19], 0, v[144:145]
	s_mov_b32 m0, s23
	s_nop 0
	global_load_lds_dwordx4 v[228:229], off
	s_barrier
	s_waitcnt lgkmcnt(0)
	s_setprio 1
	v_mfma_f32_16x16x32_bf16 v[60:63], v[128:131], v[172:175], v[60:63]
	v_mfma_f32_16x16x32_bf16 v[56:59], v[136:139], v[172:175], v[56:59]
	v_mfma_f32_16x16x32_bf16 v[44:47], v[128:131], v[182:185], v[44:47]
	v_mfma_f32_16x16x32_bf16 v[40:43], v[136:139], v[182:185], v[40:43]
	v_mfma_f32_16x16x32_bf16 v[28:31], v[128:131], v[190:193], v[28:31]
	v_mfma_f32_16x16x32_bf16 v[24:27], v[136:139], v[190:193], v[24:27]
	v_mfma_f32_16x16x32_bf16 v[12:15], v[128:131], v[198:201], v[12:15]
	v_mfma_f32_16x16x32_bf16 v[8:11], v[136:139], v[198:201], v[8:11]
	v_mfma_f32_16x16x32_bf16 v[60:63], v[132:135], v[178:181], v[60:63]
	v_mfma_f32_16x16x32_bf16 v[56:59], v[168:171], v[178:181], v[56:59]
	v_mfma_f32_16x16x32_bf16 v[44:47], v[132:135], v[186:189], v[44:47]
	v_mfma_f32_16x16x32_bf16 v[40:43], v[168:171], v[186:189], v[40:43]
	v_mfma_f32_16x16x32_bf16 v[28:31], v[132:135], v[194:197], v[28:31]
	v_mfma_f32_16x16x32_bf16 v[24:27], v[168:171], v[194:197], v[24:27]
	v_mfma_f32_16x16x32_bf16 v[12:15], v[132:135], v[202:205], v[12:15]
	v_mfma_f32_16x16x32_bf16 v[8:11], v[168:171], v[202:205], v[8:11]
	s_setprio 0
	s_barrier
; #define PG8_STAGE(bufoff, gbase, voff) do { _Pragma("unroll") for (int _i = 0; _i < 2; ++_i) \
;         __builtin_amdgcn_global_load_lds((const unsigned*)((const char*)(gbase) + (voff)[_i]), (PG8_LAS unsigned*)(lds + (bufoff) + ldsw + _i * 8192), 16, 0, 0); } while (0)
; #define PG8_LDA(dst, b, h) do { _Pragma("unroll") for (int m = 0; m < 4; ++m) _Pragma("unroll") for (int k = 0; k < 2; ++k) dst[m][k] = *(const PG8_LAS bf16x8*)(lds + PG8_SA(b, h) + aoff + m * 2048 + k * 1024); } while (0)
; #define PG8_LDB(dst, b, h) do { _Pragma("unroll") for (int n = 0; n < 2; ++n) _Pragma("unroll") for (int k = 0; k < 2; ++k) dst[n][k] = *(const PG8_LAS bf16x8*)(lds + PG8_SB(b, h) + boff + n * 2048 + k * 1024); } while (0)
; #define PG8_MMA(ai, bj, At, Bt) do { __builtin_amdgcn_s_setprio(1); _Pragma("unroll") for (int m = 0; m < 4; ++m) _Pragma("unroll") for (int n = 0; n < 2; ++n) _Pragma("unroll") for (int k = 0; k < 2; ++k) \
;         acc[ai][bj][m][n] = __builtin_amdgcn_mfma_f32_16x16x32_bf16(Bt[n][k], At[m][k], acc[ai][bj][m][n], 0, 0, 0); __builtin_amdgcn_s_setprio(0); } while (0)
; #define PG8_WAIT_V(n) asm volatile("s_waitcnt vmcnt(" #n ")" ::: "memory")
; #define PG8_WAIT_L(n) asm volatile("s_waitcnt lgkmcnt(" #n ")" ::: "memory")
; #define PG8_BAR __builtin_amdgcn_s_barrier()
; #define PG8_SCHED __builtin_amdgcn_sched_barrier(0)
; template <class Epi, class Sched>
; __device__ __forceinline__ void gemm_phase(PG8_LAS unsigned char* lds, const Gemm g, const Sched& S, const Epi& E) {
;     ...
;             PG8_STAGE(PG8_SB(0, 1), b2 + hstep, voffB);
;             PG8_WAIT_V(6); PG8_BAR; PG8_MMA(1, 1, At, B1); PG8_BAR;
;             PG8_LDB(B0, 1, 0); PG8_SCHED; PG8_LDA(At, 1, 0); PG8_STAGE(PG8_SA(0, 1), a2 + hstep, voffA);
;             PG8_WAIT_L(8); PG8_BAR; PG8_WAIT_L(0); PG8_MMA(0, 0, At, B0); PG8_BAR; PG8_SCHED;
;             PG8_LDB(B1, 1, 1); PG8_STAGE(PG8_SB(1, 0), b3, voffB);
;             PG8_BAR; PG8_WAIT_L(0); PG8_MMA(0, 1, At, B1); PG8_BAR;
;             PG8_LDA(At, 1, 1); PG8_STAGE(PG8_SA(1, 0), a3, voffA);
	s_add_u32 s42, s16, 0x20000
	s_addc_u32 s43, s17, 0
	s_add_i32 s30, s35, s22
	v_lshl_add_u64 v[128:129], s[42:43], 0, v[142:143]
	s_mov_b32 m0, s30
	s_nop 0
	global_load_lds_dwordx4 v[128:129], off
	v_lshl_add_u64 v[128:129], s[42:43], 0, v[146:147]
	s_add_i32 m0, s30, 0x2000
	s_nop 0
	global_load_lds_dwordx4 v[128:129], off
	s_waitcnt vmcnt(6)
	s_barrier
	s_setprio 1
	v_mfma_f32_16x16x32_bf16 v[52:55], v[206:209], v[172:175], v[52:55]
	v_mfma_f32_16x16x32_bf16 v[48:51], v[214:217], v[172:175], v[48:51]
	v_mfma_f32_16x16x32_bf16 v[36:39], v[206:209], v[182:185], v[36:39]
	v_mfma_f32_16x16x32_bf16 v[32:35], v[214:217], v[182:185], v[32:35]
	v_mfma_f32_16x16x32_bf16 v[20:23], v[206:209], v[190:193], v[20:23]
	v_mfma_f32_16x16x32_bf16 v[16:19], v[214:217], v[190:193], v[16:19]
	v_mfma_f32_16x16x32_bf16 v[4:7], v[206:209], v[198:201], v[4:7]
	v_mfma_f32_16x16x32_bf16 v[0:3], v[214:217], v[198:201], v[0:3]
	v_mfma_f32_16x16x32_bf16 v[52:55], v[210:213], v[178:181], v[52:55]
	v_mfma_f32_16x16x32_bf16 v[48:51], v[218:221], v[178:181], v[48:51]
	v_mfma_f32_16x16x32_bf16 v[36:39], v[210:213], v[186:189], v[36:39]
	v_mfma_f32_16x16x32_bf16 v[32:35], v[218:221], v[186:189], v[32:35]
	v_mfma_f32_16x16x32_bf16 v[20:23], v[210:213], v[194:197], v[20:23]
	v_mfma_f32_16x16x32_bf16 v[16:19], v[218:221], v[194:197], v[16:19]
	v_mfma_f32_16x16x32_bf16 v[4:7], v[210:213], v[202:205], v[4:7]
	v_mfma_f32_16x16x32_bf16 v[0:3], v[218:221], v[202:205], v[0:3]
	s_setprio 0
	s_add_i32 s30, 0, 0x18000
	v_add_u32_e32 v168, s30, v159
	s_barrier
	ds_read_b128 v[128:131], v168
	ds_read_b128 v[132:135], v168 offset:1024
	ds_read_b128 v[136:139], v168 offset:2048
	ds_read_b128 v[168:171], v168 offset:3072
	s_add_u32 s18, s18, 0x20000
	s_addc_u32 s19, s19, 0
	s_mov_b32 m0, s24
	v_lshl_add_u64 v[206:207], s[18:19], 0, v[140:141]
	ds_read_b128 v[172:175], v176 offset:32768
	ds_read_b128 v[178:181], v176 offset:33792
	ds_read_b128 v[182:185], v176 offset:34816
	ds_read_b128 v[186:189], v176 offset:35840
	ds_read_b128 v[190:193], v176 offset:36864
	ds_read_b128 v[194:197], v176 offset:37888
	ds_read_b128 v[198:201], v176 offset:38912
	ds_read_b128 v[202:205], v176 offset:39936
	global_load_lds_dwordx4 v[206:207], off
	v_lshl_add_u64 v[206:207], s[18:19], 0, v[144:145]
	s_mov_b32 m0, s25
	s_nop 0
	global_load_lds_dwordx4 v[206:207], off
	s_waitcnt lgkmcnt(8)
	s_barrier
	s_waitcnt lgkmcnt(0)
	s_setprio 1
	v_mfma_f32_16x16x32_bf16 v[124:127], v[128:131], v[172:175], v[124:127]
	v_mfma_f32_16x16x32_bf16 v[120:123], v[136:139], v[172:175], v[120:123]
	v_mfma_f32_16x16x32_bf16 v[108:111], v[128:131], v[182:185], v[108:111]
	v_mfma_f32_16x16x32_bf16 v[104:107], v[136:139], v[182:185], v[104:107]
	v_mfma_f32_16x16x32_bf16 v[92:95], v[128:131], v[190:193], v[92:95]
	v_mfma_f32_16x16x32_bf16 v[88:91], v[136:139], v[190:193], v[88:91]
	v_mfma_f32_16x16x32_bf16 v[76:79], v[128:131], v[198:201], v[76:79]
	v_mfma_f32_16x16x32_bf16 v[72:75], v[136:139], v[198:201], v[72:75]
	v_mfma_f32_16x16x32_bf16 v[124:127], v[132:135], v[178:181], v[124:127]
	v_mfma_f32_16x16x32_bf16 v[120:123], v[168:171], v[178:181], v[120:123]
	v_mfma_f32_16x16x32_bf16 v[108:111], v[132:135], v[186:189], v[108:111]
	v_mfma_f32_16x16x32_bf16 v[104:107], v[168:171], v[186:189], v[104:107]
	v_mfma_f32_16x16x32_bf16 v[92:95], v[132:135], v[194:197], v[92:95]
	v_mfma_f32_16x16x32_bf16 v[88:91], v[168:171], v[194:197], v[88:91]
	v_mfma_f32_16x16x32_bf16 v[76:79], v[132:135], v[202:205], v[76:79]
	v_mfma_f32_16x16x32_bf16 v[72:75], v[168:171], v[202:205], v[72:75]
	s_setprio 0
	s_barrier
	s_add_i32 s18, 0, 0x1c000
	s_add_i32 s19, s30, s22
	v_add_u32_e32 v218, s18, v159
	v_lshl_add_u64 v[222:223], v[222:223], 0, s[2:3]
	s_mov_b32 m0, s19
	ds_read_b128 v[206:209], v218
	ds_read_b128 v[210:213], v218 offset:1024
	ds_read_b128 v[214:217], v218 offset:2048
	ds_read_b128 v[218:221], v218 offset:3072
	global_load_lds_dwordx4 v[222:223], off
	v_lshl_add_u64 v[222:223], v[224:225], 0, s[2:3]
	s_add_i32 m0, s19, 0x2000
	s_nop 0
	global_load_lds_dwordx4 v[222:223], off
	s_barrier
	s_waitcnt lgkmcnt(0)
	s_setprio 1
	v_mfma_f32_16x16x32_bf16 v[116:119], v[206:209], v[172:175], v[116:119]
	v_mfma_f32_16x16x32_bf16 v[112:115], v[214:217], v[172:175], v[112:115]
	v_mfma_f32_16x16x32_bf16 v[100:103], v[206:209], v[182:185], v[100:103]
	v_mfma_f32_16x16x32_bf16 v[96:99], v[214:217], v[182:185], v[96:99]
	v_mfma_f32_16x16x32_bf16 v[84:87], v[206:209], v[190:193], v[84:87]
	v_mfma_f32_16x16x32_bf16 v[80:83], v[214:217], v[190:193], v[80:83]
	v_mfma_f32_16x16x32_bf16 v[68:71], v[206:209], v[198:201], v[68:71]
	v_mfma_f32_16x16x32_bf16 v[64:67], v[214:217], v[198:201], v[64:67]
	v_mfma_f32_16x16x32_bf16 v[116:119], v[210:213], v[178:181], v[116:119]
	v_mfma_f32_16x16x32_bf16 v[112:115], v[218:221], v[178:181], v[112:115]
	v_mfma_f32_16x16x32_bf16 v[100:103], v[210:213], v[186:189], v[100:103]
	v_mfma_f32_16x16x32_bf16 v[96:99], v[218:221], v[186:189], v[96:99]
	v_mfma_f32_16x16x32_bf16 v[84:87], v[210:213], v[194:197], v[84:87]
	v_mfma_f32_16x16x32_bf16 v[80:83], v[218:221], v[194:197], v[80:83]
	v_mfma_f32_16x16x32_bf16 v[68:71], v[210:213], v[202:205], v[68:71]
	v_mfma_f32_16x16x32_bf16 v[64:67], v[218:221], v[202:205], v[64:67]
	s_setprio 0
	s_mov_b32 m0, s27
	v_lshl_add_u64 v[222:223], v[226:227], 0, s[2:3]
	s_barrier
	ds_read_b128 v[172:175], v176 offset:49152
	ds_read_b128 v[178:181], v176 offset:50176
	ds_read_b128 v[182:185], v176 offset:51200
	ds_read_b128 v[186:189], v176 offset:52224
	ds_read_b128 v[190:193], v176 offset:53248
	ds_read_b128 v[194:197], v176 offset:54272
	ds_read_b128 v[198:201], v176 offset:55296
	ds_read_b128 v[202:205], v176 offset:56320
	global_load_lds_dwordx4 v[222:223], off
	v_lshl_add_u64 v[222:223], v[228:229], 0, s[2:3]
	s_mov_b32 m0, s29
	s_nop 0
	global_load_lds_dwordx4 v[222:223], off
	s_barrier
; #define PG8_STAGE(bufoff, gbase, voff) do { _Pragma("unroll") for (int _i = 0; _i < 2; ++_i) \
;         __builtin_amdgcn_global_load_lds((const unsigned*)((const char*)(gbase) + (voff)[_i]), (PG8_LAS unsigned*)(lds + (bufoff) + ldsw + _i * 8192), 16, 0, 0); } while (0)
; #define PG8_MMA(ai, bj, At, Bt) do { __builtin_amdgcn_s_setprio(1); _Pragma("unroll") for (int m = 0; m < 4; ++m) _Pragma("unroll") for (int n = 0; n < 2; ++n) _Pragma("unroll") for (int k = 0; k < 2; ++k) \
;         acc[ai][bj][m][n] = __builtin_amdgcn_mfma_f32_16x16x32_bf16(Bt[n][k], At[m][k], acc[ai][bj][m][n], 0, 0, 0); __builtin_amdgcn_s_setprio(0); } while (0)
; #define PG8_WAIT_V(n) asm volatile("s_waitcnt vmcnt(" #n ")" ::: "memory")
; #define PG8_WAIT_L(n) asm volatile("s_waitcnt lgkmcnt(" #n ")" ::: "memory")
; #define PG8_BAR __builtin_amdgcn_s_barrier()
; #define PG8_SCHED __builtin_amdgcn_sched_barrier(0)
; template <class Epi, class Sched>
; __device__ __forceinline__ void gemm_phase(PG8_LAS unsigned char* lds, const Gemm g, const Sched& S, const Epi& E) {
;     ...
;             PG8_BAR; PG8_WAIT_L(0); PG8_MMA(1, 0, At, B0); PG8_BAR; PG8_SCHED;
;             PG8_STAGE(PG8_SB(1, 1), b3 + hstep, voffB);
;             PG8_WAIT_V(6); PG8_BAR; PG8_MMA(1, 1, At, B1); PG8_BAR;
;     DI void operator()(const f32x4 (&acc)[2][2][4][2], const Unit& u, int wr, int wc, int fr, int fq, const Pre& pre) const {
;         const int cb = u.pn * 256 + wc * 32 + 8 * fq, row0 = u.pm * 256 + wr * 64 + fr;
; #pragma unroll
;         for (int ai = 0; ai < 2; ++ai) {
;             u32x4v y[4][2];
; #pragma unroll
;             for (int m = 0; m < 4; ++m)
; #pragma unroll
;                 for (int bj = 0; bj < 2; ++bj) y[m][bj] = *(const u32x4v*)(YG + (size_t)(row0 + ai * 128 + m * 16) * 512 + cb + bj * 128);
; #pragma unroll
;             for (int m = 0; m < 4; ++m) { const int row = row0 + ai * 128 + m * 16;
; #pragma unroll
;                 for (int bj = 0; bj < 2; ++bj) { const f32x4 v0 = acc[ai][bj][m][0], v1 = acc[ai][bj][m][1]; const u32x4v yy = y[m][bj]; u32x4v o;
;                     o.x = pk2(bflo(yy.x) * sigm(v0[0]), bfhi(yy.x) * sigm(v0[1])); o.y = pk2(bflo(yy.y) * sigm(v0[2]), bfhi(yy.y) * sigm(v0[3]));
;                     o.z = pk2(bflo(yy.z) * sigm(v1[0]), bfhi(yy.z) * sigm(v1[1])); o.w = pk2(bflo(yy.w) * sigm(v1[2]), bfhi(yy.w) * sigm(v1[3]));
	s_waitcnt lgkmcnt(0)
	s_setprio 1
	v_mfma_f32_16x16x32_bf16 v[60:63], v[128:131], v[172:175], v[60:63]
	v_mfma_f32_16x16x32_bf16 v[56:59], v[136:139], v[172:175], v[56:59]
	v_mfma_f32_16x16x32_bf16 v[44:47], v[128:131], v[182:185], v[44:47]
	v_mfma_f32_16x16x32_bf16 v[40:43], v[136:139], v[182:185], v[40:43]
	v_mfma_f32_16x16x32_bf16 v[28:31], v[128:131], v[190:193], v[28:31]
	v_mfma_f32_16x16x32_bf16 v[24:27], v[136:139], v[190:193], v[24:27]
	v_mfma_f32_16x16x32_bf16 v[12:15], v[128:131], v[198:201], v[12:15]
	v_mfma_f32_16x16x32_bf16 v[8:11], v[136:139], v[198:201], v[8:11]
	v_mfma_f32_16x16x32_bf16 v[60:63], v[132:135], v[178:181], v[60:63]
	v_mfma_f32_16x16x32_bf16 v[56:59], v[168:171], v[178:181], v[56:59]
	v_mfma_f32_16x16x32_bf16 v[44:47], v[132:135], v[186:189], v[44:47]
	v_mfma_f32_16x16x32_bf16 v[40:43], v[168:171], v[186:189], v[40:43]
	v_mfma_f32_16x16x32_bf16 v[28:31], v[132:135], v[194:197], v[28:31]
	v_mfma_f32_16x16x32_bf16 v[24:27], v[168:171], v[194:197], v[24:27]
	v_mfma_f32_16x16x32_bf16 v[12:15], v[132:135], v[202:205], v[12:15]
	v_mfma_f32_16x16x32_bf16 v[8:11], v[168:171], v[202:205], v[8:11]
	s_setprio 0
	s_barrier
	s_add_u32 s16, s16, 0x20080
	s_addc_u32 s17, s17, 0
	s_add_i32 s18, s18, s22
	v_lshl_add_u64 v[128:129], s[16:17], 0, v[142:143]
	s_mov_b32 m0, s18
	s_nop 0
	global_load_lds_dwordx4 v[128:129], off
	v_lshl_add_u64 v[128:129], s[16:17], 0, v[146:147]
	s_add_i32 m0, s18, 0x2000
	s_nop 0
	global_load_lds_dwordx4 v[128:129], off
	s_waitcnt vmcnt(6)
	s_barrier
	s_setprio 1
	v_mfma_f32_16x16x32_bf16 v[52:55], v[206:209], v[172:175], v[52:55]
	v_mfma_f32_16x16x32_bf16 v[48:51], v[214:217], v[172:175], v[48:51]
	v_mfma_f32_16x16x32_bf16 v[36:39], v[206:209], v[182:185], v[36:39]
	v_mfma_f32_16x16x32_bf16 v[32:35], v[214:217], v[182:185], v[32:35]
	v_mfma_f32_16x16x32_bf16 v[20:23], v[206:209], v[190:193], v[20:23]
	v_mfma_f32_16x16x32_bf16 v[16:19], v[214:217], v[190:193], v[16:19]
	v_mfma_f32_16x16x32_bf16 v[4:7], v[206:209], v[198:201], v[4:7]
	v_mfma_f32_16x16x32_bf16 v[0:3], v[214:217], v[198:201], v[0:3]
	v_mfma_f32_16x16x32_bf16 v[52:55], v[210:213], v[178:181], v[52:55]
	v_mfma_f32_16x16x32_bf16 v[48:51], v[218:221], v[178:181], v[48:51]
	v_mfma_f32_16x16x32_bf16 v[36:39], v[210:213], v[186:189], v[36:39]
	v_mfma_f32_16x16x32_bf16 v[32:35], v[218:221], v[186:189], v[32:35]
	v_mfma_f32_16x16x32_bf16 v[20:23], v[210:213], v[194:197], v[20:23]
	v_mfma_f32_16x16x32_bf16 v[16:19], v[218:221], v[194:197], v[16:19]
	v_mfma_f32_16x16x32_bf16 v[4:7], v[210:213], v[202:205], v[4:7]
	v_mfma_f32_16x16x32_bf16 v[0:3], v[218:221], v[202:205], v[0:3]
	s_setprio 0
	s_add_i32 s41, s41, 2
	s_add_u32 s14, s14, 0x100
	s_addc_u32 s15, s15, 0
	s_add_u32 s39, s39, 0x100
	s_addc_u32 s40, s40, 0
	s_cmp_lt_u32 s41, 6
	s_barrier
	s_cbranch_scc1 .LBB0_1191
	v_lshl_or_b32 v128, s36, 8, v161
	v_lshl_add_u32 v170, s12, 8, v157
	v_ashrrev_i32_e32 v129, 31, v128
	v_readlane_b32 s36, v255, 8
	v_lshlrev_b64 v[168:169], 1, v[128:129]
	v_readlane_b32 s44, v255, 16
	v_readlane_b32 s45, v255, 17
	v_ashrrev_i32_e32 v171, 31, v170
	v_lshlrev_b64 v[128:129], 10, v[170:171]
	v_lshl_add_u64 v[172:173], s[44:45], 0, v[168:169]
	v_lshl_add_u64 v[128:129], v[172:173], 0, v[128:129]
	global_load_dwordx4 v[178:181], v[128:129], off
	global_load_dwordx4 v[182:185], v[128:129], off offset:256
	v_or_b32_e32 v190, 16, v170
	v_or_b32_e32 v174, 32, v170
	v_mul_f32_e32 v124, 0xbfb8aa3b, v124
	v_mul_f32_e32 v125, 0xbfb8aa3b, v125
	v_mul_f32_e32 v120, 0xbfb8aa3b, v120
	v_mul_f32_e32 v121, 0xbfb8aa3b, v121
	v_mul_f32_e32 v122, 0xbfb8aa3b, v122
	v_mul_f32_e32 v123, 0xbfb8aa3b, v123
	v_mul_f32_e32 v128, 0xbfb8aa3b, v116
	v_mul_f32_e32 v117, 0xbfb8aa3b, v117
	v_or_b32_e32 v116, 48, v170
	v_ashrrev_i32_e32 v191, 31, v190
	v_ashrrev_i32_e32 v175, 31, v174
	v_readlane_b32 s46, v255, 18
	v_readlane_b32 s47, v255, 19
	v_mul_f32_e32 v126, 0xbfb8aa3b, v126
	v_mul_f32_e32 v127, 0xbfb8aa3b, v127
	v_exp_f32_e32 v196, v124
	v_exp_f32_e32 v197, v125
	v_exp_f32_e32 v200, v120
	v_exp_f32_e32 v201, v121
	v_exp_f32_e32 v202, v122
	v_exp_f32_e32 v203, v123
	v_exp_f32_e32 v205, v117
	v_ashrrev_i32_e32 v117, 31, v116
	v_lshlrev_b64 v[120:121], 11, v[170:171]
	v_lshlrev_b64 v[122:123], 10, v[190:191]
	v_lshlrev_b64 v[124:125], 10, v[174:175]
	v_exp_f32_e32 v198, v126
	v_exp_f32_e32 v199, v127
	v_lshlrev_b64 v[126:127], 10, v[116:117]
	v_lshl_add_u64 v[120:121], s[46:47], 0, v[120:121]
	v_lshl_add_u64 v[122:123], v[172:173], 0, v[122:123]
	v_lshl_add_u64 v[124:125], v[172:173], 0, v[124:125]
	v_exp_f32_e32 v204, v128
	v_lshl_add_u64 v[192:193], v[172:173], 0, v[126:127]
	v_lshl_add_u64 v[194:195], v[120:121], 0, v[168:169]
	global_load_dwordx4 v[186:189], v[122:123], off
	global_load_dwordx4 v[136:139], v[122:123], off offset:256
	global_load_dwordx4 v[132:135], v[124:125], off
	global_load_dwordx4 v[128:131], v[124:125], off offset:256
	s_nop 0
	global_load_dwordx4 v[124:127], v[192:193], off
	global_load_dwordx4 v[120:123], v[192:193], off offset:256
	v_add_f32_e32 v192, 1.0, v197
	v_add_f32_e32 v171, 1.0, v196
	v_add_f32_e32 v193, 1.0, v198
	v_add_f32_e32 v196, 1.0, v199
	v_add_f32_e32 v197, 1.0, v200
	v_add_f32_e32 v198, 1.0, v201
	v_add_f32_e32 v200, 1.0, v203
	v_rcp_f32_e32 v192, v192
	v_add_f32_e32 v199, 1.0, v202
	v_rcp_f32_e32 v171, v171
	v_rcp_f32_e32 v196, v196
	v_rcp_f32_e32 v198, v198
	v_rcp_f32_e32 v200, v200
	v_rcp_f32_e32 v193, v193
	v_rcp_f32_e32 v197, v197
	v_rcp_f32_e32 v199, v199
	v_mul_f32_e32 v118, 0xbfb8aa3b, v118
	v_add_f32_e32 v201, 1.0, v204
	v_exp_f32_e32 v118, v118
	v_mul_f32_e32 v119, 0xbfb8aa3b, v119
	v_exp_f32_e32 v119, v119
	v_mul_f32_e32 v112, 0xbfb8aa3b, v112
	v_exp_f32_e32 v112, v112
	v_mul_f32_e32 v113, 0xbfb8aa3b, v113
	v_exp_f32_e32 v113, v113
	v_add_f32_e32 v118, 1.0, v118
	v_rcp_f32_e32 v118, v118
	v_add_f32_e32 v119, 1.0, v119
	v_rcp_f32_e32 v119, v119
	v_add_f32_e32 v112, 1.0, v112
	v_rcp_f32_e32 v112, v112
	v_add_f32_e32 v113, 1.0, v113
	v_mul_f32_e32 v114, 0xbfb8aa3b, v114
	v_rcp_f32_e32 v113, v113
	v_exp_f32_e32 v114, v114
	v_mul_f32_e32 v115, 0xbfb8aa3b, v115
	v_exp_f32_e32 v115, v115
	v_mul_f32_e32 v108, 0xbfb8aa3b, v108
	v_exp_f32_e32 v108, v108
	v_mul_f32_e32 v109, 0xbfb8aa3b, v109
	s_waitcnt vmcnt(0)
; DI unsigned pk2(float lo, float hi) { unsigned r; asm volatile("v_cvt_pk_bf16_f32 %0, %1, %2" : "=v"(r) : "v"(lo), "v"(hi)); return r; }
; DI float bflo(unsigned u) { return __uint_as_float(u << 16); }
; DI float bfhi(unsigned u) { return __uint_as_float(u & 0xffff0000u); }
; DI float sigm(float x) { return __builtin_amdgcn_rcpf(1.f + __expf(-x)); }
;     DI void operator()(const f32x4 (&acc)[2][2][4][2], const Unit& u, int wr, int wc, int fr, int fq, const Pre& pre) const {
;     ...
;             for (int m = 0; m < 4; ++m) { const int row = row0 + ai * 128 + m * 16;
; #pragma unroll
;                 for (int bj = 0; bj < 2; ++bj) { const f32x4 v0 = acc[ai][bj][m][0], v1 = acc[ai][bj][m][1]; const u32x4v yy = y[m][bj]; u32x4v o;
;                     o.x = pk2(bflo(yy.x) * sigm(v0[0]), bfhi(yy.x) * sigm(v0[1])); o.y = pk2(bflo(yy.y) * sigm(v0[2]), bfhi(yy.y) * sigm(v0[3]));
;                     o.z = pk2(bflo(yy.z) * sigm(v1[0]), bfhi(yy.z) * sigm(v1[1])); o.w = pk2(bflo(yy.w) * sigm(v1[2]), bfhi(yy.w) * sigm(v1[3]));
;                     *(u32x4v*)(CAT + (size_t)row * 1024 + 512 + cb + bj * 128) = o; } } }
	v_lshlrev_b32_e32 v202, 16, v178
	v_and_b32_e32 v178, 0xffff0000, v178
	v_lshlrev_b32_e32 v203, 16, v179
	v_and_b32_e32 v179, 0xffff0000, v179
	v_lshlrev_b32_e32 v204, 16, v180
	v_and_b32_e32 v180, 0xffff0000, v180
	v_lshlrev_b32_e32 v206, 16, v181
	v_and_b32_e32 v181, 0xffff0000, v181
	v_mul_f32_e32 v178, v192, v178
	v_mul_f32_e32 v171, v171, v202
	v_mul_f32_e32 v179, v196, v179
	v_mul_f32_e32 v180, v198, v180
	v_mul_f32_e32 v181, v200, v181
	v_cvt_pk_bf16_f32 v178, v171, v178
	v_mul_f32_e32 v192, v193, v203
	v_mul_f32_e32 v193, v197, v204
	v_mul_f32_e32 v196, v199, v206
	v_cvt_pk_bf16_f32 v179, v192, v179
	v_cvt_pk_bf16_f32 v180, v193, v180
	v_cvt_pk_bf16_f32 v181, v196, v181
	global_store_dwordx4 v[194:195], v[178:181], off offset:1024
	v_rcp_f32_e32 v171, v201
	v_exp_f32_e32 v109, v109
	v_add_f32_e32 v178, 1.0, v205
	v_rcp_f32_e32 v178, v178
	v_lshlrev_b32_e32 v179, 16, v182
	v_mul_f32_e32 v171, v171, v179
	v_and_b32_e32 v179, 0xffff0000, v182
	v_mul_f32_e32 v178, v178, v179
	v_cvt_pk_bf16_f32 v178, v171, v178
	v_lshlrev_b32_e32 v171, 16, v183
	v_mul_f32_e32 v118, v118, v171
	v_and_b32_e32 v171, 0xffff0000, v183
	v_mul_f32_e32 v119, v119, v171
	v_cvt_pk_bf16_f32 v179, v118, v119
	v_lshlrev_b32_e32 v118, 16, v184
	v_mul_f32_e32 v112, v112, v118
	v_and_b32_e32 v118, 0xffff0000, v184
	v_mul_f32_e32 v113, v113, v118
	v_cvt_pk_bf16_f32 v180, v112, v113
	v_add_f32_e32 v112, 1.0, v114
	v_rcp_f32_e32 v112, v112
	v_add_f32_e32 v113, 1.0, v115
	v_rcp_f32_e32 v113, v113
	v_add_f32_e32 v108, 1.0, v108
	v_rcp_f32_e32 v108, v108
	v_add_f32_e32 v109, 1.0, v109
	v_lshlrev_b32_e32 v114, 16, v185
	v_rcp_f32_e32 v109, v109
	v_mul_f32_e32 v110, 0xbfb8aa3b, v110
	v_mul_f32_e32 v112, v112, v114
	v_and_b32_e32 v114, 0xffff0000, v185
	v_exp_f32_e32 v110, v110
	v_mul_f32_e32 v111, 0xbfb8aa3b, v111
	v_mul_f32_e32 v113, v113, v114
	v_lshlrev_b32_e32 v114, 16, v186
	v_exp_f32_e32 v111, v111
	v_mul_f32_e32 v108, v108, v114
	v_and_b32_e32 v114, 0xffff0000, v186
	v_mul_f32_e32 v104, 0xbfb8aa3b, v104
	v_mul_f32_e32 v109, v109, v114
	v_exp_f32_e32 v104, v104
	v_mul_f32_e32 v105, 0xbfb8aa3b, v105
	v_cvt_pk_bf16_f32 v181, v112, v113
	global_store_dwordx4 v[194:195], v[178:181], off offset:1280
	v_cvt_pk_bf16_f32 v108, v108, v109
	v_add_f32_e32 v109, 1.0, v110
	v_exp_f32_e32 v105, v105
	v_rcp_f32_e32 v109, v109
	v_add_f32_e32 v110, 1.0, v111
	v_rcp_f32_e32 v110, v110
	v_add_f32_e32 v104, 1.0, v104
	v_lshlrev_b32_e32 v111, 16, v187
	v_rcp_f32_e32 v104, v104
	v_add_f32_e32 v105, 1.0, v105
	v_mul_f32_e32 v106, 0xbfb8aa3b, v106
	v_mul_f32_e32 v109, v109, v111
	v_and_b32_e32 v111, 0xffff0000, v187
	v_rcp_f32_e32 v105, v105
	v_exp_f32_e32 v106, v106
	v_mul_f32_e32 v107, 0xbfb8aa3b, v107
	v_mul_f32_e32 v110, v110, v111
	v_exp_f32_e32 v107, v107
	v_mul_f32_e32 v100, 0xbfb8aa3b, v100
	v_cvt_pk_bf16_f32 v109, v109, v110
	v_lshlrev_b32_e32 v110, 16, v188
	v_exp_f32_e32 v100, v100
	v_mul_f32_e32 v101, 0xbfb8aa3b, v101
	v_mul_f32_e32 v104, v104, v110
	v_and_b32_e32 v110, 0xffff0000, v188
	v_exp_f32_e32 v101, v101
	v_mul_f32_e32 v105, v105, v110
	v_cvt_pk_bf16_f32 v110, v104, v105
	v_add_f32_e32 v104, 1.0, v106
	v_rcp_f32_e32 v104, v104
	v_add_f32_e32 v105, 1.0, v107
	v_rcp_f32_e32 v105, v105
	v_add_f32_e32 v100, 1.0, v100
	v_rcp_f32_e32 v100, v100
	v_add_f32_e32 v101, 1.0, v101
	v_lshlrev_b32_e32 v106, 16, v189
	v_rcp_f32_e32 v101, v101
	v_mul_f32_e32 v102, 0xbfb8aa3b, v102
	v_mul_f32_e32 v104, v104, v106
	v_and_b32_e32 v106, 0xffff0000, v189
	v_exp_f32_e32 v102, v102
	v_mul_f32_e32 v103, 0xbfb8aa3b, v103
	v_lshlrev_b64 v[112:113], 11, v[190:191]
	v_mul_f32_e32 v105, v105, v106
	v_lshlrev_b32_e32 v106, 16, v136
	v_exp_f32_e32 v103, v103
	v_cvt_pk_bf16_f32 v111, v104, v105
	v_lshl_add_u64 v[104:105], s[46:47], 0, v[112:113]
	v_mul_f32_e32 v100, v100, v106
	v_and_b32_e32 v106, 0xffff0000, v136
	v_mul_f32_e32 v96, 0xbfb8aa3b, v96
	v_lshl_add_u64 v[104:105], v[104:105], 0, v[168:169]
	v_mul_f32_e32 v101, v101, v106
	v_exp_f32_e32 v96, v96
	v_mul_f32_e32 v97, 0xbfb8aa3b, v97
	global_store_dwordx4 v[104:105], v[108:111], off offset:1024
	v_cvt_pk_bf16_f32 v100, v100, v101
	v_add_f32_e32 v101, 1.0, v102
	v_exp_f32_e32 v97, v97
	v_rcp_f32_e32 v101, v101
	v_add_f32_e32 v102, 1.0, v103
	v_rcp_f32_e32 v102, v102
	v_add_f32_e32 v96, 1.0, v96
	v_lshlrev_b32_e32 v103, 16, v137
	v_rcp_f32_e32 v96, v96
	v_add_f32_e32 v97, 1.0, v97
	v_mul_f32_e32 v98, 0xbfb8aa3b, v98
	v_mul_f32_e32 v101, v101, v103
	v_and_b32_e32 v103, 0xffff0000, v137
	v_rcp_f32_e32 v97, v97
	v_exp_f32_e32 v98, v98
	v_mul_f32_e32 v99, 0xbfb8aa3b, v99
	v_mul_f32_e32 v102, v102, v103
	v_exp_f32_e32 v99, v99
	v_mul_f32_e32 v92, 0xbfb8aa3b, v92
	v_cvt_pk_bf16_f32 v101, v101, v102
	v_lshlrev_b32_e32 v102, 16, v138
	v_exp_f32_e32 v92, v92
	v_mul_f32_e32 v93, 0xbfb8aa3b, v93
	v_mul_f32_e32 v96, v96, v102
	v_and_b32_e32 v102, 0xffff0000, v138
	v_exp_f32_e32 v93, v93
	v_mul_f32_e32 v97, v97, v102
	v_cvt_pk_bf16_f32 v102, v96, v97
	v_add_f32_e32 v96, 1.0, v98
	v_rcp_f32_e32 v96, v96
	v_add_f32_e32 v97, 1.0, v99
	v_rcp_f32_e32 v97, v97
	v_add_f32_e32 v92, 1.0, v92
	v_rcp_f32_e32 v92, v92
	v_add_f32_e32 v93, 1.0, v93
	v_lshlrev_b32_e32 v98, 16, v139
	v_rcp_f32_e32 v93, v93
	v_mul_f32_e32 v94, 0xbfb8aa3b, v94
	v_mul_f32_e32 v96, v96, v98
	v_and_b32_e32 v98, 0xffff0000, v139
	v_exp_f32_e32 v94, v94
	v_mul_f32_e32 v95, 0xbfb8aa3b, v95
	v_mul_f32_e32 v97, v97, v98
	v_lshlrev_b32_e32 v98, 16, v132
	v_exp_f32_e32 v95, v95
	v_mul_f32_e32 v92, v92, v98
	v_and_b32_e32 v98, 0xffff0000, v132
	v_mul_f32_e32 v88, 0xbfb8aa3b, v88
	v_mul_f32_e32 v93, v93, v98
	v_exp_f32_e32 v88, v88
	v_mul_f32_e32 v89, 0xbfb8aa3b, v89
	v_cvt_pk_bf16_f32 v103, v96, v97
; DI unsigned pk2(float lo, float hi) { unsigned r; asm volatile("v_cvt_pk_bf16_f32 %0, %1, %2" : "=v"(r) : "v"(lo), "v"(hi)); return r; }
; DI float bflo(unsigned u) { return __uint_as_float(u << 16); }
; DI float bfhi(unsigned u) { return __uint_as_float(u & 0xffff0000u); }
; DI float sigm(float x) { return __builtin_amdgcn_rcpf(1.f + __expf(-x)); }
;     DI void operator()(const f32x4 (&acc)[2][2][4][2], const Unit& u, int wr, int wc, int fr, int fq, const Pre& pre) const {
;     ...
;             for (int m = 0; m < 4; ++m) { const int row = row0 + ai * 128 + m * 16;
; #pragma unroll
;                 for (int bj = 0; bj < 2; ++bj) { const f32x4 v0 = acc[ai][bj][m][0], v1 = acc[ai][bj][m][1]; const u32x4v yy = y[m][bj]; u32x4v o;
;                     o.x = pk2(bflo(yy.x) * sigm(v0[0]), bfhi(yy.x) * sigm(v0[1])); o.y = pk2(bflo(yy.y) * sigm(v0[2]), bfhi(yy.y) * sigm(v0[3]));
;                     o.z = pk2(bflo(yy.z) * sigm(v1[0]), bfhi(yy.z) * sigm(v1[1])); o.w = pk2(bflo(yy.w) * sigm(v1[2]), bfhi(yy.w) * sigm(v1[3]));
;                     *(u32x4v*)(CAT + (size_t)row * 1024 + 512 + cb + bj * 128) = o; } } }
	global_store_dwordx4 v[104:105], v[100:103], off offset:1280
	v_cvt_pk_bf16_f32 v92, v92, v93
	v_add_f32_e32 v93, 1.0, v94
	v_exp_f32_e32 v89, v89
	v_rcp_f32_e32 v93, v93
	v_add_f32_e32 v94, 1.0, v95
	v_rcp_f32_e32 v94, v94
	v_add_f32_e32 v88, 1.0, v88
	v_lshlrev_b32_e32 v95, 16, v133
	v_rcp_f32_e32 v88, v88
	v_add_f32_e32 v89, 1.0, v89
	v_mul_f32_e32 v90, 0xbfb8aa3b, v90
	v_mul_f32_e32 v93, v93, v95
	v_and_b32_e32 v95, 0xffff0000, v133
	v_rcp_f32_e32 v89, v89
	v_exp_f32_e32 v90, v90
	v_mul_f32_e32 v91, 0xbfb8aa3b, v91
	v_mul_f32_e32 v94, v94, v95
	v_exp_f32_e32 v91, v91
	v_mul_f32_e32 v84, 0xbfb8aa3b, v84
	v_cvt_pk_bf16_f32 v93, v93, v94
	v_lshlrev_b32_e32 v94, 16, v134
	v_exp_f32_e32 v84, v84
	v_mul_f32_e32 v85, 0xbfb8aa3b, v85
	v_mul_f32_e32 v88, v88, v94
	v_and_b32_e32 v94, 0xffff0000, v134
	v_exp_f32_e32 v85, v85
	v_mul_f32_e32 v89, v89, v94
	v_cvt_pk_bf16_f32 v94, v88, v89
	v_add_f32_e32 v88, 1.0, v90
	v_rcp_f32_e32 v88, v88
	v_add_f32_e32 v89, 1.0, v91
	v_rcp_f32_e32 v89, v89
	v_add_f32_e32 v84, 1.0, v84
	v_rcp_f32_e32 v84, v84
	v_add_f32_e32 v85, 1.0, v85
	v_lshlrev_b32_e32 v90, 16, v135
	v_rcp_f32_e32 v85, v85
	v_mul_f32_e32 v86, 0xbfb8aa3b, v86
	v_mul_f32_e32 v88, v88, v90
	v_and_b32_e32 v90, 0xffff0000, v135
	v_exp_f32_e32 v86, v86
	v_mul_f32_e32 v87, 0xbfb8aa3b, v87
	v_lshlrev_b64 v[96:97], 11, v[174:175]
	v_mul_f32_e32 v89, v89, v90
	v_lshlrev_b32_e32 v90, 16, v128
	v_exp_f32_e32 v87, v87
	v_cvt_pk_bf16_f32 v95, v88, v89
	v_lshl_add_u64 v[88:89], s[46:47], 0, v[96:97]
	v_mul_f32_e32 v84, v84, v90
	v_and_b32_e32 v90, 0xffff0000, v128
	v_mul_f32_e32 v80, 0xbfb8aa3b, v80
	v_lshl_add_u64 v[88:89], v[88:89], 0, v[168:169]
	v_mul_f32_e32 v85, v85, v90
	v_exp_f32_e32 v80, v80
	v_mul_f32_e32 v81, 0xbfb8aa3b, v81
	global_store_dwordx4 v[88:89], v[92:95], off offset:1024
	v_cvt_pk_bf16_f32 v84, v84, v85
	v_add_f32_e32 v85, 1.0, v86
	v_exp_f32_e32 v81, v81
	v_rcp_f32_e32 v85, v85
	v_add_f32_e32 v86, 1.0, v87
	v_rcp_f32_e32 v86, v86
	v_add_f32_e32 v80, 1.0, v80
	v_lshlrev_b32_e32 v87, 16, v129
	v_rcp_f32_e32 v80, v80
	v_add_f32_e32 v81, 1.0, v81
	v_mul_f32_e32 v82, 0xbfb8aa3b, v82
	v_mul_f32_e32 v85, v85, v87
	v_and_b32_e32 v87, 0xffff0000, v129
	v_rcp_f32_e32 v81, v81
	v_exp_f32_e32 v82, v82
	v_mul_f32_e32 v83, 0xbfb8aa3b, v83
	v_mul_f32_e32 v86, v86, v87
	v_exp_f32_e32 v83, v83
	v_mul_f32_e32 v76, 0xbfb8aa3b, v76
	v_cvt_pk_bf16_f32 v85, v85, v86
	v_lshlrev_b32_e32 v86, 16, v130
	v_exp_f32_e32 v76, v76
	v_mul_f32_e32 v77, 0xbfb8aa3b, v77
	v_mul_f32_e32 v80, v80, v86
	v_and_b32_e32 v86, 0xffff0000, v130
	v_exp_f32_e32 v77, v77
	v_mul_f32_e32 v81, v81, v86
	v_cvt_pk_bf16_f32 v86, v80, v81
	v_add_f32_e32 v80, 1.0, v82
	v_rcp_f32_e32 v80, v80
	v_add_f32_e32 v81, 1.0, v83
	v_rcp_f32_e32 v81, v81
	v_add_f32_e32 v76, 1.0, v76
	v_rcp_f32_e32 v76, v76
	v_add_f32_e32 v77, 1.0, v77
	v_lshlrev_b32_e32 v82, 16, v131
	v_rcp_f32_e32 v77, v77
	v_mul_f32_e32 v78, 0xbfb8aa3b, v78
	v_mul_f32_e32 v80, v80, v82
	v_and_b32_e32 v82, 0xffff0000, v131
	v_exp_f32_e32 v78, v78
	v_mul_f32_e32 v79, 0xbfb8aa3b, v79
	v_mul_f32_e32 v81, v81, v82
	v_lshlrev_b32_e32 v82, 16, v124
	v_exp_f32_e32 v79, v79
	v_mul_f32_e32 v76, v76, v82
	v_and_b32_e32 v82, 0xffff0000, v124
	v_mul_f32_e32 v72, 0xbfb8aa3b, v72
	v_mul_f32_e32 v77, v77, v82
	v_exp_f32_e32 v72, v72
	v_mul_f32_e32 v73, 0xbfb8aa3b, v73
	v_cvt_pk_bf16_f32 v87, v80, v81
	global_store_dwordx4 v[88:89], v[84:87], off offset:1280
	v_cvt_pk_bf16_f32 v76, v76, v77
	v_add_f32_e32 v77, 1.0, v78
	v_exp_f32_e32 v73, v73
	v_rcp_f32_e32 v77, v77
	v_add_f32_e32 v78, 1.0, v79
	v_rcp_f32_e32 v78, v78
	v_add_f32_e32 v72, 1.0, v72
	v_lshlrev_b32_e32 v79, 16, v125
	v_rcp_f32_e32 v72, v72
	v_add_f32_e32 v73, 1.0, v73
	v_mul_f32_e32 v74, 0xbfb8aa3b, v74
	v_mul_f32_e32 v77, v77, v79
	v_and_b32_e32 v79, 0xffff0000, v125
	v_rcp_f32_e32 v73, v73
	v_exp_f32_e32 v74, v74
	v_mul_f32_e32 v75, 0xbfb8aa3b, v75
	v_mul_f32_e32 v78, v78, v79
	v_exp_f32_e32 v75, v75
	v_mul_f32_e32 v68, 0xbfb8aa3b, v68
	v_cvt_pk_bf16_f32 v77, v77, v78
	v_lshlrev_b32_e32 v78, 16, v126
	v_exp_f32_e32 v68, v68
	v_mul_f32_e32 v69, 0xbfb8aa3b, v69
	v_mul_f32_e32 v72, v72, v78
	v_and_b32_e32 v78, 0xffff0000, v126
	v_exp_f32_e32 v69, v69
	v_mul_f32_e32 v73, v73, v78
	v_cvt_pk_bf16_f32 v78, v72, v73
	v_add_f32_e32 v72, 1.0, v74
	v_rcp_f32_e32 v72, v72
	v_add_f32_e32 v73, 1.0, v75
	v_rcp_f32_e32 v73, v73
	v_add_f32_e32 v68, 1.0, v68
	v_rcp_f32_e32 v68, v68
	v_add_f32_e32 v69, 1.0, v69
	v_lshlrev_b32_e32 v74, 16, v127
	v_rcp_f32_e32 v69, v69
	v_mul_f32_e32 v70, 0xbfb8aa3b, v70
	v_mul_f32_e32 v72, v72, v74
	v_and_b32_e32 v74, 0xffff0000, v127
	v_exp_f32_e32 v70, v70
	v_mul_f32_e32 v71, 0xbfb8aa3b, v71
	v_lshlrev_b64 v[80:81], 11, v[116:117]
	v_mul_f32_e32 v73, v73, v74
	v_lshlrev_b32_e32 v74, 16, v120
	v_exp_f32_e32 v71, v71
	v_cvt_pk_bf16_f32 v79, v72, v73
	v_lshl_add_u64 v[72:73], s[46:47], 0, v[80:81]
	v_mul_f32_e32 v68, v68, v74
	v_and_b32_e32 v74, 0xffff0000, v120
	v_mul_f32_e32 v64, 0xbfb8aa3b, v64
	v_lshl_add_u64 v[72:73], v[72:73], 0, v[168:169]
	v_mul_f32_e32 v69, v69, v74
	v_exp_f32_e32 v64, v64
	v_mul_f32_e32 v65, 0xbfb8aa3b, v65
	global_store_dwordx4 v[72:73], v[76:79], off offset:1024
	v_cvt_pk_bf16_f32 v68, v68, v69
	v_add_f32_e32 v69, 1.0, v70
	v_exp_f32_e32 v65, v65
	v_rcp_f32_e32 v69, v69
	v_add_f32_e32 v70, 1.0, v71
	v_rcp_f32_e32 v70, v70
	v_add_f32_e32 v64, 1.0, v64
	v_lshlrev_b32_e32 v71, 16, v121
	v_rcp_f32_e32 v64, v64
	v_add_f32_e32 v65, 1.0, v65
	v_mul_f32_e32 v66, 0xbfb8aa3b, v66
	v_mul_f32_e32 v69, v69, v71
	v_and_b32_e32 v71, 0xffff0000, v121
	v_rcp_f32_e32 v65, v65
	v_exp_f32_e32 v66, v66
	v_mul_f32_e32 v67, 0xbfb8aa3b, v67
	v_mul_f32_e32 v70, v70, v71
; DI unsigned pk2(float lo, float hi) { unsigned r; asm volatile("v_cvt_pk_bf16_f32 %0, %1, %2" : "=v"(r) : "v"(lo), "v"(hi)); return r; }
; DI float bflo(unsigned u) { return __uint_as_float(u << 16); }
; DI float bfhi(unsigned u) { return __uint_as_float(u & 0xffff0000u); }
; DI float sigm(float x) { return __builtin_amdgcn_rcpf(1.f + __expf(-x)); }
;     DI void operator()(const f32x4 (&acc)[2][2][4][2], const Unit& u, int wr, int wc, int fr, int fq, const Pre& pre) const {
;     ...
;         for (int ai = 0; ai < 2; ++ai) {
;             u32x4v y[4][2];
; #pragma unroll
;             for (int m = 0; m < 4; ++m)
; #pragma unroll
;                 for (int bj = 0; bj < 2; ++bj) y[m][bj] = *(const u32x4v*)(YG + (size_t)(row0 + ai * 128 + m * 16) * 512 + cb + bj * 128);
; #pragma unroll
;             for (int m = 0; m < 4; ++m) { const int row = row0 + ai * 128 + m * 16;
; #pragma unroll
;                 for (int bj = 0; bj < 2; ++bj) { const f32x4 v0 = acc[ai][bj][m][0], v1 = acc[ai][bj][m][1]; const u32x4v yy = y[m][bj]; u32x4v o;
;                     o.x = pk2(bflo(yy.x) * sigm(v0[0]), bfhi(yy.x) * sigm(v0[1])); o.y = pk2(bflo(yy.y) * sigm(v0[2]), bfhi(yy.y) * sigm(v0[3]));
;                     o.z = pk2(bflo(yy.z) * sigm(v1[0]), bfhi(yy.z) * sigm(v1[1])); o.w = pk2(bflo(yy.w) * sigm(v1[2]), bfhi(yy.w) * sigm(v1[3]));
;                     *(u32x4v*)(CAT + (size_t)row * 1024 + 512 + cb + bj * 128) = o; } } }
	v_exp_f32_e32 v67, v67
	v_cvt_pk_bf16_f32 v69, v69, v70
	v_lshlrev_b32_e32 v70, 16, v122
	v_mul_f32_e32 v64, v64, v70
	v_and_b32_e32 v70, 0xffff0000, v122
	v_mul_f32_e32 v65, v65, v70
	v_cvt_pk_bf16_f32 v70, v64, v65
	v_add_f32_e32 v64, 1.0, v66
	v_rcp_f32_e32 v64, v64
	v_add_f32_e32 v65, 1.0, v67
	v_rcp_f32_e32 v65, v65
	v_lshlrev_b32_e32 v66, 16, v123
	v_mul_f32_e32 v64, v64, v66
	v_and_b32_e32 v66, 0xffff0000, v123
	v_add_u32_e32 v100, 0x80, v170
	v_mul_f32_e32 v65, v65, v66
	v_ashrrev_i32_e32 v101, 31, v100
	v_cvt_pk_bf16_f32 v71, v64, v65
	v_lshlrev_b64 v[64:65], 10, v[100:101]
	global_store_dwordx4 v[72:73], v[68:71], off offset:1280
	v_lshl_add_u64 v[64:65], v[172:173], 0, v[64:65]
	global_load_dwordx4 v[92:95], v[64:65], off
	global_load_dwordx4 v[96:99], v[64:65], off offset:256
	v_add_u32_e32 v102, 0x90, v170
	v_ashrrev_i32_e32 v103, 31, v102
	v_lshlrev_b64 v[64:65], 10, v[102:103]
	v_lshl_add_u64 v[64:65], v[172:173], 0, v[64:65]
	global_load_dwordx4 v[84:87], v[64:65], off
	global_load_dwordx4 v[80:83], v[64:65], off offset:256
	v_add_u32_e32 v90, 0xa0, v170
	v_ashrrev_i32_e32 v91, 31, v90
	v_lshlrev_b64 v[64:65], 10, v[90:91]
	v_lshl_add_u64 v[64:65], v[172:173], 0, v[64:65]
	v_mul_f32_e32 v60, 0xbfb8aa3b, v60
	v_mul_f32_e32 v61, 0xbfb8aa3b, v61
	global_load_dwordx4 v[76:79], v[64:65], off
	global_load_dwordx4 v[72:75], v[64:65], off offset:256
	v_exp_f32_e32 v60, v60
	v_exp_f32_e32 v61, v61
	v_mul_f32_e32 v62, 0xbfb8aa3b, v62
	v_add_u32_e32 v88, 0xb0, v170
	v_add_f32_e32 v60, 1.0, v60
	v_add_f32_e32 v61, 1.0, v61
	v_rcp_f32_e32 v60, v60
	v_rcp_f32_e32 v61, v61
	v_exp_f32_e32 v62, v62
	v_mul_f32_e32 v63, 0xbfb8aa3b, v63
	v_ashrrev_i32_e32 v89, 31, v88
	v_exp_f32_e32 v63, v63
	v_lshlrev_b64 v[64:65], 10, v[88:89]
	v_mul_f32_e32 v56, 0xbfb8aa3b, v56
	v_lshl_add_u64 v[64:65], v[172:173], 0, v[64:65]
	v_exp_f32_e32 v56, v56
	v_mul_f32_e32 v57, 0xbfb8aa3b, v57
	global_load_dwordx4 v[68:71], v[64:65], off
	s_nop 0
	global_load_dwordx4 v[64:67], v[64:65], off offset:256
	v_exp_f32_e32 v57, v57
	v_add_f32_e32 v56, 1.0, v56
	v_rcp_f32_e32 v56, v56
	v_mul_f32_e32 v58, 0xbfb8aa3b, v58
	v_add_f32_e32 v57, 1.0, v57
	v_rcp_f32_e32 v57, v57
	v_exp_f32_e32 v58, v58
	v_mul_f32_e32 v59, 0xbfb8aa3b, v59
	v_exp_f32_e32 v59, v59
	v_mul_f32_e32 v52, 0xbfb8aa3b, v52
	v_exp_f32_e32 v52, v52
	v_mul_f32_e32 v53, 0xbfb8aa3b, v53
	v_exp_f32_e32 v53, v53
	v_mul_f32_e32 v54, 0xbfb8aa3b, v54
	v_add_f32_e32 v52, 1.0, v52
	v_rcp_f32_e32 v52, v52
	v_add_f32_e32 v53, 1.0, v53
	v_rcp_f32_e32 v53, v53
	v_exp_f32_e32 v54, v54
	v_mul_f32_e32 v55, 0xbfb8aa3b, v55
	v_lshlrev_b64 v[100:101], 11, v[100:101]
	v_exp_f32_e32 v55, v55
	v_mul_f32_e32 v48, 0xbfb8aa3b, v48
	v_exp_f32_e32 v48, v48
	v_mul_f32_e32 v49, 0xbfb8aa3b, v49
	v_exp_f32_e32 v49, v49
	v_mul_f32_e32 v50, 0xbfb8aa3b, v50
	v_add_f32_e32 v48, 1.0, v48
	v_rcp_f32_e32 v48, v48
	v_add_f32_e32 v49, 1.0, v49
	v_rcp_f32_e32 v49, v49
	v_exp_f32_e32 v50, v50
	v_mul_f32_e32 v51, 0xbfb8aa3b, v51
	v_exp_f32_e32 v51, v51
	v_mul_f32_e32 v44, 0xbfb8aa3b, v44
	v_exp_f32_e32 v44, v44
	v_mul_f32_e32 v45, 0xbfb8aa3b, v45
	v_exp_f32_e32 v45, v45
	v_mul_f32_e32 v46, 0xbfb8aa3b, v46
	v_add_f32_e32 v44, 1.0, v44
	v_rcp_f32_e32 v44, v44
	v_add_f32_e32 v45, 1.0, v45
	v_rcp_f32_e32 v45, v45
	v_exp_f32_e32 v46, v46
	v_mul_f32_e32 v47, 0xbfb8aa3b, v47
	v_exp_f32_e32 v47, v47
	v_mul_f32_e32 v40, 0xbfb8aa3b, v40
	v_exp_f32_e32 v40, v40
	s_waitcnt vmcnt(0)
	v_lshlrev_b32_e32 v104, 16, v92
	v_and_b32_e32 v92, 0xffff0000, v92
	v_mul_f32_e32 v60, v60, v104
	v_mul_f32_e32 v61, v61, v92
	v_cvt_pk_bf16_f32 v60, v60, v61
	v_add_f32_e32 v61, 1.0, v62
	v_rcp_f32_e32 v61, v61
	v_add_f32_e32 v62, 1.0, v63
	v_rcp_f32_e32 v62, v62
	v_lshlrev_b32_e32 v63, 16, v93
	v_mul_f32_e32 v61, v61, v63
	v_and_b32_e32 v63, 0xffff0000, v93
	v_mul_f32_e32 v62, v62, v63
	v_cvt_pk_bf16_f32 v61, v61, v62
	v_lshlrev_b32_e32 v62, 16, v94
	v_mul_f32_e32 v56, v56, v62
	v_and_b32_e32 v62, 0xffff0000, v94
	v_mul_f32_e32 v57, v57, v62
	v_cvt_pk_bf16_f32 v62, v56, v57
	v_add_f32_e32 v56, 1.0, v58
	v_rcp_f32_e32 v56, v56
	v_add_f32_e32 v57, 1.0, v59
	v_rcp_f32_e32 v57, v57
	v_lshlrev_b32_e32 v58, 16, v95
	v_mul_f32_e32 v56, v56, v58
	v_and_b32_e32 v58, 0xffff0000, v95
	v_mul_f32_e32 v57, v57, v58
	v_lshlrev_b32_e32 v58, 16, v96
	v_cvt_pk_bf16_f32 v63, v56, v57
	v_lshl_add_u64 v[56:57], s[46:47], 0, v[100:101]
	v_mul_f32_e32 v52, v52, v58
	v_and_b32_e32 v58, 0xffff0000, v96
	v_lshl_add_u64 v[56:57], v[56:57], 0, v[168:169]
	v_mul_f32_e32 v53, v53, v58
	global_store_dwordx4 v[56:57], v[60:63], off offset:1024
	v_cvt_pk_bf16_f32 v52, v52, v53
	v_add_f32_e32 v53, 1.0, v54
	v_rcp_f32_e32 v53, v53
	v_add_f32_e32 v54, 1.0, v55
	v_rcp_f32_e32 v54, v54
	v_lshlrev_b32_e32 v55, 16, v97
	v_mul_f32_e32 v53, v53, v55
	v_and_b32_e32 v55, 0xffff0000, v97
	v_mul_f32_e32 v54, v54, v55
	v_cvt_pk_bf16_f32 v53, v53, v54
	v_lshlrev_b32_e32 v54, 16, v98
	v_mul_f32_e32 v48, v48, v54
	v_and_b32_e32 v54, 0xffff0000, v98
	v_mul_f32_e32 v49, v49, v54
	v_cvt_pk_bf16_f32 v54, v48, v49
	v_add_f32_e32 v48, 1.0, v50
	v_rcp_f32_e32 v48, v48
	v_add_f32_e32 v49, 1.0, v51
	v_rcp_f32_e32 v49, v49
	v_lshlrev_b32_e32 v50, 16, v99
	v_mul_f32_e32 v48, v48, v50
	v_and_b32_e32 v50, 0xffff0000, v99
	v_mul_f32_e32 v49, v49, v50
	v_lshlrev_b32_e32 v50, 16, v84
	v_mul_f32_e32 v44, v44, v50
	v_and_b32_e32 v50, 0xffff0000, v84
	v_mul_f32_e32 v45, v45, v50
	v_mul_f32_e32 v41, 0xbfb8aa3b, v41
	v_cvt_pk_bf16_f32 v55, v48, v49
	global_store_dwordx4 v[56:57], v[52:55], off offset:1280
	v_cvt_pk_bf16_f32 v44, v44, v45
	v_add_f32_e32 v45, 1.0, v46
	v_exp_f32_e32 v41, v41
	v_rcp_f32_e32 v45, v45
	v_add_f32_e32 v46, 1.0, v47
; DI unsigned pk2(float lo, float hi) { unsigned r; asm volatile("v_cvt_pk_bf16_f32 %0, %1, %2" : "=v"(r) : "v"(lo), "v"(hi)); return r; }
; DI float bflo(unsigned u) { return __uint_as_float(u << 16); }
; DI float bfhi(unsigned u) { return __uint_as_float(u & 0xffff0000u); }
; DI float sigm(float x) { return __builtin_amdgcn_rcpf(1.f + __expf(-x)); }
;     DI void operator()(const f32x4 (&acc)[2][2][4][2], const Unit& u, int wr, int wc, int fr, int fq, const Pre& pre) const {
;     ...
;             for (int m = 0; m < 4; ++m) { const int row = row0 + ai * 128 + m * 16;
; #pragma unroll
;                 for (int bj = 0; bj < 2; ++bj) { const f32x4 v0 = acc[ai][bj][m][0], v1 = acc[ai][bj][m][1]; const u32x4v yy = y[m][bj]; u32x4v o;
;                     o.x = pk2(bflo(yy.x) * sigm(v0[0]), bfhi(yy.x) * sigm(v0[1])); o.y = pk2(bflo(yy.y) * sigm(v0[2]), bfhi(yy.y) * sigm(v0[3]));
;                     o.z = pk2(bflo(yy.z) * sigm(v1[0]), bfhi(yy.z) * sigm(v1[1])); o.w = pk2(bflo(yy.w) * sigm(v1[2]), bfhi(yy.w) * sigm(v1[3]));
;                     *(u32x4v*)(CAT + (size_t)row * 1024 + 512 + cb + bj * 128) = o; } } }
	v_rcp_f32_e32 v46, v46
	v_add_f32_e32 v40, 1.0, v40
	v_lshlrev_b32_e32 v47, 16, v85
	v_rcp_f32_e32 v40, v40
	v_add_f32_e32 v41, 1.0, v41
	v_mul_f32_e32 v42, 0xbfb8aa3b, v42
	v_mul_f32_e32 v45, v45, v47
	v_and_b32_e32 v47, 0xffff0000, v85
	v_rcp_f32_e32 v41, v41
	v_exp_f32_e32 v42, v42
	v_mul_f32_e32 v43, 0xbfb8aa3b, v43
	v_mul_f32_e32 v46, v46, v47
	v_exp_f32_e32 v43, v43
	v_mul_f32_e32 v36, 0xbfb8aa3b, v36
	v_cvt_pk_bf16_f32 v45, v45, v46
	v_lshlrev_b32_e32 v46, 16, v86
	v_exp_f32_e32 v36, v36
	v_mul_f32_e32 v37, 0xbfb8aa3b, v37
	v_mul_f32_e32 v40, v40, v46
	v_and_b32_e32 v46, 0xffff0000, v86
	v_exp_f32_e32 v37, v37
	v_mul_f32_e32 v41, v41, v46
	v_cvt_pk_bf16_f32 v46, v40, v41
	v_add_f32_e32 v40, 1.0, v42
	v_rcp_f32_e32 v40, v40
	v_add_f32_e32 v41, 1.0, v43
	v_rcp_f32_e32 v41, v41
	v_add_f32_e32 v36, 1.0, v36
	v_rcp_f32_e32 v36, v36
	v_add_f32_e32 v37, 1.0, v37
	v_lshlrev_b32_e32 v42, 16, v87
	v_rcp_f32_e32 v37, v37
	v_mul_f32_e32 v38, 0xbfb8aa3b, v38
	v_mul_f32_e32 v40, v40, v42
	v_and_b32_e32 v42, 0xffff0000, v87
	v_exp_f32_e32 v38, v38
	v_mul_f32_e32 v39, 0xbfb8aa3b, v39
	v_lshlrev_b64 v[48:49], 11, v[102:103]
	v_mul_f32_e32 v41, v41, v42
	v_lshlrev_b32_e32 v42, 16, v80
	v_exp_f32_e32 v39, v39
	v_cvt_pk_bf16_f32 v47, v40, v41
	v_lshl_add_u64 v[40:41], s[46:47], 0, v[48:49]
	v_mul_f32_e32 v36, v36, v42
	v_and_b32_e32 v42, 0xffff0000, v80
	v_mul_f32_e32 v32, 0xbfb8aa3b, v32
	v_lshl_add_u64 v[40:41], v[40:41], 0, v[168:169]
	v_mul_f32_e32 v37, v37, v42
	v_exp_f32_e32 v32, v32
	v_mul_f32_e32 v33, 0xbfb8aa3b, v33
	global_store_dwordx4 v[40:41], v[44:47], off offset:1024
	v_cvt_pk_bf16_f32 v36, v36, v37
	v_add_f32_e32 v37, 1.0, v38
	v_exp_f32_e32 v33, v33
	v_rcp_f32_e32 v37, v37
	v_add_f32_e32 v38, 1.0, v39
	v_rcp_f32_e32 v38, v38
	v_add_f32_e32 v32, 1.0, v32
	v_lshlrev_b32_e32 v39, 16, v81
	v_rcp_f32_e32 v32, v32
	v_add_f32_e32 v33, 1.0, v33
	v_mul_f32_e32 v34, 0xbfb8aa3b, v34
	v_mul_f32_e32 v37, v37, v39
	v_and_b32_e32 v39, 0xffff0000, v81
	v_rcp_f32_e32 v33, v33
	v_exp_f32_e32 v34, v34
	v_mul_f32_e32 v35, 0xbfb8aa3b, v35
	v_mul_f32_e32 v38, v38, v39
	v_exp_f32_e32 v35, v35
	v_mul_f32_e32 v28, 0xbfb8aa3b, v28
	v_cvt_pk_bf16_f32 v37, v37, v38
	v_lshlrev_b32_e32 v38, 16, v82
	v_exp_f32_e32 v28, v28
	v_mul_f32_e32 v29, 0xbfb8aa3b, v29
	v_mul_f32_e32 v32, v32, v38
	v_and_b32_e32 v38, 0xffff0000, v82
	v_exp_f32_e32 v29, v29
	v_mul_f32_e32 v33, v33, v38
	v_cvt_pk_bf16_f32 v38, v32, v33
	v_add_f32_e32 v32, 1.0, v34
	v_rcp_f32_e32 v32, v32
	v_add_f32_e32 v33, 1.0, v35
	v_rcp_f32_e32 v33, v33
	v_add_f32_e32 v28, 1.0, v28
	v_rcp_f32_e32 v28, v28
	v_add_f32_e32 v29, 1.0, v29
	v_lshlrev_b32_e32 v34, 16, v83
	v_rcp_f32_e32 v29, v29
	v_mul_f32_e32 v30, 0xbfb8aa3b, v30
	v_mul_f32_e32 v32, v32, v34
	v_and_b32_e32 v34, 0xffff0000, v83
	v_exp_f32_e32 v30, v30
	v_mul_f32_e32 v31, 0xbfb8aa3b, v31
	v_mul_f32_e32 v33, v33, v34
	v_lshlrev_b32_e32 v34, 16, v76
	v_exp_f32_e32 v31, v31
	v_mul_f32_e32 v28, v28, v34
	v_and_b32_e32 v34, 0xffff0000, v76
	v_mul_f32_e32 v24, 0xbfb8aa3b, v24
	v_mul_f32_e32 v29, v29, v34
	v_exp_f32_e32 v24, v24
	v_mul_f32_e32 v25, 0xbfb8aa3b, v25
	v_cvt_pk_bf16_f32 v39, v32, v33
	global_store_dwordx4 v[40:41], v[36:39], off offset:1280
	v_cvt_pk_bf16_f32 v28, v28, v29
	v_add_f32_e32 v29, 1.0, v30
	v_exp_f32_e32 v25, v25
	v_rcp_f32_e32 v29, v29
	v_add_f32_e32 v30, 1.0, v31
	v_rcp_f32_e32 v30, v30
	v_add_f32_e32 v24, 1.0, v24
	v_lshlrev_b32_e32 v31, 16, v77
	v_rcp_f32_e32 v24, v24
	v_add_f32_e32 v25, 1.0, v25
	v_mul_f32_e32 v26, 0xbfb8aa3b, v26
	v_mul_f32_e32 v29, v29, v31
	v_and_b32_e32 v31, 0xffff0000, v77
	v_rcp_f32_e32 v25, v25
	v_exp_f32_e32 v26, v26
	v_mul_f32_e32 v27, 0xbfb8aa3b, v27
	v_mul_f32_e32 v30, v30, v31
	v_exp_f32_e32 v27, v27
	v_mul_f32_e32 v20, 0xbfb8aa3b, v20
	v_cvt_pk_bf16_f32 v29, v29, v30
	v_lshlrev_b32_e32 v30, 16, v78
	v_exp_f32_e32 v20, v20
	v_mul_f32_e32 v21, 0xbfb8aa3b, v21
	v_mul_f32_e32 v24, v24, v30
	v_and_b32_e32 v30, 0xffff0000, v78
	v_exp_f32_e32 v21, v21
	v_mul_f32_e32 v25, v25, v30
	v_cvt_pk_bf16_f32 v30, v24, v25
	v_add_f32_e32 v24, 1.0, v26
	v_rcp_f32_e32 v24, v24
	v_add_f32_e32 v25, 1.0, v27
	v_rcp_f32_e32 v25, v25
	v_add_f32_e32 v20, 1.0, v20
	v_rcp_f32_e32 v20, v20
	v_add_f32_e32 v21, 1.0, v21
	v_lshlrev_b32_e32 v26, 16, v79
	v_rcp_f32_e32 v21, v21
	v_mul_f32_e32 v22, 0xbfb8aa3b, v22
	v_mul_f32_e32 v24, v24, v26
	v_and_b32_e32 v26, 0xffff0000, v79
	v_exp_f32_e32 v22, v22
	v_mul_f32_e32 v23, 0xbfb8aa3b, v23
	v_lshlrev_b64 v[32:33], 11, v[90:91]
	v_mul_f32_e32 v25, v25, v26
	v_lshlrev_b32_e32 v26, 16, v72
	v_exp_f32_e32 v23, v23
	v_cvt_pk_bf16_f32 v31, v24, v25
	v_lshl_add_u64 v[24:25], s[46:47], 0, v[32:33]
	v_mul_f32_e32 v20, v20, v26
	v_and_b32_e32 v26, 0xffff0000, v72
	v_mul_f32_e32 v16, 0xbfb8aa3b, v16
	v_lshl_add_u64 v[24:25], v[24:25], 0, v[168:169]
	v_mul_f32_e32 v21, v21, v26
	v_exp_f32_e32 v16, v16
	v_mul_f32_e32 v17, 0xbfb8aa3b, v17
; #define PG8_WAIT_V(n) asm volatile("s_waitcnt vmcnt(" #n ")" ::: "memory")
; #define PG8_BAR __builtin_amdgcn_s_barrier()
; DI unsigned pk2(float lo, float hi) { unsigned r; asm volatile("v_cvt_pk_bf16_f32 %0, %1, %2" : "=v"(r) : "v"(lo), "v"(hi)); return r; }
; DI float bflo(unsigned u) { return __uint_as_float(u << 16); }
; DI float bfhi(unsigned u) { return __uint_as_float(u & 0xffff0000u); }
; DI float sigm(float x) { return __builtin_amdgcn_rcpf(1.f + __expf(-x)); }
; template <class Epi, class Sched>
; __device__ __forceinline__ void gemm_phase(PG8_LAS unsigned char* lds, const Gemm g, const Sched& S, const Epi& E) {
;     ...
;     PG8_WAIT_V(0);
;     if (wr == 0) PG8_BAR;
;     PG8_BAR;
;     DI void operator()(const f32x4 (&acc)[2][2][4][2], const Unit& u, int wr, int wc, int fr, int fq, const Pre& pre) const {
;     ...
;             for (int m = 0; m < 4; ++m) { const int row = row0 + ai * 128 + m * 16;
; #pragma unroll
;                 for (int bj = 0; bj < 2; ++bj) { const f32x4 v0 = acc[ai][bj][m][0], v1 = acc[ai][bj][m][1]; const u32x4v yy = y[m][bj]; u32x4v o;
;                     o.x = pk2(bflo(yy.x) * sigm(v0[0]), bfhi(yy.x) * sigm(v0[1])); o.y = pk2(bflo(yy.y) * sigm(v0[2]), bfhi(yy.y) * sigm(v0[3]));
;                     o.z = pk2(bflo(yy.z) * sigm(v1[0]), bfhi(yy.z) * sigm(v1[1])); o.w = pk2(bflo(yy.w) * sigm(v1[2]), bfhi(yy.w) * sigm(v1[3]));
;                     *(u32x4v*)(CAT + (size_t)row * 1024 + 512 + cb + bj * 128) = o; } } }
	global_store_dwordx4 v[24:25], v[28:31], off offset:1024
	v_cvt_pk_bf16_f32 v20, v20, v21
	v_add_f32_e32 v21, 1.0, v22
	v_exp_f32_e32 v17, v17
	v_rcp_f32_e32 v21, v21
	v_add_f32_e32 v22, 1.0, v23
	v_rcp_f32_e32 v22, v22
	v_add_f32_e32 v16, 1.0, v16
	v_lshlrev_b32_e32 v23, 16, v73
	v_rcp_f32_e32 v16, v16
	v_add_f32_e32 v17, 1.0, v17
	v_mul_f32_e32 v18, 0xbfb8aa3b, v18
	v_mul_f32_e32 v21, v21, v23
	v_and_b32_e32 v23, 0xffff0000, v73
	v_rcp_f32_e32 v17, v17
	v_exp_f32_e32 v18, v18
	v_mul_f32_e32 v19, 0xbfb8aa3b, v19
	v_mul_f32_e32 v22, v22, v23
	v_exp_f32_e32 v19, v19
	v_mul_f32_e32 v12, 0xbfb8aa3b, v12
	v_cvt_pk_bf16_f32 v21, v21, v22
	v_lshlrev_b32_e32 v22, 16, v74
	v_exp_f32_e32 v12, v12
	v_mul_f32_e32 v13, 0xbfb8aa3b, v13
	v_mul_f32_e32 v16, v16, v22
	v_and_b32_e32 v22, 0xffff0000, v74
	v_exp_f32_e32 v13, v13
	v_mul_f32_e32 v17, v17, v22
	v_cvt_pk_bf16_f32 v22, v16, v17
	v_add_f32_e32 v16, 1.0, v18
	v_rcp_f32_e32 v16, v16
	v_add_f32_e32 v17, 1.0, v19
	v_rcp_f32_e32 v17, v17
	v_add_f32_e32 v12, 1.0, v12
	v_rcp_f32_e32 v12, v12
	v_add_f32_e32 v13, 1.0, v13
	v_lshlrev_b32_e32 v18, 16, v75
	v_rcp_f32_e32 v13, v13
	v_mul_f32_e32 v14, 0xbfb8aa3b, v14
	v_mul_f32_e32 v16, v16, v18
	v_and_b32_e32 v18, 0xffff0000, v75
	v_exp_f32_e32 v14, v14
	v_mul_f32_e32 v15, 0xbfb8aa3b, v15
	v_mul_f32_e32 v17, v17, v18
	v_lshlrev_b32_e32 v18, 16, v68
	v_exp_f32_e32 v15, v15
	v_mul_f32_e32 v12, v12, v18
	v_and_b32_e32 v18, 0xffff0000, v68
	v_mul_f32_e32 v8, 0xbfb8aa3b, v8
	v_mul_f32_e32 v13, v13, v18
	v_exp_f32_e32 v8, v8
	v_mul_f32_e32 v9, 0xbfb8aa3b, v9
	v_cvt_pk_bf16_f32 v23, v16, v17
	global_store_dwordx4 v[24:25], v[20:23], off offset:1280
	v_cvt_pk_bf16_f32 v12, v12, v13
	v_add_f32_e32 v13, 1.0, v14
	v_exp_f32_e32 v9, v9
	v_rcp_f32_e32 v13, v13
	v_add_f32_e32 v14, 1.0, v15
	v_rcp_f32_e32 v14, v14
	v_add_f32_e32 v8, 1.0, v8
	v_lshlrev_b32_e32 v15, 16, v69
	v_rcp_f32_e32 v8, v8
	v_add_f32_e32 v9, 1.0, v9
	v_mul_f32_e32 v10, 0xbfb8aa3b, v10
	v_mul_f32_e32 v13, v13, v15
	v_and_b32_e32 v15, 0xffff0000, v69
	v_rcp_f32_e32 v9, v9
	v_exp_f32_e32 v10, v10
	v_mul_f32_e32 v11, 0xbfb8aa3b, v11
	v_mul_f32_e32 v14, v14, v15
	v_exp_f32_e32 v11, v11
	v_mul_f32_e32 v4, 0xbfb8aa3b, v4
	v_cvt_pk_bf16_f32 v13, v13, v14
	v_lshlrev_b32_e32 v14, 16, v70
	v_exp_f32_e32 v4, v4
	v_mul_f32_e32 v5, 0xbfb8aa3b, v5
	v_mul_f32_e32 v8, v8, v14
	v_and_b32_e32 v14, 0xffff0000, v70
	v_exp_f32_e32 v5, v5
	v_mul_f32_e32 v9, v9, v14
	v_cvt_pk_bf16_f32 v14, v8, v9
	v_add_f32_e32 v8, 1.0, v10
	v_rcp_f32_e32 v8, v8
	v_add_f32_e32 v9, 1.0, v11
	v_rcp_f32_e32 v9, v9
	v_add_f32_e32 v4, 1.0, v4
	v_rcp_f32_e32 v4, v4
	v_add_f32_e32 v5, 1.0, v5
	v_lshlrev_b32_e32 v10, 16, v71
	v_rcp_f32_e32 v5, v5
	v_mul_f32_e32 v6, 0xbfb8aa3b, v6
	v_mul_f32_e32 v8, v8, v10
	v_and_b32_e32 v10, 0xffff0000, v71
	v_exp_f32_e32 v6, v6
	v_mul_f32_e32 v7, 0xbfb8aa3b, v7
	v_lshlrev_b64 v[16:17], 11, v[88:89]
	v_mul_f32_e32 v9, v9, v10
	v_lshlrev_b32_e32 v10, 16, v64
	v_exp_f32_e32 v7, v7
	v_cvt_pk_bf16_f32 v15, v8, v9
	v_lshl_add_u64 v[8:9], s[46:47], 0, v[16:17]
	v_mul_f32_e32 v4, v4, v10
	v_and_b32_e32 v10, 0xffff0000, v64
	v_mul_f32_e32 v0, 0xbfb8aa3b, v0
	v_lshl_add_u64 v[8:9], v[8:9], 0, v[168:169]
	v_mul_f32_e32 v5, v5, v10
	v_exp_f32_e32 v0, v0
	v_mul_f32_e32 v1, 0xbfb8aa3b, v1
	global_store_dwordx4 v[8:9], v[12:15], off offset:1024
	v_cvt_pk_bf16_f32 v4, v4, v5
	v_add_f32_e32 v5, 1.0, v6
	v_exp_f32_e32 v1, v1
	v_rcp_f32_e32 v5, v5
	v_add_f32_e32 v6, 1.0, v7
	v_rcp_f32_e32 v6, v6
	v_add_f32_e32 v0, 1.0, v0
	v_lshlrev_b32_e32 v7, 16, v65
	v_rcp_f32_e32 v0, v0
	v_add_f32_e32 v1, 1.0, v1
	v_mul_f32_e32 v2, 0xbfb8aa3b, v2
	v_mul_f32_e32 v5, v5, v7
	v_and_b32_e32 v7, 0xffff0000, v65
	v_rcp_f32_e32 v1, v1
	v_exp_f32_e32 v2, v2
	v_mul_f32_e32 v3, 0xbfb8aa3b, v3
	v_mul_f32_e32 v6, v6, v7
	v_exp_f32_e32 v3, v3
	v_cvt_pk_bf16_f32 v5, v5, v6
	v_lshlrev_b32_e32 v6, 16, v66
	v_mul_f32_e32 v0, v0, v6
	v_and_b32_e32 v6, 0xffff0000, v66
	v_mul_f32_e32 v1, v1, v6
	v_cvt_pk_bf16_f32 v6, v0, v1
	v_add_f32_e32 v0, 1.0, v2
	v_rcp_f32_e32 v0, v0
	v_add_f32_e32 v1, 1.0, v3
	v_rcp_f32_e32 v1, v1
	v_lshlrev_b32_e32 v2, 16, v67
	v_mul_f32_e32 v0, v0, v2
	v_and_b32_e32 v2, 0xffff0000, v67
	s_andn2_b64 vcc, exec, s[0:1]
	s_mov_b32 s12, s6
	s_mov_b32 s36, s4
	s_mov_b64 s[16:17], s[10:11]
	s_mov_b64 s[14:15], s[8:9]
	v_readlane_b32 s37, v255, 9
	v_readlane_b32 s38, v255, 10
	v_readlane_b32 s39, v255, 11
	v_readlane_b32 s40, v255, 12
	v_readlane_b32 s41, v255, 13
	v_readlane_b32 s42, v255, 14
	v_readlane_b32 s43, v255, 15
	v_readlane_b32 s48, v255, 20
	v_readlane_b32 s49, v255, 21
	v_readlane_b32 s50, v255, 22
	v_readlane_b32 s51, v255, 23
	v_mul_f32_e32 v1, v1, v2
	v_cvt_pk_bf16_f32 v7, v0, v1
	global_store_dwordx4 v[8:9], v[4:7], off offset:1280
	s_cbranch_vccnz .LBB0_1184
	s_waitcnt vmcnt(0)
	s_cmpk_gt_u32 s20, 0xff
	s_cbranch_scc1 .LBB0_1195
	s_barrier

; #define PG8_STAGE(bufoff, gbase, voff) do { _Pragma("unroll") for (int _i = 0; _i < 2; ++_i) \
;         __builtin_amdgcn_global_load_lds((const unsigned*)((const char*)(gbase) + (voff)[_i]), (PG8_LAS unsigned*)(lds + (bufoff) + ldsw + _i * 8192), 16, 0, 0); } while (0)
; #define PG8_LDA(dst, b, h) do { _Pragma("unroll") for (int m = 0; m < 4; ++m) _Pragma("unroll") for (int k = 0; k < 2; ++k) dst[m][k] = *(const PG8_LAS bf16x8*)(lds + PG8_SA(b, h) + aoff + m * 2048 + k * 1024); } while (0)
; #define PG8_LDB(dst, b, h) do { _Pragma("unroll") for (int n = 0; n < 2; ++n) _Pragma("unroll") for (int k = 0; k < 2; ++k) dst[n][k] = *(const PG8_LAS bf16x8*)(lds + PG8_SB(b, h) + boff + n * 2048 + k * 1024); } while (0)
; #define PG8_MMA(ai, bj, At, Bt) do { __builtin_amdgcn_s_setprio(1); _Pragma("unroll") for (int m = 0; m < 4; ++m) _Pragma("unroll") for (int n = 0; n < 2; ++n) _Pragma("unroll") for (int k = 0; k < 2; ++k) \
;         acc[ai][bj][m][n] = __builtin_amdgcn_mfma_f32_16x16x32_bf16(Bt[n][k], At[m][k], acc[ai][bj][m][n], 0, 0, 0); __builtin_amdgcn_s_setprio(0); } while (0)
; #define PG8_WAIT_L(n) asm volatile("s_waitcnt lgkmcnt(" #n ")" ::: "memory")
; #define PG8_BAR __builtin_amdgcn_s_barrier()
; #define PG8_SCHED __builtin_amdgcn_sched_barrier(0)
; template <class Epi, class Sched>
; __device__ __forceinline__ void gemm_phase(PG8_LAS unsigned char* lds, const Gemm g, const Sched& S, const Epi& E) {
;     ...
;             PG8_LDB(B0, 0, 0); PG8_SCHED; PG8_LDA(At, 0, 0); PG8_STAGE(PG8_SA(1, 1), a1 + hstep, voffA);
;             PG8_WAIT_L(8); PG8_BAR; PG8_WAIT_L(0); PG8_MMA(0, 0, At, B0); PG8_BAR; PG8_SCHED;
;             PG8_LDB(B1, 0, 1); PG8_STAGE(PG8_SB(0, 0), b2, voffB);
;             PG8_BAR; PG8_WAIT_L(0); PG8_MMA(0, 1, At, B1); PG8_BAR;
;             PG8_LDA(At, 0, 1); PG8_STAGE(PG8_SA(0, 0), a2, voffA);
;             PG8_BAR; PG8_WAIT_L(0); PG8_MMA(1, 0, At, B0); PG8_BAR; PG8_SCHED;
.LBB0_1313:
	ds_read_b128 v[128:131], v163
	ds_read_b128 v[132:135], v163 offset:1024
	ds_read_b128 v[136:139], v163 offset:2048
	ds_read_b128 v[140:143], v163 offset:3072
	s_add_i32 vcc_lo, s27, 2
	s_add_u32 s30, s40, 0xfffc0080
	s_addc_u32 s42, s41, -1
	s_cmp_eq_u32 s17, s27
	s_cselect_b32 s45, s37, s42
	s_cselect_b32 s44, s36, s30
	s_cselect_b32 s43, s39, s21
	s_cselect_b32 s42, s38, s19
	v_lshl_add_u64 v[196:197], s[40:41], 0, v[174:175]
	s_add_i32 m0, s31, 0xc000
	ds_read_b128 v[144:147], v198
	ds_read_b128 v[148:151], v198 offset:1024
	ds_read_b128 v[180:183], v198 offset:2048
	ds_read_b128 v[184:187], v198 offset:3072
	ds_read_b128 v[188:191], v198 offset:4096
	ds_read_b128 v[192:195], v198 offset:5120
	ds_read_b128 v[202:205], v198 offset:6144
	ds_read_b128 v[206:209], v198 offset:7168
	global_load_lds_dwordx4 v[196:197], off
	v_lshl_add_u64 v[196:197], s[40:41], 0, v[176:177]
	s_add_i32 m0, s31, 0xe000
	s_nop 0
	global_load_lds_dwordx4 v[196:197], off
	s_waitcnt lgkmcnt(8)
	s_barrier
	s_waitcnt lgkmcnt(0)
	s_setprio 1
	v_mfma_f32_16x16x32_bf16 v[124:127], v[128:131], v[144:147], v[124:127]
	v_mfma_f32_16x16x32_bf16 v[120:123], v[136:139], v[144:147], v[120:123]
	v_mfma_f32_16x16x32_bf16 v[108:111], v[128:131], v[180:183], v[108:111]
	v_mfma_f32_16x16x32_bf16 v[104:107], v[136:139], v[180:183], v[104:107]
	v_mfma_f32_16x16x32_bf16 v[92:95], v[128:131], v[188:191], v[92:95]
	v_mfma_f32_16x16x32_bf16 v[88:91], v[136:139], v[188:191], v[88:91]
	v_mfma_f32_16x16x32_bf16 v[76:79], v[128:131], v[202:205], v[76:79]
	v_mfma_f32_16x16x32_bf16 v[72:75], v[136:139], v[202:205], v[72:75]
	v_mfma_f32_16x16x32_bf16 v[124:127], v[132:135], v[148:151], v[124:127]
	v_mfma_f32_16x16x32_bf16 v[120:123], v[140:143], v[148:151], v[120:123]
	v_mfma_f32_16x16x32_bf16 v[108:111], v[132:135], v[184:187], v[108:111]
	v_mfma_f32_16x16x32_bf16 v[104:107], v[140:143], v[184:187], v[104:107]
	v_mfma_f32_16x16x32_bf16 v[92:95], v[132:135], v[192:195], v[92:95]
	v_mfma_f32_16x16x32_bf16 v[88:91], v[140:143], v[192:195], v[88:91]
	v_mfma_f32_16x16x32_bf16 v[76:79], v[132:135], v[206:209], v[76:79]
	v_mfma_f32_16x16x32_bf16 v[72:75], v[140:143], v[206:209], v[72:75]
	s_setprio 0
	s_barrier
	s_add_i32 s27, s88, s29
	v_lshl_add_u64 v[196:197], s[42:43], 0, v[166:167]
	s_mov_b32 m0, s27
	ds_read_b128 v[210:213], v199
	ds_read_b128 v[214:217], v199 offset:1024
	ds_read_b128 v[218:221], v199 offset:2048
	ds_read_b128 v[222:225], v199 offset:3072
	global_load_lds_dwordx4 v[196:197], off
	v_lshl_add_u64 v[226:227], s[42:43], 0, v[170:171]
	s_add_i32 m0, s27, 0x2000
	s_nop 0
	global_load_lds_dwordx4 v[226:227], off
	s_barrier
	s_waitcnt lgkmcnt(0)
	s_setprio 1
	v_mfma_f32_16x16x32_bf16 v[116:119], v[210:213], v[144:147], v[116:119]
	v_mfma_f32_16x16x32_bf16 v[112:115], v[218:221], v[144:147], v[112:115]
	v_mfma_f32_16x16x32_bf16 v[100:103], v[210:213], v[180:183], v[100:103]
	v_mfma_f32_16x16x32_bf16 v[96:99], v[218:221], v[180:183], v[96:99]
	v_mfma_f32_16x16x32_bf16 v[84:87], v[210:213], v[188:191], v[84:87]
	v_mfma_f32_16x16x32_bf16 v[80:83], v[218:221], v[188:191], v[80:83]
	v_mfma_f32_16x16x32_bf16 v[68:71], v[210:213], v[202:205], v[68:71]
	v_mfma_f32_16x16x32_bf16 v[64:67], v[218:221], v[202:205], v[64:67]
	v_mfma_f32_16x16x32_bf16 v[116:119], v[214:217], v[148:151], v[116:119]
	v_mfma_f32_16x16x32_bf16 v[112:115], v[222:225], v[148:151], v[112:115]
	v_mfma_f32_16x16x32_bf16 v[100:103], v[214:217], v[184:187], v[100:103]
	v_mfma_f32_16x16x32_bf16 v[96:99], v[222:225], v[184:187], v[96:99]
	v_mfma_f32_16x16x32_bf16 v[84:87], v[214:217], v[192:195], v[84:87]
	v_mfma_f32_16x16x32_bf16 v[80:83], v[222:225], v[192:195], v[80:83]
	v_mfma_f32_16x16x32_bf16 v[68:71], v[214:217], v[206:209], v[68:71]
	v_mfma_f32_16x16x32_bf16 v[64:67], v[222:225], v[206:209], v[64:67]
	s_setprio 0
	s_mov_b32 m0, s31
	v_lshl_add_u64 v[228:229], s[44:45], 0, v[164:165]
	s_barrier
	ds_read_b128 v[144:147], v198 offset:16384
	ds_read_b128 v[148:151], v198 offset:17408
	ds_read_b128 v[180:183], v198 offset:18432
	ds_read_b128 v[184:187], v198 offset:19456
	ds_read_b128 v[188:191], v198 offset:20480
	ds_read_b128 v[192:195], v198 offset:21504
	ds_read_b128 v[202:205], v198 offset:22528
	ds_read_b128 v[206:209], v198 offset:23552
	global_load_lds_dwordx4 v[228:229], off
	v_lshl_add_u64 v[230:231], s[44:45], 0, v[168:169]
	s_mov_b32 m0, s33
	s_nop 0
	global_load_lds_dwordx4 v[230:231], off
	s_barrier
	s_waitcnt lgkmcnt(0)
	s_setprio 1
	v_mfma_f32_16x16x32_bf16 v[60:63], v[128:131], v[144:147], v[60:63]
	v_mfma_f32_16x16x32_bf16 v[56:59], v[136:139], v[144:147], v[56:59]
	v_mfma_f32_16x16x32_bf16 v[44:47], v[128:131], v[180:183], v[44:47]
	v_mfma_f32_16x16x32_bf16 v[40:43], v[136:139], v[180:183], v[40:43]
	v_mfma_f32_16x16x32_bf16 v[28:31], v[128:131], v[188:191], v[28:31]
	v_mfma_f32_16x16x32_bf16 v[24:27], v[136:139], v[188:191], v[24:27]
	v_mfma_f32_16x16x32_bf16 v[12:15], v[128:131], v[202:205], v[12:15]
	v_mfma_f32_16x16x32_bf16 v[8:11], v[136:139], v[202:205], v[8:11]
	v_mfma_f32_16x16x32_bf16 v[60:63], v[132:135], v[148:151], v[60:63]
	v_mfma_f32_16x16x32_bf16 v[56:59], v[140:143], v[148:151], v[56:59]
	v_mfma_f32_16x16x32_bf16 v[44:47], v[132:135], v[184:187], v[44:47]
	v_mfma_f32_16x16x32_bf16 v[40:43], v[140:143], v[184:187], v[40:43]
	v_mfma_f32_16x16x32_bf16 v[28:31], v[132:135], v[192:195], v[28:31]
	v_mfma_f32_16x16x32_bf16 v[24:27], v[140:143], v[192:195], v[24:27]
	v_mfma_f32_16x16x32_bf16 v[12:15], v[132:135], v[206:209], v[12:15]
	v_mfma_f32_16x16x32_bf16 v[8:11], v[140:143], v[206:209], v[8:11]
	s_setprio 0
	s_barrier
; #define PG8_STAGE(bufoff, gbase, voff) do { _Pragma("unroll") for (int _i = 0; _i < 2; ++_i) \
;         __builtin_amdgcn_global_load_lds((const unsigned*)((const char*)(gbase) + (voff)[_i]), (PG8_LAS unsigned*)(lds + (bufoff) + ldsw + _i * 8192), 16, 0, 0); } while (0)
; #define PG8_LDA(dst, b, h) do { _Pragma("unroll") for (int m = 0; m < 4; ++m) _Pragma("unroll") for (int k = 0; k < 2; ++k) dst[m][k] = *(const PG8_LAS bf16x8*)(lds + PG8_SA(b, h) + aoff + m * 2048 + k * 1024); } while (0)
; #define PG8_LDB(dst, b, h) do { _Pragma("unroll") for (int n = 0; n < 2; ++n) _Pragma("unroll") for (int k = 0; k < 2; ++k) dst[n][k] = *(const PG8_LAS bf16x8*)(lds + PG8_SB(b, h) + boff + n * 2048 + k * 1024); } while (0)
; #define PG8_MMA(ai, bj, At, Bt) do { __builtin_amdgcn_s_setprio(1); _Pragma("unroll") for (int m = 0; m < 4; ++m) _Pragma("unroll") for (int n = 0; n < 2; ++n) _Pragma("unroll") for (int k = 0; k < 2; ++k) \
;         acc[ai][bj][m][n] = __builtin_amdgcn_mfma_f32_16x16x32_bf16(Bt[n][k], At[m][k], acc[ai][bj][m][n], 0, 0, 0); __builtin_amdgcn_s_setprio(0); } while (0)
; #define PG8_WAIT_V(n) asm volatile("s_waitcnt vmcnt(" #n ")" ::: "memory")
; #define PG8_WAIT_L(n) asm volatile("s_waitcnt lgkmcnt(" #n ")" ::: "memory")
; #define PG8_BAR __builtin_amdgcn_s_barrier()
; #define PG8_SCHED __builtin_amdgcn_sched_barrier(0)
; template <class Epi, class Sched>
; __device__ __forceinline__ void gemm_phase(PG8_LAS unsigned char* lds, const Gemm g, const Sched& S, const Epi& E) {
;     ...
;             PG8_STAGE(PG8_SB(0, 1), b2 + hstep, voffB);
;             PG8_WAIT_V(6); PG8_BAR; PG8_MMA(1, 1, At, B1); PG8_BAR;
;             PG8_LDB(B0, 1, 0); PG8_SCHED; PG8_LDA(At, 1, 0); PG8_STAGE(PG8_SA(0, 1), a2 + hstep, voffA);
;             PG8_WAIT_L(8); PG8_BAR; PG8_WAIT_L(0); PG8_MMA(0, 0, At, B0); PG8_BAR; PG8_SCHED;
;             PG8_LDB(B1, 1, 1); PG8_STAGE(PG8_SB(1, 0), b3, voffB);
	s_add_u32 s96, s42, 0x40000
	s_addc_u32 s97, s43, 0
	s_add_i32 s27, s89, s29
	v_lshl_add_u64 v[128:129], s[96:97], 0, v[166:167]
	s_mov_b32 m0, s27
	s_nop 0
	global_load_lds_dwordx4 v[128:129], off
	v_lshl_add_u64 v[128:129], s[96:97], 0, v[170:171]
	s_add_i32 m0, s27, 0x2000
	s_nop 0
	global_load_lds_dwordx4 v[128:129], off
	s_waitcnt vmcnt(6)
	s_barrier
	s_setprio 1
	v_mfma_f32_16x16x32_bf16 v[52:55], v[210:213], v[144:147], v[52:55]
	v_mfma_f32_16x16x32_bf16 v[48:51], v[218:221], v[144:147], v[48:51]
	v_mfma_f32_16x16x32_bf16 v[36:39], v[210:213], v[180:183], v[36:39]
	v_mfma_f32_16x16x32_bf16 v[32:35], v[218:221], v[180:183], v[32:35]
	v_mfma_f32_16x16x32_bf16 v[20:23], v[210:213], v[188:191], v[20:23]
	v_mfma_f32_16x16x32_bf16 v[16:19], v[218:221], v[188:191], v[16:19]
	v_mfma_f32_16x16x32_bf16 v[4:7], v[210:213], v[202:205], v[4:7]
	v_mfma_f32_16x16x32_bf16 v[0:3], v[218:221], v[202:205], v[0:3]
	v_mfma_f32_16x16x32_bf16 v[52:55], v[214:217], v[148:151], v[52:55]
	v_mfma_f32_16x16x32_bf16 v[48:51], v[222:225], v[148:151], v[48:51]
	v_mfma_f32_16x16x32_bf16 v[36:39], v[214:217], v[184:187], v[36:39]
	v_mfma_f32_16x16x32_bf16 v[32:35], v[222:225], v[184:187], v[32:35]
	v_mfma_f32_16x16x32_bf16 v[20:23], v[214:217], v[192:195], v[20:23]
	v_mfma_f32_16x16x32_bf16 v[16:19], v[222:225], v[192:195], v[16:19]
	v_mfma_f32_16x16x32_bf16 v[4:7], v[214:217], v[206:209], v[4:7]
	v_mfma_f32_16x16x32_bf16 v[0:3], v[222:225], v[206:209], v[0:3]
	s_setprio 0
	s_add_i32 s27, 0, 0x18000
	v_add_u32_e32 v140, s27, v159
	s_barrier
	ds_read_b128 v[128:131], v140
	ds_read_b128 v[132:135], v140 offset:1024
	ds_read_b128 v[136:139], v140 offset:2048
	ds_read_b128 v[140:143], v140 offset:3072
	s_add_u32 s44, s44, 0x40000
	s_addc_u32 s45, s45, 0
	s_mov_b32 m0, s34
	v_lshl_add_u64 v[210:211], s[44:45], 0, v[164:165]
	ds_read_b128 v[144:147], v198 offset:32768
	ds_read_b128 v[148:151], v198 offset:33792
	ds_read_b128 v[180:183], v198 offset:34816
	ds_read_b128 v[184:187], v198 offset:35840
	ds_read_b128 v[188:191], v198 offset:36864
	ds_read_b128 v[192:195], v198 offset:37888
	ds_read_b128 v[202:205], v198 offset:38912
	ds_read_b128 v[206:209], v198 offset:39936
	global_load_lds_dwordx4 v[210:211], off
	v_lshl_add_u64 v[210:211], s[44:45], 0, v[168:169]
	s_mov_b32 m0, s35
	s_nop 0
	global_load_lds_dwordx4 v[210:211], off
	s_waitcnt lgkmcnt(8)
	s_barrier
	s_waitcnt lgkmcnt(0)
	s_setprio 1
	v_mfma_f32_16x16x32_bf16 v[124:127], v[128:131], v[144:147], v[124:127]
	v_mfma_f32_16x16x32_bf16 v[120:123], v[136:139], v[144:147], v[120:123]
	v_mfma_f32_16x16x32_bf16 v[108:111], v[128:131], v[180:183], v[108:111]
	v_mfma_f32_16x16x32_bf16 v[104:107], v[136:139], v[180:183], v[104:107]
	v_mfma_f32_16x16x32_bf16 v[92:95], v[128:131], v[188:191], v[92:95]
	v_mfma_f32_16x16x32_bf16 v[88:91], v[136:139], v[188:191], v[88:91]
	v_mfma_f32_16x16x32_bf16 v[76:79], v[128:131], v[202:205], v[76:79]
	v_mfma_f32_16x16x32_bf16 v[72:75], v[136:139], v[202:205], v[72:75]
	v_mfma_f32_16x16x32_bf16 v[124:127], v[132:135], v[148:151], v[124:127]
	v_mfma_f32_16x16x32_bf16 v[120:123], v[140:143], v[148:151], v[120:123]
	v_mfma_f32_16x16x32_bf16 v[108:111], v[132:135], v[184:187], v[108:111]
	v_mfma_f32_16x16x32_bf16 v[104:107], v[140:143], v[184:187], v[104:107]
	v_mfma_f32_16x16x32_bf16 v[92:95], v[132:135], v[192:195], v[92:95]
	v_mfma_f32_16x16x32_bf16 v[88:91], v[140:143], v[192:195], v[88:91]
	v_mfma_f32_16x16x32_bf16 v[76:79], v[132:135], v[206:209], v[76:79]
	v_mfma_f32_16x16x32_bf16 v[72:75], v[140:143], v[206:209], v[72:75]
	s_setprio 0
	s_barrier
	s_add_i32 s30, 0, 0x1c000
	s_add_i32 s27, s27, s29
	v_add_u32_e32 v201, s30, v159
	v_lshl_add_u64 v[196:197], v[196:197], 0, s[10:11]
	s_mov_b32 m0, s27
	ds_read_b128 v[210:213], v201
	ds_read_b128 v[214:217], v201 offset:1024
	ds_read_b128 v[218:221], v201 offset:2048
	ds_read_b128 v[222:225], v201 offset:3072
	global_load_lds_dwordx4 v[196:197], off
	v_lshl_add_u64 v[196:197], v[226:227], 0, s[10:11]
	s_add_i32 m0, s27, 0x2000
	s_nop 0
	global_load_lds_dwordx4 v[196:197], off
	s_barrier
; #define PG8_STAGE(bufoff, gbase, voff) do { _Pragma("unroll") for (int _i = 0; _i < 2; ++_i) \
;         __builtin_amdgcn_global_load_lds((const unsigned*)((const char*)(gbase) + (voff)[_i]), (PG8_LAS unsigned*)(lds + (bufoff) + ldsw + _i * 8192), 16, 0, 0); } while (0)
; #define PG8_LDA(dst, b, h) do { _Pragma("unroll") for (int m = 0; m < 4; ++m) _Pragma("unroll") for (int k = 0; k < 2; ++k) dst[m][k] = *(const PG8_LAS bf16x8*)(lds + PG8_SA(b, h) + aoff + m * 2048 + k * 1024); } while (0)
; #define PG8_MMA(ai, bj, At, Bt) do { __builtin_amdgcn_s_setprio(1); _Pragma("unroll") for (int m = 0; m < 4; ++m) _Pragma("unroll") for (int n = 0; n < 2; ++n) _Pragma("unroll") for (int k = 0; k < 2; ++k) \
;         acc[ai][bj][m][n] = __builtin_amdgcn_mfma_f32_16x16x32_bf16(Bt[n][k], At[m][k], acc[ai][bj][m][n], 0, 0, 0); __builtin_amdgcn_s_setprio(0); } while (0)
; #define PG8_WAIT_V(n) asm volatile("s_waitcnt vmcnt(" #n ")" ::: "memory")
; #define PG8_WAIT_L(n) asm volatile("s_waitcnt lgkmcnt(" #n ")" ::: "memory")
; #define PG8_BAR __builtin_amdgcn_s_barrier()
; #define PG8_SCHED __builtin_amdgcn_sched_barrier(0)
; template <class Epi, class Sched>
; __device__ __forceinline__ void gemm_phase(PG8_LAS unsigned char* lds, const Gemm g, const Sched& S, const Epi& E) {
;     ...
;             PG8_BAR; PG8_WAIT_L(0); PG8_MMA(0, 1, At, B1); PG8_BAR;
;             PG8_LDA(At, 1, 1); PG8_STAGE(PG8_SA(1, 0), a3, voffA);
;             PG8_BAR; PG8_WAIT_L(0); PG8_MMA(1, 0, At, B0); PG8_BAR; PG8_SCHED;
;             PG8_STAGE(PG8_SB(1, 1), b3 + hstep, voffB);
;             PG8_WAIT_V(6); PG8_BAR; PG8_MMA(1, 1, At, B1); PG8_BAR;
;         }
;         if constexpr (!Epi::AFTER_DRAIN) {
;             if (cur.part < 0) E(acc, cur, wr, wc, fr, fq, pre);
;             else { f32x4* pp = (f32x4*)g.part + (size_t)cur.part * 32 * 512 + tid;
	s_waitcnt lgkmcnt(0)
	s_setprio 1
	v_mfma_f32_16x16x32_bf16 v[116:119], v[210:213], v[144:147], v[116:119]
	v_mfma_f32_16x16x32_bf16 v[112:115], v[218:221], v[144:147], v[112:115]
	v_mfma_f32_16x16x32_bf16 v[100:103], v[210:213], v[180:183], v[100:103]
	v_mfma_f32_16x16x32_bf16 v[96:99], v[218:221], v[180:183], v[96:99]
	v_mfma_f32_16x16x32_bf16 v[84:87], v[210:213], v[188:191], v[84:87]
	v_mfma_f32_16x16x32_bf16 v[80:83], v[218:221], v[188:191], v[80:83]
	v_mfma_f32_16x16x32_bf16 v[68:71], v[210:213], v[202:205], v[68:71]
	v_mfma_f32_16x16x32_bf16 v[64:67], v[218:221], v[202:205], v[64:67]
	v_mfma_f32_16x16x32_bf16 v[116:119], v[214:217], v[148:151], v[116:119]
	v_mfma_f32_16x16x32_bf16 v[112:115], v[222:225], v[148:151], v[112:115]
	v_mfma_f32_16x16x32_bf16 v[100:103], v[214:217], v[184:187], v[100:103]
	v_mfma_f32_16x16x32_bf16 v[96:99], v[222:225], v[184:187], v[96:99]
	v_mfma_f32_16x16x32_bf16 v[84:87], v[214:217], v[192:195], v[84:87]
	v_mfma_f32_16x16x32_bf16 v[80:83], v[222:225], v[192:195], v[80:83]
	v_mfma_f32_16x16x32_bf16 v[68:71], v[214:217], v[206:209], v[68:71]
	v_mfma_f32_16x16x32_bf16 v[64:67], v[222:225], v[206:209], v[64:67]
	s_setprio 0
	s_mov_b32 m0, s47
	v_lshl_add_u64 v[196:197], v[228:229], 0, s[10:11]
	s_barrier
	ds_read_b128 v[144:147], v198 offset:49152
	ds_read_b128 v[148:151], v198 offset:50176
	ds_read_b128 v[180:183], v198 offset:51200
	ds_read_b128 v[184:187], v198 offset:52224
	ds_read_b128 v[188:191], v198 offset:53248
	ds_read_b128 v[192:195], v198 offset:54272
	ds_read_b128 v[202:205], v198 offset:55296
	ds_read_b128 v[206:209], v198 offset:56320
	global_load_lds_dwordx4 v[196:197], off
	v_lshl_add_u64 v[196:197], v[230:231], 0, s[10:11]
	s_mov_b32 m0, s48
	s_nop 0
	global_load_lds_dwordx4 v[196:197], off
	s_barrier
	s_waitcnt lgkmcnt(0)
	s_setprio 1
	v_mfma_f32_16x16x32_bf16 v[60:63], v[128:131], v[144:147], v[60:63]
	v_mfma_f32_16x16x32_bf16 v[56:59], v[136:139], v[144:147], v[56:59]
	v_mfma_f32_16x16x32_bf16 v[44:47], v[128:131], v[180:183], v[44:47]
	v_mfma_f32_16x16x32_bf16 v[40:43], v[136:139], v[180:183], v[40:43]
	v_mfma_f32_16x16x32_bf16 v[28:31], v[128:131], v[188:191], v[28:31]
	v_mfma_f32_16x16x32_bf16 v[24:27], v[136:139], v[188:191], v[24:27]
	v_mfma_f32_16x16x32_bf16 v[12:15], v[128:131], v[202:205], v[12:15]
	v_mfma_f32_16x16x32_bf16 v[8:11], v[136:139], v[202:205], v[8:11]
	v_mfma_f32_16x16x32_bf16 v[60:63], v[132:135], v[148:151], v[60:63]
	v_mfma_f32_16x16x32_bf16 v[56:59], v[140:143], v[148:151], v[56:59]
	v_mfma_f32_16x16x32_bf16 v[44:47], v[132:135], v[184:187], v[44:47]
	v_mfma_f32_16x16x32_bf16 v[40:43], v[140:143], v[184:187], v[40:43]
	v_mfma_f32_16x16x32_bf16 v[28:31], v[132:135], v[192:195], v[28:31]
	v_mfma_f32_16x16x32_bf16 v[24:27], v[140:143], v[192:195], v[24:27]
	v_mfma_f32_16x16x32_bf16 v[12:15], v[132:135], v[206:209], v[12:15]
	v_mfma_f32_16x16x32_bf16 v[8:11], v[140:143], v[206:209], v[8:11]
	s_setprio 0
	s_barrier
	s_add_u32 s42, s42, 0x40080
	s_addc_u32 s43, s43, 0
	s_add_i32 s27, s30, s29
	v_lshl_add_u64 v[128:129], s[42:43], 0, v[166:167]
	s_mov_b32 m0, s27
	s_nop 0
	global_load_lds_dwordx4 v[128:129], off
	v_lshl_add_u64 v[128:129], s[42:43], 0, v[170:171]
	s_add_i32 m0, s27, 0x2000
	s_nop 0
	global_load_lds_dwordx4 v[128:129], off
	s_waitcnt vmcnt(6)
	s_barrier
	s_setprio 1
	v_mfma_f32_16x16x32_bf16 v[52:55], v[210:213], v[144:147], v[52:55]
	v_mfma_f32_16x16x32_bf16 v[48:51], v[218:221], v[144:147], v[48:51]
	v_mfma_f32_16x16x32_bf16 v[36:39], v[210:213], v[180:183], v[36:39]
	v_mfma_f32_16x16x32_bf16 v[32:35], v[218:221], v[180:183], v[32:35]
	v_mfma_f32_16x16x32_bf16 v[20:23], v[210:213], v[188:191], v[20:23]
	v_mfma_f32_16x16x32_bf16 v[16:19], v[218:221], v[188:191], v[16:19]
	v_mfma_f32_16x16x32_bf16 v[4:7], v[210:213], v[202:205], v[4:7]
	v_mfma_f32_16x16x32_bf16 v[0:3], v[218:221], v[202:205], v[0:3]
	v_mfma_f32_16x16x32_bf16 v[52:55], v[214:217], v[148:151], v[52:55]
	v_mfma_f32_16x16x32_bf16 v[48:51], v[222:225], v[148:151], v[48:51]
	v_mfma_f32_16x16x32_bf16 v[36:39], v[214:217], v[184:187], v[36:39]
	v_mfma_f32_16x16x32_bf16 v[32:35], v[222:225], v[184:187], v[32:35]
	v_mfma_f32_16x16x32_bf16 v[20:23], v[214:217], v[192:195], v[20:23]
	v_mfma_f32_16x16x32_bf16 v[16:19], v[222:225], v[192:195], v[16:19]
	v_mfma_f32_16x16x32_bf16 v[4:7], v[214:217], v[206:209], v[4:7]
	v_mfma_f32_16x16x32_bf16 v[0:3], v[222:225], v[206:209], v[0:3]
	s_setprio 0
	s_add_u32 s40, s40, 0x100
	s_addc_u32 s41, s41, 0
	s_add_u32 s19, s19, 0x100
	s_addc_u32 s21, s21, 0
	s_cmp_ge_i32 vcc_lo, s15
	s_mov_b32 s27, vcc_lo
	s_barrier
	s_cbranch_scc0 .LBB0_1313
	s_cmp_gt_i32 s8, -1
	s_mov_b64 s[40:41], -1
	s_cbranch_scc0 .LBB0_1316

; #define PG8_STAGE(bufoff, gbase, voff) do { _Pragma("unroll") for (int _i = 0; _i < 2; ++_i) \
;         __builtin_amdgcn_global_load_lds((const unsigned*)((const char*)(gbase) + (voff)[_i]), (PG8_LAS unsigned*)(lds + (bufoff) + ldsw + _i * 8192), 16, 0, 0); } while (0)
; #define PG8_LDA(dst, b, h) do { _Pragma("unroll") for (int m = 0; m < 4; ++m) _Pragma("unroll") for (int k = 0; k < 2; ++k) dst[m][k] = *(const PG8_LAS bf16x8*)(lds + PG8_SA(b, h) + aoff + m * 2048 + k * 1024); } while (0)
; #define PG8_LDB(dst, b, h) do { _Pragma("unroll") for (int n = 0; n < 2; ++n) _Pragma("unroll") for (int k = 0; k < 2; ++k) dst[n][k] = *(const PG8_LAS bf16x8*)(lds + PG8_SB(b, h) + boff + n * 2048 + k * 1024); } while (0)
; #define PG8_MMA(ai, bj, At, Bt) do { __builtin_amdgcn_s_setprio(1); _Pragma("unroll") for (int m = 0; m < 4; ++m) _Pragma("unroll") for (int n = 0; n < 2; ++n) _Pragma("unroll") for (int k = 0; k < 2; ++k) \
;         acc[ai][bj][m][n] = __builtin_amdgcn_mfma_f32_16x16x32_bf16(Bt[n][k], At[m][k], acc[ai][bj][m][n], 0, 0, 0); __builtin_amdgcn_s_setprio(0); } while (0)
; #define PG8_WAIT_L(n) asm volatile("s_waitcnt lgkmcnt(" #n ")" ::: "memory")
; #define PG8_BAR __builtin_amdgcn_s_barrier()
; #define PG8_SCHED __builtin_amdgcn_sched_barrier(0)
; template <class Epi, class Sched>
; __device__ __forceinline__ void gemm_phase(PG8_LAS unsigned char* lds, const Gemm g, const Sched& S, const Epi& E) {
;     ...
;             PG8_LDB(B0, 0, 0); PG8_SCHED; PG8_LDA(At, 0, 0); PG8_STAGE(PG8_SA(1, 1), a1 + hstep, voffA);
;             PG8_WAIT_L(8); PG8_BAR; PG8_WAIT_L(0); PG8_MMA(0, 0, At, B0); PG8_BAR; PG8_SCHED;
;             PG8_LDB(B1, 0, 1); PG8_STAGE(PG8_SB(0, 0), b2, voffB);
;             PG8_BAR; PG8_WAIT_L(0); PG8_MMA(0, 1, At, B1); PG8_BAR;
;             PG8_LDA(At, 0, 1); PG8_STAGE(PG8_SA(0, 0), a2, voffA);
;             PG8_BAR; PG8_WAIT_L(0); PG8_MMA(1, 0, At, B0); PG8_BAR; PG8_SCHED;
.LBB0_1509:
	v_add_u32_e32 v142, s33, v159
	ds_read_b128 v[130:133], v142
	ds_read_b128 v[134:137], v142 offset:1024
	ds_read_b128 v[138:141], v142 offset:2048
	ds_read_b128 v[142:145], v142 offset:3072
	s_add_u32 s30, s4, 0xfffc0080
	s_addc_u32 s40, s5, -1
	s_and_b64 s[38:39], s[38:39], exec
	s_cselect_b32 s41, s23, s40
	s_cselect_b32 s40, s43, s30
	s_cselect_b32 s39, s21, s46
	s_cselect_b32 s38, s44, s45
	v_lshl_add_u64 v[150:151], s[4:5], 0, v[174:175]
	s_add_i32 m0, s16, 0xc000
	ds_read_b128 v[146:149], v163
	ds_read_b128 v[192:195], v163 offset:1024
	ds_read_b128 v[196:199], v163 offset:2048
	ds_read_b128 v[200:203], v163 offset:3072
	ds_read_b128 v[206:209], v163 offset:4096
	ds_read_b128 v[210:213], v163 offset:5120
	ds_read_b128 v[214:217], v163 offset:6144
	ds_read_b128 v[218:221], v163 offset:7168
	global_load_lds_dwordx4 v[150:151], off
	v_lshl_add_u64 v[150:151], s[4:5], 0, v[176:177]
	s_add_i32 m0, s16, 0xe000
	s_nop 0
	global_load_lds_dwordx4 v[150:151], off
	s_waitcnt lgkmcnt(8)
	s_barrier
	s_waitcnt lgkmcnt(0)
	s_setprio 1
	v_mfma_f32_16x16x32_bf16 v[124:127], v[130:133], v[146:149], v[124:127]
	v_mfma_f32_16x16x32_bf16 v[120:123], v[138:141], v[146:149], v[120:123]
	v_mfma_f32_16x16x32_bf16 v[108:111], v[130:133], v[196:199], v[108:111]
	v_mfma_f32_16x16x32_bf16 v[104:107], v[138:141], v[196:199], v[104:107]
	v_mfma_f32_16x16x32_bf16 v[92:95], v[130:133], v[206:209], v[92:95]
	v_mfma_f32_16x16x32_bf16 v[88:91], v[138:141], v[206:209], v[88:91]
	v_mfma_f32_16x16x32_bf16 v[76:79], v[130:133], v[214:217], v[76:79]
	v_mfma_f32_16x16x32_bf16 v[72:75], v[138:141], v[214:217], v[72:75]
	v_mfma_f32_16x16x32_bf16 v[124:127], v[134:137], v[192:195], v[124:127]
	v_mfma_f32_16x16x32_bf16 v[120:123], v[142:145], v[192:195], v[120:123]
	v_mfma_f32_16x16x32_bf16 v[108:111], v[134:137], v[200:203], v[108:111]
	v_mfma_f32_16x16x32_bf16 v[104:107], v[142:145], v[200:203], v[104:107]
	v_mfma_f32_16x16x32_bf16 v[92:95], v[134:137], v[210:213], v[92:95]
	v_mfma_f32_16x16x32_bf16 v[88:91], v[142:145], v[210:213], v[88:91]
	v_mfma_f32_16x16x32_bf16 v[76:79], v[134:137], v[218:221], v[76:79]
	v_mfma_f32_16x16x32_bf16 v[72:75], v[142:145], v[218:221], v[72:75]
	s_setprio 0
	s_barrier
	v_add_u32_e32 v150, s34, v159
	s_add_i32 s30, s33, s3
	ds_read_b128 v[222:225], v150
	ds_read_b128 v[226:229], v150 offset:1024
	ds_read_b128 v[230:233], v150 offset:2048
	ds_read_b128 v[234:237], v150 offset:3072
	v_lshl_add_u64 v[150:151], s[38:39], 0, v[168:169]
	s_mov_b32 m0, s30
	v_lshl_add_u64 v[238:239], s[38:39], 0, v[164:165]
	global_load_lds_dwordx4 v[150:151], off
	s_add_i32 m0, s30, 0x2000
	s_nop 0
	global_load_lds_dwordx4 v[238:239], off
	s_barrier
	s_waitcnt lgkmcnt(0)
	s_setprio 1
	v_mfma_f32_16x16x32_bf16 v[116:119], v[222:225], v[146:149], v[116:119]
	v_mfma_f32_16x16x32_bf16 v[112:115], v[230:233], v[146:149], v[112:115]
	v_mfma_f32_16x16x32_bf16 v[100:103], v[222:225], v[196:199], v[100:103]
	v_mfma_f32_16x16x32_bf16 v[96:99], v[230:233], v[196:199], v[96:99]
	v_mfma_f32_16x16x32_bf16 v[84:87], v[222:225], v[206:209], v[84:87]
	v_mfma_f32_16x16x32_bf16 v[80:83], v[230:233], v[206:209], v[80:83]
	v_mfma_f32_16x16x32_bf16 v[68:71], v[222:225], v[214:217], v[68:71]
	v_mfma_f32_16x16x32_bf16 v[64:67], v[230:233], v[214:217], v[64:67]
	v_mfma_f32_16x16x32_bf16 v[116:119], v[226:229], v[192:195], v[116:119]
	v_mfma_f32_16x16x32_bf16 v[112:115], v[234:237], v[192:195], v[112:115]
	v_mfma_f32_16x16x32_bf16 v[100:103], v[226:229], v[200:203], v[100:103]
	v_mfma_f32_16x16x32_bf16 v[96:99], v[234:237], v[200:203], v[96:99]
	v_mfma_f32_16x16x32_bf16 v[84:87], v[226:229], v[210:213], v[84:87]
	v_mfma_f32_16x16x32_bf16 v[80:83], v[234:237], v[210:213], v[80:83]
	v_mfma_f32_16x16x32_bf16 v[68:71], v[226:229], v[218:221], v[68:71]
	v_mfma_f32_16x16x32_bf16 v[64:67], v[234:237], v[218:221], v[64:67]
	s_setprio 0
	s_mov_b32 m0, s16
	v_lshl_add_u64 v[240:241], s[40:41], 0, v[170:171]
	s_barrier
	ds_read_b128 v[146:149], v163 offset:16384
	ds_read_b128 v[192:195], v163 offset:17408
	ds_read_b128 v[196:199], v163 offset:18432
	ds_read_b128 v[200:203], v163 offset:19456
	ds_read_b128 v[206:209], v163 offset:20480
	ds_read_b128 v[210:213], v163 offset:21504
	ds_read_b128 v[214:217], v163 offset:22528
	ds_read_b128 v[218:221], v163 offset:23552
	global_load_lds_dwordx4 v[240:241], off
	v_lshl_add_u64 v[242:243], s[40:41], 0, v[166:167]
	s_mov_b32 m0, s17
	s_nop 0
	global_load_lds_dwordx4 v[242:243], off
	s_barrier
	s_waitcnt lgkmcnt(0)
	s_setprio 1
	v_mfma_f32_16x16x32_bf16 v[60:63], v[130:133], v[146:149], v[60:63]
	v_mfma_f32_16x16x32_bf16 v[56:59], v[138:141], v[146:149], v[56:59]
	v_mfma_f32_16x16x32_bf16 v[44:47], v[130:133], v[196:199], v[44:47]
	v_mfma_f32_16x16x32_bf16 v[40:43], v[138:141], v[196:199], v[40:43]
	v_mfma_f32_16x16x32_bf16 v[28:31], v[130:133], v[206:209], v[28:31]
	v_mfma_f32_16x16x32_bf16 v[24:27], v[138:141], v[206:209], v[24:27]
	v_mfma_f32_16x16x32_bf16 v[12:15], v[130:133], v[214:217], v[12:15]
	v_mfma_f32_16x16x32_bf16 v[8:11], v[138:141], v[214:217], v[8:11]
	v_mfma_f32_16x16x32_bf16 v[60:63], v[134:137], v[192:195], v[60:63]
	v_mfma_f32_16x16x32_bf16 v[56:59], v[142:145], v[192:195], v[56:59]
	v_mfma_f32_16x16x32_bf16 v[44:47], v[134:137], v[200:203], v[44:47]
	v_mfma_f32_16x16x32_bf16 v[40:43], v[142:145], v[200:203], v[40:43]
	v_mfma_f32_16x16x32_bf16 v[28:31], v[134:137], v[210:213], v[28:31]
	v_mfma_f32_16x16x32_bf16 v[24:27], v[142:145], v[210:213], v[24:27]
	v_mfma_f32_16x16x32_bf16 v[12:15], v[134:137], v[218:221], v[12:15]
	v_mfma_f32_16x16x32_bf16 v[8:11], v[142:145], v[218:221], v[8:11]
	s_setprio 0
	s_barrier
; #define PG8_STAGE(bufoff, gbase, voff) do { _Pragma("unroll") for (int _i = 0; _i < 2; ++_i) \
;         __builtin_amdgcn_global_load_lds((const unsigned*)((const char*)(gbase) + (voff)[_i]), (PG8_LAS unsigned*)(lds + (bufoff) + ldsw + _i * 8192), 16, 0, 0); } while (0)
; #define PG8_LDA(dst, b, h) do { _Pragma("unroll") for (int m = 0; m < 4; ++m) _Pragma("unroll") for (int k = 0; k < 2; ++k) dst[m][k] = *(const PG8_LAS bf16x8*)(lds + PG8_SA(b, h) + aoff + m * 2048 + k * 1024); } while (0)
; #define PG8_LDB(dst, b, h) do { _Pragma("unroll") for (int n = 0; n < 2; ++n) _Pragma("unroll") for (int k = 0; k < 2; ++k) dst[n][k] = *(const PG8_LAS bf16x8*)(lds + PG8_SB(b, h) + boff + n * 2048 + k * 1024); } while (0)
; #define PG8_MMA(ai, bj, At, Bt) do { __builtin_amdgcn_s_setprio(1); _Pragma("unroll") for (int m = 0; m < 4; ++m) _Pragma("unroll") for (int n = 0; n < 2; ++n) _Pragma("unroll") for (int k = 0; k < 2; ++k) \
;         acc[ai][bj][m][n] = __builtin_amdgcn_mfma_f32_16x16x32_bf16(Bt[n][k], At[m][k], acc[ai][bj][m][n], 0, 0, 0); __builtin_amdgcn_s_setprio(0); } while (0)
; #define PG8_WAIT_V(n) asm volatile("s_waitcnt vmcnt(" #n ")" ::: "memory")
; #define PG8_WAIT_L(n) asm volatile("s_waitcnt lgkmcnt(" #n ")" ::: "memory")
; #define PG8_BAR __builtin_amdgcn_s_barrier()
; #define PG8_SCHED __builtin_amdgcn_sched_barrier(0)
; template <class Epi, class Sched>
; __device__ __forceinline__ void gemm_phase(PG8_LAS unsigned char* lds, const Gemm g, const Sched& S, const Epi& E) {
;     ...
;             PG8_STAGE(PG8_SB(0, 1), b2 + hstep, voffB);
;             PG8_WAIT_V(6); PG8_BAR; PG8_MMA(1, 1, At, B1); PG8_BAR;
;             PG8_LDB(B0, 1, 0); PG8_SCHED; PG8_LDA(At, 1, 0); PG8_STAGE(PG8_SA(0, 1), a2 + hstep, voffA);
;             PG8_WAIT_L(8); PG8_BAR; PG8_WAIT_L(0); PG8_MMA(0, 0, At, B0); PG8_BAR; PG8_SCHED;
;             PG8_LDB(B1, 1, 1); PG8_STAGE(PG8_SB(1, 0), b3, voffB);
	s_add_u32 s48, s38, 0x40000
	s_addc_u32 s49, s39, 0
	s_add_i32 s30, s34, s3
	v_lshl_add_u64 v[130:131], s[48:49], 0, v[168:169]
	s_mov_b32 m0, s30
	s_nop 0
	global_load_lds_dwordx4 v[130:131], off
	v_lshl_add_u64 v[130:131], s[48:49], 0, v[164:165]
	s_add_i32 m0, s30, 0x2000
	s_nop 0
	global_load_lds_dwordx4 v[130:131], off
	s_waitcnt vmcnt(6)
	s_barrier
	s_setprio 1
	v_mfma_f32_16x16x32_bf16 v[52:55], v[222:225], v[146:149], v[52:55]
	v_mfma_f32_16x16x32_bf16 v[48:51], v[230:233], v[146:149], v[48:51]
	v_mfma_f32_16x16x32_bf16 v[36:39], v[222:225], v[196:199], v[36:39]
	v_mfma_f32_16x16x32_bf16 v[32:35], v[230:233], v[196:199], v[32:35]
	v_mfma_f32_16x16x32_bf16 v[20:23], v[222:225], v[206:209], v[20:23]
	v_mfma_f32_16x16x32_bf16 v[16:19], v[230:233], v[206:209], v[16:19]
	v_mfma_f32_16x16x32_bf16 v[4:7], v[222:225], v[214:217], v[4:7]
	v_mfma_f32_16x16x32_bf16 v[0:3], v[230:233], v[214:217], v[0:3]
	v_mfma_f32_16x16x32_bf16 v[52:55], v[226:229], v[192:195], v[52:55]
	v_mfma_f32_16x16x32_bf16 v[48:51], v[234:237], v[192:195], v[48:51]
	v_mfma_f32_16x16x32_bf16 v[36:39], v[226:229], v[200:203], v[36:39]
	v_mfma_f32_16x16x32_bf16 v[32:35], v[234:237], v[200:203], v[32:35]
	v_mfma_f32_16x16x32_bf16 v[20:23], v[226:229], v[210:213], v[20:23]
	v_mfma_f32_16x16x32_bf16 v[16:19], v[234:237], v[210:213], v[16:19]
	v_mfma_f32_16x16x32_bf16 v[4:7], v[226:229], v[218:221], v[4:7]
	v_mfma_f32_16x16x32_bf16 v[0:3], v[234:237], v[218:221], v[0:3]
	s_setprio 0
	s_add_i32 s30, 0, 0x18000
	v_add_u32_e32 v142, s30, v159
	s_barrier
	ds_read_b128 v[130:133], v142
	ds_read_b128 v[134:137], v142 offset:1024
	ds_read_b128 v[138:141], v142 offset:2048
	ds_read_b128 v[142:145], v142 offset:3072
	s_add_u32 s40, s40, 0x40000
	s_addc_u32 s41, s41, 0
	s_mov_b32 m0, s18
	v_lshl_add_u64 v[222:223], s[40:41], 0, v[170:171]
	ds_read_b128 v[146:149], v163 offset:32768
	ds_read_b128 v[192:195], v163 offset:33792
	ds_read_b128 v[196:199], v163 offset:34816
	ds_read_b128 v[200:203], v163 offset:35840
	ds_read_b128 v[206:209], v163 offset:36864
	ds_read_b128 v[210:213], v163 offset:37888
	ds_read_b128 v[214:217], v163 offset:38912
	ds_read_b128 v[218:221], v163 offset:39936
	global_load_lds_dwordx4 v[222:223], off
	v_lshl_add_u64 v[222:223], s[40:41], 0, v[166:167]
	s_mov_b32 m0, s19
	s_nop 0
	global_load_lds_dwordx4 v[222:223], off
	s_waitcnt lgkmcnt(8)
	s_barrier
	s_waitcnt lgkmcnt(0)
	s_setprio 1
	v_mfma_f32_16x16x32_bf16 v[124:127], v[130:133], v[146:149], v[124:127]
	v_mfma_f32_16x16x32_bf16 v[120:123], v[138:141], v[146:149], v[120:123]
	v_mfma_f32_16x16x32_bf16 v[108:111], v[130:133], v[196:199], v[108:111]
	v_mfma_f32_16x16x32_bf16 v[104:107], v[138:141], v[196:199], v[104:107]
	v_mfma_f32_16x16x32_bf16 v[92:95], v[130:133], v[206:209], v[92:95]
	v_mfma_f32_16x16x32_bf16 v[88:91], v[138:141], v[206:209], v[88:91]
	v_mfma_f32_16x16x32_bf16 v[76:79], v[130:133], v[214:217], v[76:79]
	v_mfma_f32_16x16x32_bf16 v[72:75], v[138:141], v[214:217], v[72:75]
	v_mfma_f32_16x16x32_bf16 v[124:127], v[134:137], v[192:195], v[124:127]
	v_mfma_f32_16x16x32_bf16 v[120:123], v[142:145], v[192:195], v[120:123]
	v_mfma_f32_16x16x32_bf16 v[108:111], v[134:137], v[200:203], v[108:111]
	v_mfma_f32_16x16x32_bf16 v[104:107], v[142:145], v[200:203], v[104:107]
	v_mfma_f32_16x16x32_bf16 v[92:95], v[134:137], v[210:213], v[92:95]
	v_mfma_f32_16x16x32_bf16 v[88:91], v[142:145], v[210:213], v[88:91]
	v_mfma_f32_16x16x32_bf16 v[76:79], v[134:137], v[218:221], v[76:79]
	v_mfma_f32_16x16x32_bf16 v[72:75], v[142:145], v[218:221], v[72:75]
	s_setprio 0
	s_barrier
	s_add_i32 s40, 0, 0x1c000
	s_add_i32 s30, s30, s3
	v_add_u32_e32 v205, s40, v159
	v_lshl_add_u64 v[150:151], v[150:151], 0, s[8:9]
	s_mov_b32 m0, s30
	ds_read_b128 v[222:225], v205
	ds_read_b128 v[226:229], v205 offset:1024
	ds_read_b128 v[230:233], v205 offset:2048
	ds_read_b128 v[234:237], v205 offset:3072
	global_load_lds_dwordx4 v[150:151], off
	v_lshl_add_u64 v[150:151], v[238:239], 0, s[8:9]
	s_add_i32 m0, s30, 0x2000
	s_nop 0
	global_load_lds_dwordx4 v[150:151], off
	s_barrier
; #define PG8_STAGE(bufoff, gbase, voff) do { _Pragma("unroll") for (int _i = 0; _i < 2; ++_i) \
;         __builtin_amdgcn_global_load_lds((const unsigned*)((const char*)(gbase) + (voff)[_i]), (PG8_LAS unsigned*)(lds + (bufoff) + ldsw + _i * 8192), 16, 0, 0); } while (0)
; #define PG8_LDA(dst, b, h) do { _Pragma("unroll") for (int m = 0; m < 4; ++m) _Pragma("unroll") for (int k = 0; k < 2; ++k) dst[m][k] = *(const PG8_LAS bf16x8*)(lds + PG8_SA(b, h) + aoff + m * 2048 + k * 1024); } while (0)
; #define PG8_MMA(ai, bj, At, Bt) do { __builtin_amdgcn_s_setprio(1); _Pragma("unroll") for (int m = 0; m < 4; ++m) _Pragma("unroll") for (int n = 0; n < 2; ++n) _Pragma("unroll") for (int k = 0; k < 2; ++k) \
;         acc[ai][bj][m][n] = __builtin_amdgcn_mfma_f32_16x16x32_bf16(Bt[n][k], At[m][k], acc[ai][bj][m][n], 0, 0, 0); __builtin_amdgcn_s_setprio(0); } while (0)
; #define PG8_WAIT_V(n) asm volatile("s_waitcnt vmcnt(" #n ")" ::: "memory")
; #define PG8_WAIT_L(n) asm volatile("s_waitcnt lgkmcnt(" #n ")" ::: "memory")
; #define PG8_BAR __builtin_amdgcn_s_barrier()
; #define PG8_SCHED __builtin_amdgcn_sched_barrier(0)
; template <class Epi, class Sched>
; __device__ __forceinline__ void gemm_phase(PG8_LAS unsigned char* lds, const Gemm g, const Sched& S, const Epi& E) {
;     ...
;             PG8_BAR; PG8_WAIT_L(0); PG8_MMA(0, 1, At, B1); PG8_BAR;
;             PG8_LDA(At, 1, 1); PG8_STAGE(PG8_SA(1, 0), a3, voffA);
;             PG8_BAR; PG8_WAIT_L(0); PG8_MMA(1, 0, At, B0); PG8_BAR; PG8_SCHED;
;             PG8_STAGE(PG8_SB(1, 1), b3 + hstep, voffB);
;             PG8_WAIT_V(6); PG8_BAR; PG8_MMA(1, 1, At, B1); PG8_BAR;
	s_waitcnt lgkmcnt(0)
	s_setprio 1
	v_mfma_f32_16x16x32_bf16 v[116:119], v[222:225], v[146:149], v[116:119]
	v_mfma_f32_16x16x32_bf16 v[112:115], v[230:233], v[146:149], v[112:115]
	v_mfma_f32_16x16x32_bf16 v[100:103], v[222:225], v[196:199], v[100:103]
	v_mfma_f32_16x16x32_bf16 v[96:99], v[230:233], v[196:199], v[96:99]
	v_mfma_f32_16x16x32_bf16 v[84:87], v[222:225], v[206:209], v[84:87]
	v_mfma_f32_16x16x32_bf16 v[80:83], v[230:233], v[206:209], v[80:83]
	v_mfma_f32_16x16x32_bf16 v[68:71], v[222:225], v[214:217], v[68:71]
	v_mfma_f32_16x16x32_bf16 v[64:67], v[230:233], v[214:217], v[64:67]
	v_mfma_f32_16x16x32_bf16 v[116:119], v[226:229], v[192:195], v[116:119]
	v_mfma_f32_16x16x32_bf16 v[112:115], v[234:237], v[192:195], v[112:115]
	v_mfma_f32_16x16x32_bf16 v[100:103], v[226:229], v[200:203], v[100:103]
	v_mfma_f32_16x16x32_bf16 v[96:99], v[234:237], v[200:203], v[96:99]
	v_mfma_f32_16x16x32_bf16 v[84:87], v[226:229], v[210:213], v[84:87]
	v_mfma_f32_16x16x32_bf16 v[80:83], v[234:237], v[210:213], v[80:83]
	v_mfma_f32_16x16x32_bf16 v[68:71], v[226:229], v[218:221], v[68:71]
	v_mfma_f32_16x16x32_bf16 v[64:67], v[234:237], v[218:221], v[64:67]
	s_setprio 0
	s_mov_b32 m0, s25
	v_lshl_add_u64 v[150:151], v[240:241], 0, s[8:9]
	s_barrier
	ds_read_b128 v[146:149], v163 offset:49152
	ds_read_b128 v[192:195], v163 offset:50176
	ds_read_b128 v[196:199], v163 offset:51200
	ds_read_b128 v[200:203], v163 offset:52224
	ds_read_b128 v[206:209], v163 offset:53248
	ds_read_b128 v[210:213], v163 offset:54272
	ds_read_b128 v[214:217], v163 offset:55296
	ds_read_b128 v[218:221], v163 offset:56320
	global_load_lds_dwordx4 v[150:151], off
	v_lshl_add_u64 v[150:151], v[242:243], 0, s[8:9]
	s_mov_b32 m0, s29
	s_nop 0
	global_load_lds_dwordx4 v[150:151], off
	s_barrier
	s_waitcnt lgkmcnt(0)
	s_setprio 1
	v_mfma_f32_16x16x32_bf16 v[60:63], v[130:133], v[146:149], v[60:63]
	v_mfma_f32_16x16x32_bf16 v[56:59], v[138:141], v[146:149], v[56:59]
	v_mfma_f32_16x16x32_bf16 v[44:47], v[130:133], v[196:199], v[44:47]
	v_mfma_f32_16x16x32_bf16 v[40:43], v[138:141], v[196:199], v[40:43]
	v_mfma_f32_16x16x32_bf16 v[28:31], v[130:133], v[206:209], v[28:31]
	v_mfma_f32_16x16x32_bf16 v[24:27], v[138:141], v[206:209], v[24:27]
	v_mfma_f32_16x16x32_bf16 v[12:15], v[130:133], v[214:217], v[12:15]
	v_mfma_f32_16x16x32_bf16 v[8:11], v[138:141], v[214:217], v[8:11]
	v_mfma_f32_16x16x32_bf16 v[60:63], v[134:137], v[192:195], v[60:63]
	v_mfma_f32_16x16x32_bf16 v[56:59], v[142:145], v[192:195], v[56:59]
	v_mfma_f32_16x16x32_bf16 v[44:47], v[134:137], v[200:203], v[44:47]
	v_mfma_f32_16x16x32_bf16 v[40:43], v[142:145], v[200:203], v[40:43]
	v_mfma_f32_16x16x32_bf16 v[28:31], v[134:137], v[210:213], v[28:31]
	v_mfma_f32_16x16x32_bf16 v[24:27], v[142:145], v[210:213], v[24:27]
	v_mfma_f32_16x16x32_bf16 v[12:15], v[134:137], v[218:221], v[12:15]
	v_mfma_f32_16x16x32_bf16 v[8:11], v[142:145], v[218:221], v[8:11]
	s_setprio 0
	s_barrier
	s_add_u32 s38, s38, 0x40080
	s_addc_u32 s39, s39, 0
	s_add_i32 s30, s40, s3
	v_lshl_add_u64 v[130:131], s[38:39], 0, v[168:169]
	s_mov_b32 m0, s30
	s_nop 0
	global_load_lds_dwordx4 v[130:131], off
	v_lshl_add_u64 v[130:131], s[38:39], 0, v[164:165]
	s_add_i32 m0, s30, 0x2000
	s_nop 0
	global_load_lds_dwordx4 v[130:131], off
	s_waitcnt vmcnt(6)
	s_barrier
	s_setprio 1
	v_mfma_f32_16x16x32_bf16 v[52:55], v[222:225], v[146:149], v[52:55]
	v_mfma_f32_16x16x32_bf16 v[48:51], v[230:233], v[146:149], v[48:51]
	v_mfma_f32_16x16x32_bf16 v[36:39], v[222:225], v[196:199], v[36:39]
	v_mfma_f32_16x16x32_bf16 v[32:35], v[230:233], v[196:199], v[32:35]
	v_mfma_f32_16x16x32_bf16 v[20:23], v[222:225], v[206:209], v[20:23]
	v_mfma_f32_16x16x32_bf16 v[16:19], v[230:233], v[206:209], v[16:19]
	v_mfma_f32_16x16x32_bf16 v[4:7], v[222:225], v[214:217], v[4:7]
	v_mfma_f32_16x16x32_bf16 v[0:3], v[230:233], v[214:217], v[0:3]
	v_mfma_f32_16x16x32_bf16 v[52:55], v[226:229], v[192:195], v[52:55]
	v_mfma_f32_16x16x32_bf16 v[48:51], v[234:237], v[192:195], v[48:51]
	v_mfma_f32_16x16x32_bf16 v[36:39], v[226:229], v[200:203], v[36:39]
	v_mfma_f32_16x16x32_bf16 v[32:35], v[234:237], v[200:203], v[32:35]
	v_mfma_f32_16x16x32_bf16 v[20:23], v[226:229], v[210:213], v[20:23]
	v_mfma_f32_16x16x32_bf16 v[16:19], v[234:237], v[210:213], v[16:19]
	v_mfma_f32_16x16x32_bf16 v[4:7], v[226:229], v[218:221], v[4:7]
	v_mfma_f32_16x16x32_bf16 v[0:3], v[234:237], v[218:221], v[0:3]
	s_setprio 0
	s_add_i32 s47, s47, 2
	s_add_u32 s4, s4, 0x100
	s_addc_u32 s5, s5, 0
	s_add_u32 s45, s45, 0x100
	s_addc_u32 s46, s46, 0
	s_cmp_lt_u32 s47, 14
	s_barrier
	s_cbranch_scc0 .LBB0_1512

; #define PG8_STAGE(bufoff, gbase, voff) do { _Pragma("unroll") for (int _i = 0; _i < 2; ++_i) \
;         __builtin_amdgcn_global_load_lds((const unsigned*)((const char*)(gbase) + (voff)[_i]), (PG8_LAS unsigned*)(lds + (bufoff) + ldsw + _i * 8192), 16, 0, 0); } while (0)
; #define PG8_LDA(dst, b, h) do { _Pragma("unroll") for (int m = 0; m < 4; ++m) _Pragma("unroll") for (int k = 0; k < 2; ++k) dst[m][k] = *(const PG8_LAS bf16x8*)(lds + PG8_SA(b, h) + aoff + m * 2048 + k * 1024); } while (0)
; #define PG8_LDB(dst, b, h) do { _Pragma("unroll") for (int n = 0; n < 2; ++n) _Pragma("unroll") for (int k = 0; k < 2; ++k) dst[n][k] = *(const PG8_LAS bf16x8*)(lds + PG8_SB(b, h) + boff + n * 2048 + k * 1024); } while (0)
; #define PG8_MMA(ai, bj, At, Bt) do { __builtin_amdgcn_s_setprio(1); _Pragma("unroll") for (int m = 0; m < 4; ++m) _Pragma("unroll") for (int n = 0; n < 2; ++n) _Pragma("unroll") for (int k = 0; k < 2; ++k) \
;         acc[ai][bj][m][n] = __builtin_amdgcn_mfma_f32_16x16x32_bf16(Bt[n][k], At[m][k], acc[ai][bj][m][n], 0, 0, 0); __builtin_amdgcn_s_setprio(0); } while (0)
; #define PG8_WAIT_L(n) asm volatile("s_waitcnt lgkmcnt(" #n ")" ::: "memory")
; #define PG8_BAR __builtin_amdgcn_s_barrier()
; #define PG8_SCHED __builtin_amdgcn_sched_barrier(0)
; template <class Epi, class Sched>
; __device__ __forceinline__ void gemm_phase(PG8_LAS unsigned char* lds, const Gemm g, const Sched& S, const Epi& E) {
;     ...
;             PG8_LDB(B0, 0, 0); PG8_SCHED; PG8_LDA(At, 0, 0); PG8_STAGE(PG8_SA(1, 1), a1 + hstep, voffA);
;             PG8_WAIT_L(8); PG8_BAR; PG8_WAIT_L(0); PG8_MMA(0, 0, At, B0); PG8_BAR; PG8_SCHED;
;             PG8_LDB(B1, 0, 1); PG8_STAGE(PG8_SB(0, 0), b2, voffB);
;             PG8_BAR; PG8_WAIT_L(0); PG8_MMA(0, 1, At, B1); PG8_BAR;
;             PG8_LDA(At, 0, 1); PG8_STAGE(PG8_SA(0, 0), a2, voffA);
;             PG8_BAR; PG8_WAIT_L(0); PG8_MMA(1, 0, At, B0); PG8_BAR; PG8_SCHED;
.LBB0_1636:
	ds_read_b128 v[128:131], v163
	ds_read_b128 v[132:135], v163 offset:1024
	ds_read_b128 v[136:139], v163 offset:2048
	ds_read_b128 v[140:143], v163 offset:3072
	s_add_i32 s76, s45, 2
	s_add_u32 s30, s48, 0xfff00080
	s_addc_u32 s50, s49, -1
	s_cmp_eq_u32 s27, s45
	s_cselect_b32 s53, s43, s50
	s_cselect_b32 s52, s42, s30
	s_cselect_b32 s51, s47, s39
	s_cselect_b32 s50, s46, s37
	v_lshl_add_u64 v[196:197], s[48:49], 0, v[174:175]
	s_add_i32 m0, s5, 0xc000
	ds_read_b128 v[144:147], v198
	ds_read_b128 v[148:151], v198 offset:1024
	ds_read_b128 v[180:183], v198 offset:2048
	ds_read_b128 v[184:187], v198 offset:3072
	ds_read_b128 v[188:191], v198 offset:4096
	ds_read_b128 v[192:195], v198 offset:5120
	ds_read_b128 v[202:205], v198 offset:6144
	ds_read_b128 v[206:209], v198 offset:7168
	global_load_lds_dwordx4 v[196:197], off
	v_lshl_add_u64 v[196:197], s[48:49], 0, v[176:177]
	s_add_i32 m0, s5, 0xe000
	s_nop 0
	global_load_lds_dwordx4 v[196:197], off
	s_waitcnt lgkmcnt(8)
	s_barrier
	s_waitcnt lgkmcnt(0)
	s_setprio 1
	v_mfma_f32_16x16x32_bf16 v[124:127], v[128:131], v[144:147], v[124:127]
	v_mfma_f32_16x16x32_bf16 v[120:123], v[136:139], v[144:147], v[120:123]
	v_mfma_f32_16x16x32_bf16 v[108:111], v[128:131], v[180:183], v[108:111]
	v_mfma_f32_16x16x32_bf16 v[104:107], v[136:139], v[180:183], v[104:107]
	v_mfma_f32_16x16x32_bf16 v[92:95], v[128:131], v[188:191], v[92:95]
	v_mfma_f32_16x16x32_bf16 v[88:91], v[136:139], v[188:191], v[88:91]
	v_mfma_f32_16x16x32_bf16 v[76:79], v[128:131], v[202:205], v[76:79]
	v_mfma_f32_16x16x32_bf16 v[72:75], v[136:139], v[202:205], v[72:75]
	v_mfma_f32_16x16x32_bf16 v[124:127], v[132:135], v[148:151], v[124:127]
	v_mfma_f32_16x16x32_bf16 v[120:123], v[140:143], v[148:151], v[120:123]
	v_mfma_f32_16x16x32_bf16 v[108:111], v[132:135], v[184:187], v[108:111]
	v_mfma_f32_16x16x32_bf16 v[104:107], v[140:143], v[184:187], v[104:107]
	v_mfma_f32_16x16x32_bf16 v[92:95], v[132:135], v[192:195], v[92:95]
	v_mfma_f32_16x16x32_bf16 v[88:91], v[140:143], v[192:195], v[88:91]
	v_mfma_f32_16x16x32_bf16 v[76:79], v[132:135], v[206:209], v[76:79]
	v_mfma_f32_16x16x32_bf16 v[72:75], v[140:143], v[206:209], v[72:75]
	s_setprio 0
	s_barrier
	s_add_i32 s30, s71, s4
	v_lshl_add_u64 v[196:197], s[50:51], 0, v[166:167]
	s_mov_b32 m0, s30
	ds_read_b128 v[210:213], v199
	ds_read_b128 v[214:217], v199 offset:1024
	ds_read_b128 v[218:221], v199 offset:2048
	ds_read_b128 v[222:225], v199 offset:3072
	global_load_lds_dwordx4 v[196:197], off
	v_lshl_add_u64 v[226:227], s[50:51], 0, v[170:171]
	s_add_i32 m0, s30, 0x2000
	s_nop 0
	global_load_lds_dwordx4 v[226:227], off
	s_barrier
	s_waitcnt lgkmcnt(0)
	s_setprio 1
	v_mfma_f32_16x16x32_bf16 v[116:119], v[210:213], v[144:147], v[116:119]
	v_mfma_f32_16x16x32_bf16 v[112:115], v[218:221], v[144:147], v[112:115]
	v_mfma_f32_16x16x32_bf16 v[100:103], v[210:213], v[180:183], v[100:103]
	v_mfma_f32_16x16x32_bf16 v[96:99], v[218:221], v[180:183], v[96:99]
	v_mfma_f32_16x16x32_bf16 v[84:87], v[210:213], v[188:191], v[84:87]
	v_mfma_f32_16x16x32_bf16 v[80:83], v[218:221], v[188:191], v[80:83]
	v_mfma_f32_16x16x32_bf16 v[68:71], v[210:213], v[202:205], v[68:71]
	v_mfma_f32_16x16x32_bf16 v[64:67], v[218:221], v[202:205], v[64:67]
	v_mfma_f32_16x16x32_bf16 v[116:119], v[214:217], v[148:151], v[116:119]
	v_mfma_f32_16x16x32_bf16 v[112:115], v[222:225], v[148:151], v[112:115]
	v_mfma_f32_16x16x32_bf16 v[100:103], v[214:217], v[184:187], v[100:103]
	v_mfma_f32_16x16x32_bf16 v[96:99], v[222:225], v[184:187], v[96:99]
	v_mfma_f32_16x16x32_bf16 v[84:87], v[214:217], v[192:195], v[84:87]
	v_mfma_f32_16x16x32_bf16 v[80:83], v[222:225], v[192:195], v[80:83]
	v_mfma_f32_16x16x32_bf16 v[68:71], v[214:217], v[206:209], v[68:71]
	v_mfma_f32_16x16x32_bf16 v[64:67], v[222:225], v[206:209], v[64:67]
	s_setprio 0
	s_mov_b32 m0, s5
	v_lshl_add_u64 v[228:229], s[52:53], 0, v[164:165]
	s_barrier
	ds_read_b128 v[144:147], v198 offset:16384
	ds_read_b128 v[148:151], v198 offset:17408
	ds_read_b128 v[180:183], v198 offset:18432
	ds_read_b128 v[184:187], v198 offset:19456
	ds_read_b128 v[188:191], v198 offset:20480
	ds_read_b128 v[192:195], v198 offset:21504
	ds_read_b128 v[202:205], v198 offset:22528
	ds_read_b128 v[206:209], v198 offset:23552
	global_load_lds_dwordx4 v[228:229], off
	v_lshl_add_u64 v[230:231], s[52:53], 0, v[168:169]
	s_mov_b32 m0, s16
	s_nop 0
	global_load_lds_dwordx4 v[230:231], off
	s_barrier
	s_waitcnt lgkmcnt(0)
	s_setprio 1
	v_mfma_f32_16x16x32_bf16 v[60:63], v[128:131], v[144:147], v[60:63]
	v_mfma_f32_16x16x32_bf16 v[56:59], v[136:139], v[144:147], v[56:59]
	v_mfma_f32_16x16x32_bf16 v[44:47], v[128:131], v[180:183], v[44:47]
	v_mfma_f32_16x16x32_bf16 v[40:43], v[136:139], v[180:183], v[40:43]
	v_mfma_f32_16x16x32_bf16 v[28:31], v[128:131], v[188:191], v[28:31]
	v_mfma_f32_16x16x32_bf16 v[24:27], v[136:139], v[188:191], v[24:27]
	v_mfma_f32_16x16x32_bf16 v[12:15], v[128:131], v[202:205], v[12:15]
	v_mfma_f32_16x16x32_bf16 v[8:11], v[136:139], v[202:205], v[8:11]
	v_mfma_f32_16x16x32_bf16 v[60:63], v[132:135], v[148:151], v[60:63]
	v_mfma_f32_16x16x32_bf16 v[56:59], v[140:143], v[148:151], v[56:59]
	v_mfma_f32_16x16x32_bf16 v[44:47], v[132:135], v[184:187], v[44:47]
	v_mfma_f32_16x16x32_bf16 v[40:43], v[140:143], v[184:187], v[40:43]
	v_mfma_f32_16x16x32_bf16 v[28:31], v[132:135], v[192:195], v[28:31]
	v_mfma_f32_16x16x32_bf16 v[24:27], v[140:143], v[192:195], v[24:27]
	v_mfma_f32_16x16x32_bf16 v[12:15], v[132:135], v[206:209], v[12:15]
	v_mfma_f32_16x16x32_bf16 v[8:11], v[140:143], v[206:209], v[8:11]
	s_setprio 0
	s_barrier
; #define PG8_STAGE(bufoff, gbase, voff) do { _Pragma("unroll") for (int _i = 0; _i < 2; ++_i) \
;         __builtin_amdgcn_global_load_lds((const unsigned*)((const char*)(gbase) + (voff)[_i]), (PG8_LAS unsigned*)(lds + (bufoff) + ldsw + _i * 8192), 16, 0, 0); } while (0)
; #define PG8_LDA(dst, b, h) do { _Pragma("unroll") for (int m = 0; m < 4; ++m) _Pragma("unroll") for (int k = 0; k < 2; ++k) dst[m][k] = *(const PG8_LAS bf16x8*)(lds + PG8_SA(b, h) + aoff + m * 2048 + k * 1024); } while (0)
; #define PG8_LDB(dst, b, h) do { _Pragma("unroll") for (int n = 0; n < 2; ++n) _Pragma("unroll") for (int k = 0; k < 2; ++k) dst[n][k] = *(const PG8_LAS bf16x8*)(lds + PG8_SB(b, h) + boff + n * 2048 + k * 1024); } while (0)
; #define PG8_MMA(ai, bj, At, Bt) do { __builtin_amdgcn_s_setprio(1); _Pragma("unroll") for (int m = 0; m < 4; ++m) _Pragma("unroll") for (int n = 0; n < 2; ++n) _Pragma("unroll") for (int k = 0; k < 2; ++k) \
;         acc[ai][bj][m][n] = __builtin_amdgcn_mfma_f32_16x16x32_bf16(Bt[n][k], At[m][k], acc[ai][bj][m][n], 0, 0, 0); __builtin_amdgcn_s_setprio(0); } while (0)
; #define PG8_WAIT_V(n) asm volatile("s_waitcnt vmcnt(" #n ")" ::: "memory")
; #define PG8_WAIT_L(n) asm volatile("s_waitcnt lgkmcnt(" #n ")" ::: "memory")
; #define PG8_BAR __builtin_amdgcn_s_barrier()
; #define PG8_SCHED __builtin_amdgcn_sched_barrier(0)
; template <class Epi, class Sched>
; __device__ __forceinline__ void gemm_phase(PG8_LAS unsigned char* lds, const Gemm g, const Sched& S, const Epi& E) {
;     ...
;             PG8_STAGE(PG8_SB(0, 1), b2 + hstep, voffB);
;             PG8_WAIT_V(6); PG8_BAR; PG8_MMA(1, 1, At, B1); PG8_BAR;
;             PG8_LDB(B0, 1, 0); PG8_SCHED; PG8_LDA(At, 1, 0); PG8_STAGE(PG8_SA(0, 1), a2 + hstep, voffA);
;             PG8_WAIT_L(8); PG8_BAR; PG8_WAIT_L(0); PG8_MMA(0, 0, At, B0); PG8_BAR; PG8_SCHED;
;             PG8_LDB(B1, 1, 1); PG8_STAGE(PG8_SB(1, 0), b3, voffB);
	s_add_u32 s96, s50, 0x100000
	s_addc_u32 s97, s51, 0
	s_add_i32 s30, s72, s4
	v_lshl_add_u64 v[128:129], s[96:97], 0, v[166:167]
	s_mov_b32 m0, s30
	s_nop 0
	global_load_lds_dwordx4 v[128:129], off
	v_lshl_add_u64 v[128:129], s[96:97], 0, v[170:171]
	s_add_i32 m0, s30, 0x2000
	s_nop 0
	global_load_lds_dwordx4 v[128:129], off
	s_waitcnt vmcnt(6)
	s_barrier
	s_setprio 1
	v_mfma_f32_16x16x32_bf16 v[52:55], v[210:213], v[144:147], v[52:55]
	v_mfma_f32_16x16x32_bf16 v[48:51], v[218:221], v[144:147], v[48:51]
	v_mfma_f32_16x16x32_bf16 v[36:39], v[210:213], v[180:183], v[36:39]
	v_mfma_f32_16x16x32_bf16 v[32:35], v[218:221], v[180:183], v[32:35]
	v_mfma_f32_16x16x32_bf16 v[20:23], v[210:213], v[188:191], v[20:23]
	v_mfma_f32_16x16x32_bf16 v[16:19], v[218:221], v[188:191], v[16:19]
	v_mfma_f32_16x16x32_bf16 v[4:7], v[210:213], v[202:205], v[4:7]
	v_mfma_f32_16x16x32_bf16 v[0:3], v[218:221], v[202:205], v[0:3]
	v_mfma_f32_16x16x32_bf16 v[52:55], v[214:217], v[148:151], v[52:55]
	v_mfma_f32_16x16x32_bf16 v[48:51], v[222:225], v[148:151], v[48:51]
	v_mfma_f32_16x16x32_bf16 v[36:39], v[214:217], v[184:187], v[36:39]
	v_mfma_f32_16x16x32_bf16 v[32:35], v[222:225], v[184:187], v[32:35]
	v_mfma_f32_16x16x32_bf16 v[20:23], v[214:217], v[192:195], v[20:23]
	v_mfma_f32_16x16x32_bf16 v[16:19], v[222:225], v[192:195], v[16:19]
	v_mfma_f32_16x16x32_bf16 v[4:7], v[214:217], v[206:209], v[4:7]
	v_mfma_f32_16x16x32_bf16 v[0:3], v[222:225], v[206:209], v[0:3]
	s_setprio 0
	s_add_i32 s30, 0, 0x18000
	v_add_u32_e32 v140, s30, v159
	s_barrier
	ds_read_b128 v[128:131], v140
	ds_read_b128 v[132:135], v140 offset:1024
	ds_read_b128 v[136:139], v140 offset:2048
	ds_read_b128 v[140:143], v140 offset:3072
	s_add_u32 s52, s52, 0x100000
	s_addc_u32 s53, s53, 0
	s_mov_b32 m0, s17
	v_lshl_add_u64 v[210:211], s[52:53], 0, v[164:165]
	ds_read_b128 v[144:147], v198 offset:32768
	ds_read_b128 v[148:151], v198 offset:33792
	ds_read_b128 v[180:183], v198 offset:34816
	ds_read_b128 v[184:187], v198 offset:35840
	ds_read_b128 v[188:191], v198 offset:36864
	ds_read_b128 v[192:195], v198 offset:37888
	ds_read_b128 v[202:205], v198 offset:38912
	ds_read_b128 v[206:209], v198 offset:39936
	global_load_lds_dwordx4 v[210:211], off
	v_lshl_add_u64 v[210:211], s[52:53], 0, v[168:169]
	s_mov_b32 m0, s18
	s_nop 0
	global_load_lds_dwordx4 v[210:211], off
	s_waitcnt lgkmcnt(8)
	s_barrier
	s_waitcnt lgkmcnt(0)
	s_setprio 1
	v_mfma_f32_16x16x32_bf16 v[124:127], v[128:131], v[144:147], v[124:127]
	v_mfma_f32_16x16x32_bf16 v[120:123], v[136:139], v[144:147], v[120:123]
	v_mfma_f32_16x16x32_bf16 v[108:111], v[128:131], v[180:183], v[108:111]
	v_mfma_f32_16x16x32_bf16 v[104:107], v[136:139], v[180:183], v[104:107]
	v_mfma_f32_16x16x32_bf16 v[92:95], v[128:131], v[188:191], v[92:95]
	v_mfma_f32_16x16x32_bf16 v[88:91], v[136:139], v[188:191], v[88:91]
	v_mfma_f32_16x16x32_bf16 v[76:79], v[128:131], v[202:205], v[76:79]
	v_mfma_f32_16x16x32_bf16 v[72:75], v[136:139], v[202:205], v[72:75]
	v_mfma_f32_16x16x32_bf16 v[124:127], v[132:135], v[148:151], v[124:127]
	v_mfma_f32_16x16x32_bf16 v[120:123], v[140:143], v[148:151], v[120:123]
	v_mfma_f32_16x16x32_bf16 v[108:111], v[132:135], v[184:187], v[108:111]
	v_mfma_f32_16x16x32_bf16 v[104:107], v[140:143], v[184:187], v[104:107]
	v_mfma_f32_16x16x32_bf16 v[92:95], v[132:135], v[192:195], v[92:95]
	v_mfma_f32_16x16x32_bf16 v[88:91], v[140:143], v[192:195], v[88:91]
	v_mfma_f32_16x16x32_bf16 v[76:79], v[132:135], v[206:209], v[76:79]
	v_mfma_f32_16x16x32_bf16 v[72:75], v[140:143], v[206:209], v[72:75]
	s_setprio 0
	s_barrier
	s_add_i32 s45, 0, 0x1c000
	s_add_i32 s30, s30, s4
	v_add_u32_e32 v201, s45, v159
	v_lshl_add_u64 v[196:197], v[196:197], 0, s[14:15]
	s_mov_b32 m0, s30
	ds_read_b128 v[210:213], v201
	ds_read_b128 v[214:217], v201 offset:1024
	ds_read_b128 v[218:221], v201 offset:2048
	ds_read_b128 v[222:225], v201 offset:3072
	global_load_lds_dwordx4 v[196:197], off
	v_lshl_add_u64 v[196:197], v[226:227], 0, s[14:15]
	s_add_i32 m0, s30, 0x2000
	s_nop 0
	global_load_lds_dwordx4 v[196:197], off
	s_barrier
; #define PG8_STAGE(bufoff, gbase, voff) do { _Pragma("unroll") for (int _i = 0; _i < 2; ++_i) \
;         __builtin_amdgcn_global_load_lds((const unsigned*)((const char*)(gbase) + (voff)[_i]), (PG8_LAS unsigned*)(lds + (bufoff) + ldsw + _i * 8192), 16, 0, 0); } while (0)
; #define PG8_LDA(dst, b, h) do { _Pragma("unroll") for (int m = 0; m < 4; ++m) _Pragma("unroll") for (int k = 0; k < 2; ++k) dst[m][k] = *(const PG8_LAS bf16x8*)(lds + PG8_SA(b, h) + aoff + m * 2048 + k * 1024); } while (0)
; #define PG8_MMA(ai, bj, At, Bt) do { __builtin_amdgcn_s_setprio(1); _Pragma("unroll") for (int m = 0; m < 4; ++m) _Pragma("unroll") for (int n = 0; n < 2; ++n) _Pragma("unroll") for (int k = 0; k < 2; ++k) \
;         acc[ai][bj][m][n] = __builtin_amdgcn_mfma_f32_16x16x32_bf16(Bt[n][k], At[m][k], acc[ai][bj][m][n], 0, 0, 0); __builtin_amdgcn_s_setprio(0); } while (0)
; #define PG8_WAIT_V(n) asm volatile("s_waitcnt vmcnt(" #n ")" ::: "memory")
; #define PG8_WAIT_L(n) asm volatile("s_waitcnt lgkmcnt(" #n ")" ::: "memory")
; #define PG8_BAR __builtin_amdgcn_s_barrier()
; #define PG8_SCHED __builtin_amdgcn_sched_barrier(0)
; template <class Epi, class Sched>
; __device__ __forceinline__ void gemm_phase(PG8_LAS unsigned char* lds, const Gemm g, const Sched& S, const Epi& E) {
;     ...
;             PG8_BAR; PG8_WAIT_L(0); PG8_MMA(0, 1, At, B1); PG8_BAR;
;             PG8_LDA(At, 1, 1); PG8_STAGE(PG8_SA(1, 0), a3, voffA);
;             PG8_BAR; PG8_WAIT_L(0); PG8_MMA(1, 0, At, B0); PG8_BAR; PG8_SCHED;
;             PG8_STAGE(PG8_SB(1, 1), b3 + hstep, voffB);
;             PG8_WAIT_V(6); PG8_BAR; PG8_MMA(1, 1, At, B1); PG8_BAR;
;         }
;         if constexpr (!Epi::AFTER_DRAIN) {
;             if (cur.part < 0) E(acc, cur, wr, wc, fr, fq, pre);
;             else { f32x4* pp = (f32x4*)g.part + (size_t)cur.part * 32 * 512 + tid;
	s_waitcnt lgkmcnt(0)
	s_setprio 1
	v_mfma_f32_16x16x32_bf16 v[116:119], v[210:213], v[144:147], v[116:119]
	v_mfma_f32_16x16x32_bf16 v[112:115], v[218:221], v[144:147], v[112:115]
	v_mfma_f32_16x16x32_bf16 v[100:103], v[210:213], v[180:183], v[100:103]
	v_mfma_f32_16x16x32_bf16 v[96:99], v[218:221], v[180:183], v[96:99]
	v_mfma_f32_16x16x32_bf16 v[84:87], v[210:213], v[188:191], v[84:87]
	v_mfma_f32_16x16x32_bf16 v[80:83], v[218:221], v[188:191], v[80:83]
	v_mfma_f32_16x16x32_bf16 v[68:71], v[210:213], v[202:205], v[68:71]
	v_mfma_f32_16x16x32_bf16 v[64:67], v[218:221], v[202:205], v[64:67]
	v_mfma_f32_16x16x32_bf16 v[116:119], v[214:217], v[148:151], v[116:119]
	v_mfma_f32_16x16x32_bf16 v[112:115], v[222:225], v[148:151], v[112:115]
	v_mfma_f32_16x16x32_bf16 v[100:103], v[214:217], v[184:187], v[100:103]
	v_mfma_f32_16x16x32_bf16 v[96:99], v[222:225], v[184:187], v[96:99]
	v_mfma_f32_16x16x32_bf16 v[84:87], v[214:217], v[192:195], v[84:87]
	v_mfma_f32_16x16x32_bf16 v[80:83], v[222:225], v[192:195], v[80:83]
	v_mfma_f32_16x16x32_bf16 v[68:71], v[214:217], v[206:209], v[68:71]
	v_mfma_f32_16x16x32_bf16 v[64:67], v[222:225], v[206:209], v[64:67]
	s_setprio 0
	s_mov_b32 m0, s24
	v_lshl_add_u64 v[196:197], v[228:229], 0, s[14:15]
	s_barrier
	ds_read_b128 v[144:147], v198 offset:49152
	ds_read_b128 v[148:151], v198 offset:50176
	ds_read_b128 v[180:183], v198 offset:51200
	ds_read_b128 v[184:187], v198 offset:52224
	ds_read_b128 v[188:191], v198 offset:53248
	ds_read_b128 v[192:195], v198 offset:54272
	ds_read_b128 v[202:205], v198 offset:55296
	ds_read_b128 v[206:209], v198 offset:56320
	global_load_lds_dwordx4 v[196:197], off
	v_lshl_add_u64 v[196:197], v[230:231], 0, s[14:15]
	s_mov_b32 m0, s25
	s_nop 0
	global_load_lds_dwordx4 v[196:197], off
	s_barrier
	s_waitcnt lgkmcnt(0)
	s_setprio 1
	v_mfma_f32_16x16x32_bf16 v[60:63], v[128:131], v[144:147], v[60:63]
	v_mfma_f32_16x16x32_bf16 v[56:59], v[136:139], v[144:147], v[56:59]
	v_mfma_f32_16x16x32_bf16 v[44:47], v[128:131], v[180:183], v[44:47]
	v_mfma_f32_16x16x32_bf16 v[40:43], v[136:139], v[180:183], v[40:43]
	v_mfma_f32_16x16x32_bf16 v[28:31], v[128:131], v[188:191], v[28:31]
	v_mfma_f32_16x16x32_bf16 v[24:27], v[136:139], v[188:191], v[24:27]
	v_mfma_f32_16x16x32_bf16 v[12:15], v[128:131], v[202:205], v[12:15]
	v_mfma_f32_16x16x32_bf16 v[8:11], v[136:139], v[202:205], v[8:11]
	v_mfma_f32_16x16x32_bf16 v[60:63], v[132:135], v[148:151], v[60:63]
	v_mfma_f32_16x16x32_bf16 v[56:59], v[140:143], v[148:151], v[56:59]
	v_mfma_f32_16x16x32_bf16 v[44:47], v[132:135], v[184:187], v[44:47]
	v_mfma_f32_16x16x32_bf16 v[40:43], v[140:143], v[184:187], v[40:43]
	v_mfma_f32_16x16x32_bf16 v[28:31], v[132:135], v[192:195], v[28:31]
	v_mfma_f32_16x16x32_bf16 v[24:27], v[140:143], v[192:195], v[24:27]
	v_mfma_f32_16x16x32_bf16 v[12:15], v[132:135], v[206:209], v[12:15]
	v_mfma_f32_16x16x32_bf16 v[8:11], v[140:143], v[206:209], v[8:11]
	s_setprio 0
	s_barrier
	s_add_u32 s50, s50, 0x100080
	s_addc_u32 s51, s51, 0
	s_add_i32 s30, s45, s4
	v_lshl_add_u64 v[128:129], s[50:51], 0, v[166:167]
	s_mov_b32 m0, s30
	s_nop 0
	global_load_lds_dwordx4 v[128:129], off
	v_lshl_add_u64 v[128:129], s[50:51], 0, v[170:171]
	s_add_i32 m0, s30, 0x2000
	s_nop 0
	global_load_lds_dwordx4 v[128:129], off
	s_waitcnt vmcnt(6)
	s_barrier
	s_setprio 1
	v_mfma_f32_16x16x32_bf16 v[52:55], v[210:213], v[144:147], v[52:55]
	v_mfma_f32_16x16x32_bf16 v[48:51], v[218:221], v[144:147], v[48:51]
	v_mfma_f32_16x16x32_bf16 v[36:39], v[210:213], v[180:183], v[36:39]
	v_mfma_f32_16x16x32_bf16 v[32:35], v[218:221], v[180:183], v[32:35]
	v_mfma_f32_16x16x32_bf16 v[20:23], v[210:213], v[188:191], v[20:23]
	v_mfma_f32_16x16x32_bf16 v[16:19], v[218:221], v[188:191], v[16:19]
	v_mfma_f32_16x16x32_bf16 v[4:7], v[210:213], v[202:205], v[4:7]
	v_mfma_f32_16x16x32_bf16 v[0:3], v[218:221], v[202:205], v[0:3]
	v_mfma_f32_16x16x32_bf16 v[52:55], v[214:217], v[148:151], v[52:55]
	v_mfma_f32_16x16x32_bf16 v[48:51], v[222:225], v[148:151], v[48:51]
	v_mfma_f32_16x16x32_bf16 v[36:39], v[214:217], v[184:187], v[36:39]
	v_mfma_f32_16x16x32_bf16 v[32:35], v[222:225], v[184:187], v[32:35]
	v_mfma_f32_16x16x32_bf16 v[20:23], v[214:217], v[192:195], v[20:23]
	v_mfma_f32_16x16x32_bf16 v[16:19], v[222:225], v[192:195], v[16:19]
	v_mfma_f32_16x16x32_bf16 v[4:7], v[214:217], v[206:209], v[4:7]
	v_mfma_f32_16x16x32_bf16 v[0:3], v[222:225], v[206:209], v[0:3]
	s_setprio 0
	s_add_u32 s48, s48, 0x100
	s_addc_u32 s49, s49, 0
	s_add_u32 s37, s37, 0x100
	s_addc_u32 s39, s39, 0
	s_cmp_ge_i32 s76, s23
	s_mov_b32 s45, s76
	s_barrier
	s_cbranch_scc0 .LBB0_1636
	s_cmp_gt_i32 s10, -1
	s_mov_b64 s[48:49], -1
	s_cbranch_scc0 .LBB0_1639

; #define PG8_STAGE(bufoff, gbase, voff) do { _Pragma("unroll") for (int _i = 0; _i < 2; ++_i) \
;         __builtin_amdgcn_global_load_lds((const unsigned*)((const char*)(gbase) + (voff)[_i]), (PG8_LAS unsigned*)(lds + (bufoff) + ldsw + _i * 8192), 16, 0, 0); } while (0)
; #define PG8_LDA(dst, b, h) do { _Pragma("unroll") for (int m = 0; m < 4; ++m) _Pragma("unroll") for (int k = 0; k < 2; ++k) dst[m][k] = *(const PG8_LAS bf16x8*)(lds + PG8_SA(b, h) + aoff + m * 2048 + k * 1024); } while (0)
; #define PG8_LDB(dst, b, h) do { _Pragma("unroll") for (int n = 0; n < 2; ++n) _Pragma("unroll") for (int k = 0; k < 2; ++k) dst[n][k] = *(const PG8_LAS bf16x8*)(lds + PG8_SB(b, h) + boff + n * 2048 + k * 1024); } while (0)
; #define PG8_MMA(ai, bj, At, Bt) do { __builtin_amdgcn_s_setprio(1); _Pragma("unroll") for (int m = 0; m < 4; ++m) _Pragma("unroll") for (int n = 0; n < 2; ++n) _Pragma("unroll") for (int k = 0; k < 2; ++k) \
;         acc[ai][bj][m][n] = __builtin_amdgcn_mfma_f32_16x16x32_bf16(Bt[n][k], At[m][k], acc[ai][bj][m][n], 0, 0, 0); __builtin_amdgcn_s_setprio(0); } while (0)
; #define PG8_WAIT_L(n) asm volatile("s_waitcnt lgkmcnt(" #n ")" ::: "memory")
; #define PG8_BAR __builtin_amdgcn_s_barrier()
; #define PG8_SCHED __builtin_amdgcn_sched_barrier(0)
; template <class Epi, class Sched>
; __device__ __forceinline__ void gemm_phase(PG8_LAS unsigned char* lds, const Gemm g, const Sched& S, const Epi& E) {
;     ...
;             const bool last = (t == cnk - 2);
;             const char* a1 = cA + (size_t)(t + 1) * kstep;
;             const char* a2 = last ? nA : cA + (size_t)(t + 2) * kstep; const char* b2 = last ? nB : cB + (size_t)(t + 2) * kstep;
;             const char* a3 = a2 + kstep; const char* b3 = b2 + kstep;
;             if (last && has_next) S.a_ready(nxt);
;             if (last) E.prefetch(pre, cur, wr, fr);
;             PG8_LDB(B0, 0, 0); PG8_SCHED; PG8_LDA(At, 0, 0); PG8_STAGE(PG8_SA(1, 1), a1 + hstep, voffA);
;             PG8_WAIT_L(8); PG8_BAR; PG8_WAIT_L(0); PG8_MMA(0, 0, At, B0); PG8_BAR; PG8_SCHED;
;             PG8_LDB(B1, 0, 1); PG8_STAGE(PG8_SB(0, 0), b2, voffB);
;             PG8_BAR; PG8_WAIT_L(0); PG8_MMA(0, 1, At, B1); PG8_BAR;
;             PG8_LDA(At, 0, 1); PG8_STAGE(PG8_SA(0, 0), a2, voffA);
;             PG8_BAR; PG8_WAIT_L(0); PG8_MMA(1, 0, At, B0); PG8_BAR; PG8_SCHED;
.LBB0_1847:
	v_add_u32_e32 v138, s73, v159
	ds_read_b128 v[130:133], v138
	ds_read_b128 v[134:137], v138 offset:1024
	ds_read_b128 v[182:185], v138 offset:2048
	ds_read_b128 v[186:189], v138 offset:3072
	s_add_u32 s14, s0, 0xfffc0080
	s_addc_u32 s15, s1, -1
	s_and_b64 s[12:13], s[12:13], exec
	s_cselect_b32 s15, s11, s15
	s_cselect_b32 s14, s47, s14
	s_cselect_b32 s13, s45, s55
	s_cselect_b32 s12, vcc_lo, vcc_hi
	v_lshl_add_u64 v[138:139], s[0:1], 0, v[166:167]
	s_add_i32 m0, s25, 0xc000
	ds_read_b128 v[190:193], v213
	ds_read_b128 v[194:197], v213 offset:1024
	ds_read_b128 v[198:201], v213 offset:2048
	ds_read_b128 v[202:205], v213 offset:3072
	ds_read_b128 v[218:221], v213 offset:4096
	ds_read_b128 v[222:225], v213 offset:5120
	ds_read_b128 v[226:229], v213 offset:6144
	ds_read_b128 v[230:233], v213 offset:7168
	global_load_lds_dwordx4 v[138:139], off
	v_lshl_add_u64 v[138:139], s[0:1], 0, v[168:169]
	s_add_i32 m0, s25, 0xe000
	s_nop 0
	global_load_lds_dwordx4 v[138:139], off
	s_waitcnt lgkmcnt(8)
	s_barrier
	s_waitcnt lgkmcnt(0)
	s_setprio 1
	v_mfma_f32_16x16x32_bf16 v[124:127], v[130:133], v[190:193], v[124:127]
	v_mfma_f32_16x16x32_bf16 v[120:123], v[182:185], v[190:193], v[120:123]
	v_mfma_f32_16x16x32_bf16 v[108:111], v[130:133], v[198:201], v[108:111]
	v_mfma_f32_16x16x32_bf16 v[104:107], v[182:185], v[198:201], v[104:107]
	v_mfma_f32_16x16x32_bf16 v[92:95], v[130:133], v[218:221], v[92:95]
	v_mfma_f32_16x16x32_bf16 v[88:91], v[182:185], v[218:221], v[88:91]
	v_mfma_f32_16x16x32_bf16 v[76:79], v[130:133], v[226:229], v[76:79]
	v_mfma_f32_16x16x32_bf16 v[72:75], v[182:185], v[226:229], v[72:75]
	v_mfma_f32_16x16x32_bf16 v[124:127], v[134:137], v[194:197], v[124:127]
	v_mfma_f32_16x16x32_bf16 v[120:123], v[186:189], v[194:197], v[120:123]
	v_mfma_f32_16x16x32_bf16 v[108:111], v[134:137], v[202:205], v[108:111]
	v_mfma_f32_16x16x32_bf16 v[104:107], v[186:189], v[202:205], v[104:107]
	v_mfma_f32_16x16x32_bf16 v[92:95], v[134:137], v[222:225], v[92:95]
	v_mfma_f32_16x16x32_bf16 v[88:91], v[186:189], v[222:225], v[88:91]
	v_mfma_f32_16x16x32_bf16 v[76:79], v[134:137], v[230:233], v[76:79]
	v_mfma_f32_16x16x32_bf16 v[72:75], v[186:189], v[230:233], v[72:75]
	s_setprio 0
	s_barrier
	v_add_u32_e32 v138, s74, v159
	s_add_i32 s30, s73, s24
	ds_read_b128 v[234:237], v138
	ds_read_b128 v[238:241], v138 offset:1024
	ds_read_b128 v[242:245], v138 offset:2048
	ds_read_b128 v[246:249], v138 offset:3072
	v_lshl_add_u64 v[138:139], s[12:13], 0, v[142:143]
	s_mov_b32 m0, s30
	v_lshl_add_u64 v[206:207], s[12:13], 0, v[146:147]
	global_load_lds_dwordx4 v[138:139], off
	s_add_i32 m0, s30, 0x2000
	s_nop 0
	global_load_lds_dwordx4 v[206:207], off
	s_barrier
	s_waitcnt lgkmcnt(0)
	s_setprio 1
	v_mfma_f32_16x16x32_bf16 v[116:119], v[234:237], v[190:193], v[116:119]
	v_mfma_f32_16x16x32_bf16 v[112:115], v[242:245], v[190:193], v[112:115]
	v_mfma_f32_16x16x32_bf16 v[100:103], v[234:237], v[198:201], v[100:103]
	v_mfma_f32_16x16x32_bf16 v[96:99], v[242:245], v[198:201], v[96:99]
	v_mfma_f32_16x16x32_bf16 v[84:87], v[234:237], v[218:221], v[84:87]
	v_mfma_f32_16x16x32_bf16 v[80:83], v[242:245], v[218:221], v[80:83]
	v_mfma_f32_16x16x32_bf16 v[68:71], v[234:237], v[226:229], v[68:71]
	v_mfma_f32_16x16x32_bf16 v[64:67], v[242:245], v[226:229], v[64:67]
	v_mfma_f32_16x16x32_bf16 v[116:119], v[238:241], v[194:197], v[116:119]
	v_mfma_f32_16x16x32_bf16 v[112:115], v[246:249], v[194:197], v[112:115]
	v_mfma_f32_16x16x32_bf16 v[100:103], v[238:241], v[202:205], v[100:103]
	v_mfma_f32_16x16x32_bf16 v[96:99], v[246:249], v[202:205], v[96:99]
	v_mfma_f32_16x16x32_bf16 v[84:87], v[238:241], v[222:225], v[84:87]
	v_mfma_f32_16x16x32_bf16 v[80:83], v[246:249], v[222:225], v[80:83]
	v_mfma_f32_16x16x32_bf16 v[68:71], v[238:241], v[230:233], v[68:71]
	v_mfma_f32_16x16x32_bf16 v[64:67], v[246:249], v[230:233], v[64:67]
	s_setprio 0
	s_mov_b32 m0, s25
	v_lshl_add_u64 v[250:251], s[14:15], 0, v[140:141]
	s_barrier
	ds_read_b128 v[190:193], v213 offset:16384
	ds_read_b128 v[194:197], v213 offset:17408
	ds_read_b128 v[198:201], v213 offset:18432
	ds_read_b128 v[202:205], v213 offset:19456
	ds_read_b128 v[218:221], v213 offset:20480
	ds_read_b128 v[222:225], v213 offset:21504
	ds_read_b128 v[226:229], v213 offset:22528
	ds_read_b128 v[230:233], v213 offset:23552
	global_load_lds_dwordx4 v[250:251], off
	v_lshl_add_u64 v[252:253], s[14:15], 0, v[144:145]
	s_mov_b32 m0, s27
	s_nop 0
	global_load_lds_dwordx4 v[252:253], off
	s_barrier
	s_waitcnt lgkmcnt(0)
	s_setprio 1
	v_mfma_f32_16x16x32_bf16 v[60:63], v[130:133], v[190:193], v[60:63]
	v_mfma_f32_16x16x32_bf16 v[56:59], v[182:185], v[190:193], v[56:59]
	v_mfma_f32_16x16x32_bf16 v[44:47], v[130:133], v[198:201], v[44:47]
	v_mfma_f32_16x16x32_bf16 v[40:43], v[182:185], v[198:201], v[40:43]
	v_mfma_f32_16x16x32_bf16 v[28:31], v[130:133], v[218:221], v[28:31]
	v_mfma_f32_16x16x32_bf16 v[24:27], v[182:185], v[218:221], v[24:27]
	v_mfma_f32_16x16x32_bf16 v[12:15], v[130:133], v[226:229], v[12:15]
	v_mfma_f32_16x16x32_bf16 v[8:11], v[182:185], v[226:229], v[8:11]
	v_mfma_f32_16x16x32_bf16 v[60:63], v[134:137], v[194:197], v[60:63]
	v_mfma_f32_16x16x32_bf16 v[56:59], v[186:189], v[194:197], v[56:59]
	v_mfma_f32_16x16x32_bf16 v[44:47], v[134:137], v[202:205], v[44:47]
	v_mfma_f32_16x16x32_bf16 v[40:43], v[186:189], v[202:205], v[40:43]
	v_mfma_f32_16x16x32_bf16 v[28:31], v[134:137], v[222:225], v[28:31]
	v_mfma_f32_16x16x32_bf16 v[24:27], v[186:189], v[222:225], v[24:27]
	v_mfma_f32_16x16x32_bf16 v[12:15], v[134:137], v[230:233], v[12:15]
	v_mfma_f32_16x16x32_bf16 v[8:11], v[186:189], v[230:233], v[8:11]
	s_setprio 0
	s_barrier
; #define PG8_STAGE(bufoff, gbase, voff) do { _Pragma("unroll") for (int _i = 0; _i < 2; ++_i) \
;         __builtin_amdgcn_global_load_lds((const unsigned*)((const char*)(gbase) + (voff)[_i]), (PG8_LAS unsigned*)(lds + (bufoff) + ldsw + _i * 8192), 16, 0, 0); } while (0)
; #define PG8_LDA(dst, b, h) do { _Pragma("unroll") for (int m = 0; m < 4; ++m) _Pragma("unroll") for (int k = 0; k < 2; ++k) dst[m][k] = *(const PG8_LAS bf16x8*)(lds + PG8_SA(b, h) + aoff + m * 2048 + k * 1024); } while (0)
; #define PG8_LDB(dst, b, h) do { _Pragma("unroll") for (int n = 0; n < 2; ++n) _Pragma("unroll") for (int k = 0; k < 2; ++k) dst[n][k] = *(const PG8_LAS bf16x8*)(lds + PG8_SB(b, h) + boff + n * 2048 + k * 1024); } while (0)
; #define PG8_MMA(ai, bj, At, Bt) do { __builtin_amdgcn_s_setprio(1); _Pragma("unroll") for (int m = 0; m < 4; ++m) _Pragma("unroll") for (int n = 0; n < 2; ++n) _Pragma("unroll") for (int k = 0; k < 2; ++k) \
;         acc[ai][bj][m][n] = __builtin_amdgcn_mfma_f32_16x16x32_bf16(Bt[n][k], At[m][k], acc[ai][bj][m][n], 0, 0, 0); __builtin_amdgcn_s_setprio(0); } while (0)
; #define PG8_WAIT_V(n) asm volatile("s_waitcnt vmcnt(" #n ")" ::: "memory")
; #define PG8_WAIT_L(n) asm volatile("s_waitcnt lgkmcnt(" #n ")" ::: "memory")
; #define PG8_BAR __builtin_amdgcn_s_barrier()
; #define PG8_SCHED __builtin_amdgcn_sched_barrier(0)
; template <class Epi, class Sched>
; __device__ __forceinline__ void gemm_phase(PG8_LAS unsigned char* lds, const Gemm g, const Sched& S, const Epi& E) {
;     ...
;             PG8_STAGE(PG8_SB(0, 1), b2 + hstep, voffB);
;             PG8_WAIT_V(6); PG8_BAR; PG8_MMA(1, 1, At, B1); PG8_BAR;
;             PG8_LDB(B0, 1, 0); PG8_SCHED; PG8_LDA(At, 1, 0); PG8_STAGE(PG8_SA(0, 1), a2 + hstep, voffA);
;             PG8_WAIT_L(8); PG8_BAR; PG8_WAIT_L(0); PG8_MMA(0, 0, At, B0); PG8_BAR; PG8_SCHED;
;             PG8_LDB(B1, 1, 1); PG8_STAGE(PG8_SB(1, 0), b3, voffB);
	s_add_u32 s96, s12, 0x40000
	s_addc_u32 s97, s13, 0
	s_add_i32 s30, s74, s24
	v_lshl_add_u64 v[130:131], s[96:97], 0, v[142:143]
	s_mov_b32 m0, s30
	s_nop 0
	global_load_lds_dwordx4 v[130:131], off
	v_lshl_add_u64 v[130:131], s[96:97], 0, v[146:147]
	s_add_i32 m0, s30, 0x2000
	s_nop 0
	global_load_lds_dwordx4 v[130:131], off
	s_waitcnt vmcnt(6)
	s_barrier
	s_setprio 1
	v_mfma_f32_16x16x32_bf16 v[52:55], v[234:237], v[190:193], v[52:55]
	v_mfma_f32_16x16x32_bf16 v[48:51], v[242:245], v[190:193], v[48:51]
	v_mfma_f32_16x16x32_bf16 v[36:39], v[234:237], v[198:201], v[36:39]
	v_mfma_f32_16x16x32_bf16 v[32:35], v[242:245], v[198:201], v[32:35]
	v_mfma_f32_16x16x32_bf16 v[20:23], v[234:237], v[218:221], v[20:23]
	v_mfma_f32_16x16x32_bf16 v[16:19], v[242:245], v[218:221], v[16:19]
	v_mfma_f32_16x16x32_bf16 v[4:7], v[234:237], v[226:229], v[4:7]
	v_mfma_f32_16x16x32_bf16 v[0:3], v[242:245], v[226:229], v[0:3]
	v_mfma_f32_16x16x32_bf16 v[52:55], v[238:241], v[194:197], v[52:55]
	v_mfma_f32_16x16x32_bf16 v[48:51], v[246:249], v[194:197], v[48:51]
	v_mfma_f32_16x16x32_bf16 v[36:39], v[238:241], v[202:205], v[36:39]
	v_mfma_f32_16x16x32_bf16 v[32:35], v[246:249], v[202:205], v[32:35]
	v_mfma_f32_16x16x32_bf16 v[20:23], v[238:241], v[222:225], v[20:23]
	v_mfma_f32_16x16x32_bf16 v[16:19], v[246:249], v[222:225], v[16:19]
	v_mfma_f32_16x16x32_bf16 v[4:7], v[238:241], v[230:233], v[4:7]
	v_mfma_f32_16x16x32_bf16 v[0:3], v[246:249], v[230:233], v[0:3]
	s_setprio 0
	s_add_i32 s30, 0, 0x18000
	v_add_u32_e32 v148, s30, v159
	s_barrier
	ds_read_b128 v[130:133], v148
	ds_read_b128 v[134:137], v148 offset:1024
	ds_read_b128 v[182:185], v148 offset:2048
	ds_read_b128 v[186:189], v148 offset:3072
	s_add_u32 s14, s14, 0x40000
	s_addc_u32 s15, s15, 0
	s_mov_b32 m0, s29
	v_lshl_add_u64 v[234:235], s[14:15], 0, v[140:141]
	ds_read_b128 v[190:193], v213 offset:32768
	ds_read_b128 v[194:197], v213 offset:33792
	ds_read_b128 v[198:201], v213 offset:34816
	ds_read_b128 v[202:205], v213 offset:35840
	ds_read_b128 v[218:221], v213 offset:36864
	ds_read_b128 v[222:225], v213 offset:37888
	ds_read_b128 v[226:229], v213 offset:38912
	ds_read_b128 v[230:233], v213 offset:39936
	global_load_lds_dwordx4 v[234:235], off
	v_lshl_add_u64 v[234:235], s[14:15], 0, v[144:145]
	s_mov_b32 m0, s33
	s_nop 0
	global_load_lds_dwordx4 v[234:235], off
	s_waitcnt lgkmcnt(8)
	s_barrier
	s_waitcnt lgkmcnt(0)
	s_setprio 1
	v_mfma_f32_16x16x32_bf16 v[124:127], v[130:133], v[190:193], v[124:127]
	v_mfma_f32_16x16x32_bf16 v[120:123], v[182:185], v[190:193], v[120:123]
	v_mfma_f32_16x16x32_bf16 v[108:111], v[130:133], v[198:201], v[108:111]
	v_mfma_f32_16x16x32_bf16 v[104:107], v[182:185], v[198:201], v[104:107]
	v_mfma_f32_16x16x32_bf16 v[92:95], v[130:133], v[218:221], v[92:95]
	v_mfma_f32_16x16x32_bf16 v[88:91], v[182:185], v[218:221], v[88:91]
	v_mfma_f32_16x16x32_bf16 v[76:79], v[130:133], v[226:229], v[76:79]
	v_mfma_f32_16x16x32_bf16 v[72:75], v[182:185], v[226:229], v[72:75]
	v_mfma_f32_16x16x32_bf16 v[124:127], v[134:137], v[194:197], v[124:127]
	v_mfma_f32_16x16x32_bf16 v[120:123], v[186:189], v[194:197], v[120:123]
	v_mfma_f32_16x16x32_bf16 v[108:111], v[134:137], v[202:205], v[108:111]
	v_mfma_f32_16x16x32_bf16 v[104:107], v[186:189], v[202:205], v[104:107]
	v_mfma_f32_16x16x32_bf16 v[92:95], v[134:137], v[222:225], v[92:95]
	v_mfma_f32_16x16x32_bf16 v[88:91], v[186:189], v[222:225], v[88:91]
	v_mfma_f32_16x16x32_bf16 v[76:79], v[134:137], v[230:233], v[76:79]
	v_mfma_f32_16x16x32_bf16 v[72:75], v[186:189], v[230:233], v[72:75]
	s_setprio 0
	s_barrier
	s_add_i32 s14, 0, 0x1c000
	s_add_i32 s15, s30, s24
	v_add_u32_e32 v148, s14, v159
	v_lshl_add_u64 v[138:139], v[138:139], 0, s[20:21]
	s_mov_b32 m0, s15
	ds_read_b128 v[234:237], v148
	ds_read_b128 v[238:241], v148 offset:1024
	ds_read_b128 v[242:245], v148 offset:2048
	ds_read_b128 v[246:249], v148 offset:3072
	global_load_lds_dwordx4 v[138:139], off
	v_lshl_add_u64 v[138:139], v[206:207], 0, s[20:21]
	s_add_i32 m0, s15, 0x2000
	s_nop 0
	global_load_lds_dwordx4 v[138:139], off
	s_barrier
; #define PG8_STAGE(bufoff, gbase, voff) do { _Pragma("unroll") for (int _i = 0; _i < 2; ++_i) \
;         __builtin_amdgcn_global_load_lds((const unsigned*)((const char*)(gbase) + (voff)[_i]), (PG8_LAS unsigned*)(lds + (bufoff) + ldsw + _i * 8192), 16, 0, 0); } while (0)
; #define PG8_LDA(dst, b, h) do { _Pragma("unroll") for (int m = 0; m < 4; ++m) _Pragma("unroll") for (int k = 0; k < 2; ++k) dst[m][k] = *(const PG8_LAS bf16x8*)(lds + PG8_SA(b, h) + aoff + m * 2048 + k * 1024); } while (0)
; #define PG8_MMA(ai, bj, At, Bt) do { __builtin_amdgcn_s_setprio(1); _Pragma("unroll") for (int m = 0; m < 4; ++m) _Pragma("unroll") for (int n = 0; n < 2; ++n) _Pragma("unroll") for (int k = 0; k < 2; ++k) \
;         acc[ai][bj][m][n] = __builtin_amdgcn_mfma_f32_16x16x32_bf16(Bt[n][k], At[m][k], acc[ai][bj][m][n], 0, 0, 0); __builtin_amdgcn_s_setprio(0); } while (0)
; #define PG8_WAIT_V(n) asm volatile("s_waitcnt vmcnt(" #n ")" ::: "memory")
; #define PG8_WAIT_L(n) asm volatile("s_waitcnt lgkmcnt(" #n ")" ::: "memory")
; #define PG8_BAR __builtin_amdgcn_s_barrier()
; #define PG8_SCHED __builtin_amdgcn_sched_barrier(0)
; template <class Epi, class Sched>
; __device__ __forceinline__ void gemm_phase(PG8_LAS unsigned char* lds, const Gemm g, const Sched& S, const Epi& E) {
;     ...
;             PG8_BAR; PG8_WAIT_L(0); PG8_MMA(0, 1, At, B1); PG8_BAR;
;             PG8_LDA(At, 1, 1); PG8_STAGE(PG8_SA(1, 0), a3, voffA);
;             PG8_BAR; PG8_WAIT_L(0); PG8_MMA(1, 0, At, B0); PG8_BAR; PG8_SCHED;
;             PG8_STAGE(PG8_SB(1, 1), b3 + hstep, voffB);
;             PG8_WAIT_V(6); PG8_BAR; PG8_MMA(1, 1, At, B1); PG8_BAR;
;         }
	s_waitcnt lgkmcnt(0)
	s_setprio 1
	v_mfma_f32_16x16x32_bf16 v[116:119], v[234:237], v[190:193], v[116:119]
	v_mfma_f32_16x16x32_bf16 v[112:115], v[242:245], v[190:193], v[112:115]
	v_mfma_f32_16x16x32_bf16 v[100:103], v[234:237], v[198:201], v[100:103]
	v_mfma_f32_16x16x32_bf16 v[96:99], v[242:245], v[198:201], v[96:99]
	v_mfma_f32_16x16x32_bf16 v[84:87], v[234:237], v[218:221], v[84:87]
	v_mfma_f32_16x16x32_bf16 v[80:83], v[242:245], v[218:221], v[80:83]
	v_mfma_f32_16x16x32_bf16 v[68:71], v[234:237], v[226:229], v[68:71]
	v_mfma_f32_16x16x32_bf16 v[64:67], v[242:245], v[226:229], v[64:67]
	v_mfma_f32_16x16x32_bf16 v[116:119], v[238:241], v[194:197], v[116:119]
	v_mfma_f32_16x16x32_bf16 v[112:115], v[246:249], v[194:197], v[112:115]
	v_mfma_f32_16x16x32_bf16 v[100:103], v[238:241], v[202:205], v[100:103]
	v_mfma_f32_16x16x32_bf16 v[96:99], v[246:249], v[202:205], v[96:99]
	v_mfma_f32_16x16x32_bf16 v[84:87], v[238:241], v[222:225], v[84:87]
	v_mfma_f32_16x16x32_bf16 v[80:83], v[246:249], v[222:225], v[80:83]
	v_mfma_f32_16x16x32_bf16 v[68:71], v[238:241], v[230:233], v[68:71]
	v_mfma_f32_16x16x32_bf16 v[64:67], v[246:249], v[230:233], v[64:67]
	s_setprio 0
	s_mov_b32 m0, s16
	v_lshl_add_u64 v[138:139], v[250:251], 0, s[20:21]
	s_barrier
	ds_read_b128 v[190:193], v213 offset:49152
	ds_read_b128 v[194:197], v213 offset:50176
	ds_read_b128 v[198:201], v213 offset:51200
	ds_read_b128 v[202:205], v213 offset:52224
	ds_read_b128 v[218:221], v213 offset:53248
	ds_read_b128 v[222:225], v213 offset:54272
	ds_read_b128 v[226:229], v213 offset:55296
	ds_read_b128 v[230:233], v213 offset:56320
	global_load_lds_dwordx4 v[138:139], off
	v_lshl_add_u64 v[138:139], v[252:253], 0, s[20:21]
	s_mov_b32 m0, s17
	s_nop 0
	global_load_lds_dwordx4 v[138:139], off
	s_barrier
	s_waitcnt lgkmcnt(0)
	s_setprio 1
	v_mfma_f32_16x16x32_bf16 v[60:63], v[130:133], v[190:193], v[60:63]
	v_mfma_f32_16x16x32_bf16 v[56:59], v[182:185], v[190:193], v[56:59]
	v_mfma_f32_16x16x32_bf16 v[44:47], v[130:133], v[198:201], v[44:47]
	v_mfma_f32_16x16x32_bf16 v[40:43], v[182:185], v[198:201], v[40:43]
	v_mfma_f32_16x16x32_bf16 v[28:31], v[130:133], v[218:221], v[28:31]
	v_mfma_f32_16x16x32_bf16 v[24:27], v[182:185], v[218:221], v[24:27]
	v_mfma_f32_16x16x32_bf16 v[12:15], v[130:133], v[226:229], v[12:15]
	v_mfma_f32_16x16x32_bf16 v[8:11], v[182:185], v[226:229], v[8:11]
	v_mfma_f32_16x16x32_bf16 v[60:63], v[134:137], v[194:197], v[60:63]
	v_mfma_f32_16x16x32_bf16 v[56:59], v[186:189], v[194:197], v[56:59]
	v_mfma_f32_16x16x32_bf16 v[44:47], v[134:137], v[202:205], v[44:47]
	v_mfma_f32_16x16x32_bf16 v[40:43], v[186:189], v[202:205], v[40:43]
	v_mfma_f32_16x16x32_bf16 v[28:31], v[134:137], v[222:225], v[28:31]
	v_mfma_f32_16x16x32_bf16 v[24:27], v[186:189], v[222:225], v[24:27]
	v_mfma_f32_16x16x32_bf16 v[12:15], v[134:137], v[230:233], v[12:15]
	v_mfma_f32_16x16x32_bf16 v[8:11], v[186:189], v[230:233], v[8:11]
	s_setprio 0
	s_barrier
	s_add_u32 s12, s12, 0x40080
	s_addc_u32 s13, s13, 0
	s_add_i32 s14, s14, s24
	v_lshl_add_u64 v[130:131], s[12:13], 0, v[142:143]
	s_mov_b32 m0, s14
	s_nop 0
	global_load_lds_dwordx4 v[130:131], off
	v_lshl_add_u64 v[130:131], s[12:13], 0, v[146:147]
	s_add_i32 m0, s14, 0x2000
	s_nop 0
	global_load_lds_dwordx4 v[130:131], off
	s_waitcnt vmcnt(6)
	s_barrier
	s_setprio 1
	v_mfma_f32_16x16x32_bf16 v[52:55], v[234:237], v[190:193], v[52:55]
	v_mfma_f32_16x16x32_bf16 v[48:51], v[242:245], v[190:193], v[48:51]
	v_mfma_f32_16x16x32_bf16 v[36:39], v[234:237], v[198:201], v[36:39]
	v_mfma_f32_16x16x32_bf16 v[32:35], v[242:245], v[198:201], v[32:35]
	v_mfma_f32_16x16x32_bf16 v[20:23], v[234:237], v[218:221], v[20:23]
	v_mfma_f32_16x16x32_bf16 v[16:19], v[242:245], v[218:221], v[16:19]
	v_mfma_f32_16x16x32_bf16 v[4:7], v[234:237], v[226:229], v[4:7]
	v_mfma_f32_16x16x32_bf16 v[0:3], v[242:245], v[226:229], v[0:3]
	v_mfma_f32_16x16x32_bf16 v[52:55], v[238:241], v[194:197], v[52:55]
	v_mfma_f32_16x16x32_bf16 v[48:51], v[246:249], v[194:197], v[48:51]
	v_mfma_f32_16x16x32_bf16 v[36:39], v[238:241], v[202:205], v[36:39]
	v_mfma_f32_16x16x32_bf16 v[32:35], v[246:249], v[202:205], v[32:35]
	v_mfma_f32_16x16x32_bf16 v[20:23], v[238:241], v[222:225], v[20:23]
	v_mfma_f32_16x16x32_bf16 v[16:19], v[246:249], v[222:225], v[16:19]
	v_mfma_f32_16x16x32_bf16 v[4:7], v[238:241], v[230:233], v[4:7]
	v_mfma_f32_16x16x32_bf16 v[0:3], v[246:249], v[230:233], v[0:3]
	s_setprio 0
	s_add_i32 s5, s5, 2
	s_add_u32 s0, s0, 0x100
	s_addc_u32 s1, s1, 0
	s_add_u32 vcc_hi, vcc_hi, 0x100
	s_addc_u32 s55, s55, 0
	s_cmp_lt_u32 s5, 14
	s_barrier
	s_cbranch_scc0 .LBB0_1850

; #define PG8_STAGE(bufoff, gbase, voff) do { _Pragma("unroll") for (int _i = 0; _i < 2; ++_i) \
;         __builtin_amdgcn_global_load_lds((const unsigned*)((const char*)(gbase) + (voff)[_i]), (PG8_LAS unsigned*)(lds + (bufoff) + ldsw + _i * 8192), 16, 0, 0); } while (0)
; #define PG8_LDA(dst, b, h) do { _Pragma("unroll") for (int m = 0; m < 4; ++m) _Pragma("unroll") for (int k = 0; k < 2; ++k) dst[m][k] = *(const PG8_LAS bf16x8*)(lds + PG8_SA(b, h) + aoff + m * 2048 + k * 1024); } while (0)
; #define PG8_LDB(dst, b, h) do { _Pragma("unroll") for (int n = 0; n < 2; ++n) _Pragma("unroll") for (int k = 0; k < 2; ++k) dst[n][k] = *(const PG8_LAS bf16x8*)(lds + PG8_SB(b, h) + boff + n * 2048 + k * 1024); } while (0)
; #define PG8_MMA(ai, bj, At, Bt) do { __builtin_amdgcn_s_setprio(1); _Pragma("unroll") for (int m = 0; m < 4; ++m) _Pragma("unroll") for (int n = 0; n < 2; ++n) _Pragma("unroll") for (int k = 0; k < 2; ++k) \
;         acc[ai][bj][m][n] = __builtin_amdgcn_mfma_f32_16x16x32_bf16(Bt[n][k], At[m][k], acc[ai][bj][m][n], 0, 0, 0); __builtin_amdgcn_s_setprio(0); } while (0)
; #define PG8_WAIT_L(n) asm volatile("s_waitcnt lgkmcnt(" #n ")" ::: "memory")
; #define PG8_BAR __builtin_amdgcn_s_barrier()
; #define PG8_SCHED __builtin_amdgcn_sched_barrier(0)
; template <class Epi, class Sched>
; __device__ __forceinline__ void gemm_phase(PG8_LAS unsigned char* lds, const Gemm g, const Sched& S, const Epi& E) {
;     ...
;             const bool last = (t == cnk - 2);
;             const char* a1 = cA + (size_t)(t + 1) * kstep;
;             const char* a2 = last ? nA : cA + (size_t)(t + 2) * kstep; const char* b2 = last ? nB : cB + (size_t)(t + 2) * kstep;
;             const char* a3 = a2 + kstep; const char* b3 = b2 + kstep;
;             if (last && has_next) S.a_ready(nxt);
;             if (last) E.prefetch(pre, cur, wr, fr);
;             PG8_LDB(B0, 0, 0); PG8_SCHED; PG8_LDA(At, 0, 0); PG8_STAGE(PG8_SA(1, 1), a1 + hstep, voffA);
;             PG8_WAIT_L(8); PG8_BAR; PG8_WAIT_L(0); PG8_MMA(0, 0, At, B0); PG8_BAR; PG8_SCHED;
;             PG8_LDB(B1, 0, 1); PG8_STAGE(PG8_SB(0, 0), b2, voffB);
;             PG8_BAR; PG8_WAIT_L(0); PG8_MMA(0, 1, At, B1); PG8_BAR;
;             PG8_LDA(At, 0, 1); PG8_STAGE(PG8_SA(0, 0), a2, voffA);
;             PG8_BAR; PG8_WAIT_L(0); PG8_MMA(1, 0, At, B0); PG8_BAR; PG8_SCHED;
.LBB0_2251:
	ds_read_b128 v[128:131], v192
	ds_read_b128 v[132:135], v192 offset:1024
	ds_read_b128 v[136:139], v192 offset:2048
	ds_read_b128 v[140:143], v192 offset:3072
	s_add_i32 s70, s43, 2
	s_add_u32 s30, s46, 0xfffc0080
	s_addc_u32 s48, s47, -1
	s_cmp_eq_u32 s25, s43
	s_cselect_b32 s51, s41, s48
	s_cselect_b32 s50, s40, s30
	s_cselect_b32 s49, s45, s37
	s_cselect_b32 s48, s44, s27
	v_lshl_add_u64 v[190:191], s[46:47], 0, v[168:169]
	s_add_i32 m0, s5, 0xc000
	ds_read_b128 v[144:147], v193
	ds_read_b128 v[148:151], v193 offset:1024
	ds_read_b128 v[174:177], v193 offset:2048
	ds_read_b128 v[178:181], v193 offset:3072
	ds_read_b128 v[182:185], v193 offset:4096
	ds_read_b128 v[186:189], v193 offset:5120
	ds_read_b128 v[196:199], v193 offset:6144
	ds_read_b128 v[200:203], v193 offset:7168
	global_load_lds_dwordx4 v[190:191], off
	v_lshl_add_u64 v[190:191], s[46:47], 0, v[170:171]
	s_add_i32 m0, s5, 0xe000
	s_nop 0
	global_load_lds_dwordx4 v[190:191], off
	s_waitcnt lgkmcnt(8)
	s_barrier
	s_waitcnt lgkmcnt(0)
	s_setprio 1
	v_mfma_f32_16x16x32_bf16 v[124:127], v[128:131], v[144:147], v[124:127]
	v_mfma_f32_16x16x32_bf16 v[120:123], v[136:139], v[144:147], v[120:123]
	v_mfma_f32_16x16x32_bf16 v[108:111], v[128:131], v[174:177], v[108:111]
	v_mfma_f32_16x16x32_bf16 v[104:107], v[136:139], v[174:177], v[104:107]
	v_mfma_f32_16x16x32_bf16 v[92:95], v[128:131], v[182:185], v[92:95]
	v_mfma_f32_16x16x32_bf16 v[88:91], v[136:139], v[182:185], v[88:91]
	v_mfma_f32_16x16x32_bf16 v[76:79], v[128:131], v[196:199], v[76:79]
	v_mfma_f32_16x16x32_bf16 v[72:75], v[136:139], v[196:199], v[72:75]
	v_mfma_f32_16x16x32_bf16 v[124:127], v[132:135], v[148:151], v[124:127]
	v_mfma_f32_16x16x32_bf16 v[120:123], v[140:143], v[148:151], v[120:123]
	v_mfma_f32_16x16x32_bf16 v[108:111], v[132:135], v[178:181], v[108:111]
	v_mfma_f32_16x16x32_bf16 v[104:107], v[140:143], v[178:181], v[104:107]
	v_mfma_f32_16x16x32_bf16 v[92:95], v[132:135], v[186:189], v[92:95]
	v_mfma_f32_16x16x32_bf16 v[88:91], v[140:143], v[186:189], v[88:91]
	v_mfma_f32_16x16x32_bf16 v[76:79], v[132:135], v[200:203], v[76:79]
	v_mfma_f32_16x16x32_bf16 v[72:75], v[140:143], v[200:203], v[72:75]
	s_setprio 0
	s_barrier
	s_add_i32 s30, s53, s4
	v_lshl_add_u64 v[190:191], s[48:49], 0, v[160:161]
	s_mov_b32 m0, s30
	ds_read_b128 v[204:207], v194
	ds_read_b128 v[208:211], v194 offset:1024
	ds_read_b128 v[212:215], v194 offset:2048
	ds_read_b128 v[216:219], v194 offset:3072
	global_load_lds_dwordx4 v[190:191], off
	v_lshl_add_u64 v[220:221], s[48:49], 0, v[164:165]
	s_add_i32 m0, s30, 0x2000
	s_nop 0
	global_load_lds_dwordx4 v[220:221], off
	s_barrier
	s_waitcnt lgkmcnt(0)
	s_setprio 1
	v_mfma_f32_16x16x32_bf16 v[116:119], v[204:207], v[144:147], v[116:119]
	v_mfma_f32_16x16x32_bf16 v[112:115], v[212:215], v[144:147], v[112:115]
	v_mfma_f32_16x16x32_bf16 v[100:103], v[204:207], v[174:177], v[100:103]
	v_mfma_f32_16x16x32_bf16 v[96:99], v[212:215], v[174:177], v[96:99]
	v_mfma_f32_16x16x32_bf16 v[84:87], v[204:207], v[182:185], v[84:87]
	v_mfma_f32_16x16x32_bf16 v[80:83], v[212:215], v[182:185], v[80:83]
	v_mfma_f32_16x16x32_bf16 v[68:71], v[204:207], v[196:199], v[68:71]
	v_mfma_f32_16x16x32_bf16 v[64:67], v[212:215], v[196:199], v[64:67]
	v_mfma_f32_16x16x32_bf16 v[116:119], v[208:211], v[148:151], v[116:119]
	v_mfma_f32_16x16x32_bf16 v[112:115], v[216:219], v[148:151], v[112:115]
	v_mfma_f32_16x16x32_bf16 v[100:103], v[208:211], v[178:181], v[100:103]
	v_mfma_f32_16x16x32_bf16 v[96:99], v[216:219], v[178:181], v[96:99]
	v_mfma_f32_16x16x32_bf16 v[84:87], v[208:211], v[186:189], v[84:87]
	v_mfma_f32_16x16x32_bf16 v[80:83], v[216:219], v[186:189], v[80:83]
	v_mfma_f32_16x16x32_bf16 v[68:71], v[208:211], v[200:203], v[68:71]
	v_mfma_f32_16x16x32_bf16 v[64:67], v[216:219], v[200:203], v[64:67]
	s_setprio 0
	s_mov_b32 m0, s5
	v_lshl_add_u64 v[222:223], s[50:51], 0, v[158:159]
	s_barrier
	ds_read_b128 v[144:147], v193 offset:16384
	ds_read_b128 v[148:151], v193 offset:17408
	ds_read_b128 v[174:177], v193 offset:18432
	ds_read_b128 v[178:181], v193 offset:19456
	ds_read_b128 v[182:185], v193 offset:20480
	ds_read_b128 v[186:189], v193 offset:21504
	ds_read_b128 v[196:199], v193 offset:22528
	ds_read_b128 v[200:203], v193 offset:23552
	global_load_lds_dwordx4 v[222:223], off
	v_lshl_add_u64 v[224:225], s[50:51], 0, v[162:163]
	s_mov_b32 m0, s6
	s_nop 0
	global_load_lds_dwordx4 v[224:225], off
	s_barrier
	s_waitcnt lgkmcnt(0)
	s_setprio 1
	v_mfma_f32_16x16x32_bf16 v[60:63], v[128:131], v[144:147], v[60:63]
	v_mfma_f32_16x16x32_bf16 v[56:59], v[136:139], v[144:147], v[56:59]
	v_mfma_f32_16x16x32_bf16 v[44:47], v[128:131], v[174:177], v[44:47]
	v_mfma_f32_16x16x32_bf16 v[40:43], v[136:139], v[174:177], v[40:43]
	v_mfma_f32_16x16x32_bf16 v[28:31], v[128:131], v[182:185], v[28:31]
	v_mfma_f32_16x16x32_bf16 v[24:27], v[136:139], v[182:185], v[24:27]
	v_mfma_f32_16x16x32_bf16 v[12:15], v[128:131], v[196:199], v[12:15]
	v_mfma_f32_16x16x32_bf16 v[8:11], v[136:139], v[196:199], v[8:11]
	v_mfma_f32_16x16x32_bf16 v[60:63], v[132:135], v[148:151], v[60:63]
	v_mfma_f32_16x16x32_bf16 v[56:59], v[140:143], v[148:151], v[56:59]
	v_mfma_f32_16x16x32_bf16 v[44:47], v[132:135], v[178:181], v[44:47]
	v_mfma_f32_16x16x32_bf16 v[40:43], v[140:143], v[178:181], v[40:43]
	v_mfma_f32_16x16x32_bf16 v[28:31], v[132:135], v[186:189], v[28:31]
	v_mfma_f32_16x16x32_bf16 v[24:27], v[140:143], v[186:189], v[24:27]
	v_mfma_f32_16x16x32_bf16 v[12:15], v[132:135], v[200:203], v[12:15]
	v_mfma_f32_16x16x32_bf16 v[8:11], v[140:143], v[200:203], v[8:11]
	s_setprio 0
	s_barrier
; #define PG8_STAGE(bufoff, gbase, voff) do { _Pragma("unroll") for (int _i = 0; _i < 2; ++_i) \
;         __builtin_amdgcn_global_load_lds((const unsigned*)((const char*)(gbase) + (voff)[_i]), (PG8_LAS unsigned*)(lds + (bufoff) + ldsw + _i * 8192), 16, 0, 0); } while (0)
; #define PG8_LDA(dst, b, h) do { _Pragma("unroll") for (int m = 0; m < 4; ++m) _Pragma("unroll") for (int k = 0; k < 2; ++k) dst[m][k] = *(const PG8_LAS bf16x8*)(lds + PG8_SA(b, h) + aoff + m * 2048 + k * 1024); } while (0)
; #define PG8_LDB(dst, b, h) do { _Pragma("unroll") for (int n = 0; n < 2; ++n) _Pragma("unroll") for (int k = 0; k < 2; ++k) dst[n][k] = *(const PG8_LAS bf16x8*)(lds + PG8_SB(b, h) + boff + n * 2048 + k * 1024); } while (0)
; #define PG8_MMA(ai, bj, At, Bt) do { __builtin_amdgcn_s_setprio(1); _Pragma("unroll") for (int m = 0; m < 4; ++m) _Pragma("unroll") for (int n = 0; n < 2; ++n) _Pragma("unroll") for (int k = 0; k < 2; ++k) \
;         acc[ai][bj][m][n] = __builtin_amdgcn_mfma_f32_16x16x32_bf16(Bt[n][k], At[m][k], acc[ai][bj][m][n], 0, 0, 0); __builtin_amdgcn_s_setprio(0); } while (0)
; #define PG8_WAIT_V(n) asm volatile("s_waitcnt vmcnt(" #n ")" ::: "memory")
; #define PG8_WAIT_L(n) asm volatile("s_waitcnt lgkmcnt(" #n ")" ::: "memory")
; #define PG8_BAR __builtin_amdgcn_s_barrier()
; #define PG8_SCHED __builtin_amdgcn_sched_barrier(0)
; template <class Epi, class Sched>
; __device__ __forceinline__ void gemm_phase(PG8_LAS unsigned char* lds, const Gemm g, const Sched& S, const Epi& E) {
;     ...
;             PG8_STAGE(PG8_SB(0, 1), b2 + hstep, voffB);
;             PG8_WAIT_V(6); PG8_BAR; PG8_MMA(1, 1, At, B1); PG8_BAR;
;             PG8_LDB(B0, 1, 0); PG8_SCHED; PG8_LDA(At, 1, 0); PG8_STAGE(PG8_SA(0, 1), a2 + hstep, voffA);
;             PG8_WAIT_L(8); PG8_BAR; PG8_WAIT_L(0); PG8_MMA(0, 0, At, B0); PG8_BAR; PG8_SCHED;
;             PG8_LDB(B1, 1, 1); PG8_STAGE(PG8_SB(1, 0), b3, voffB);
	s_add_u32 s72, s48, 0x40000
	s_addc_u32 s73, s49, 0
	s_add_i32 s30, s54, s4
	v_lshl_add_u64 v[128:129], s[72:73], 0, v[160:161]
	s_mov_b32 m0, s30
	s_nop 0
	global_load_lds_dwordx4 v[128:129], off
	v_lshl_add_u64 v[128:129], s[72:73], 0, v[164:165]
	s_add_i32 m0, s30, 0x2000
	s_nop 0
	global_load_lds_dwordx4 v[128:129], off
	s_waitcnt vmcnt(6)
	s_barrier
	s_setprio 1
	v_mfma_f32_16x16x32_bf16 v[52:55], v[204:207], v[144:147], v[52:55]
	v_mfma_f32_16x16x32_bf16 v[48:51], v[212:215], v[144:147], v[48:51]
	v_mfma_f32_16x16x32_bf16 v[36:39], v[204:207], v[174:177], v[36:39]
	v_mfma_f32_16x16x32_bf16 v[32:35], v[212:215], v[174:177], v[32:35]
	v_mfma_f32_16x16x32_bf16 v[20:23], v[204:207], v[182:185], v[20:23]
	v_mfma_f32_16x16x32_bf16 v[16:19], v[212:215], v[182:185], v[16:19]
	v_mfma_f32_16x16x32_bf16 v[4:7], v[204:207], v[196:199], v[4:7]
	v_mfma_f32_16x16x32_bf16 v[0:3], v[212:215], v[196:199], v[0:3]
	v_mfma_f32_16x16x32_bf16 v[52:55], v[208:211], v[148:151], v[52:55]
	v_mfma_f32_16x16x32_bf16 v[48:51], v[216:219], v[148:151], v[48:51]
	v_mfma_f32_16x16x32_bf16 v[36:39], v[208:211], v[178:181], v[36:39]
	v_mfma_f32_16x16x32_bf16 v[32:35], v[216:219], v[178:181], v[32:35]
	v_mfma_f32_16x16x32_bf16 v[20:23], v[208:211], v[186:189], v[20:23]
	v_mfma_f32_16x16x32_bf16 v[16:19], v[216:219], v[186:189], v[16:19]
	v_mfma_f32_16x16x32_bf16 v[4:7], v[208:211], v[200:203], v[4:7]
	v_mfma_f32_16x16x32_bf16 v[0:3], v[216:219], v[200:203], v[0:3]
	s_setprio 0
	s_add_i32 s30, 0, 0x18000
	v_add_u32_e32 v140, s30, v155
	s_barrier
	ds_read_b128 v[128:131], v140
	ds_read_b128 v[132:135], v140 offset:1024
	ds_read_b128 v[136:139], v140 offset:2048
	ds_read_b128 v[140:143], v140 offset:3072
	s_add_u32 s50, s50, 0x40000
	s_addc_u32 s51, s51, 0
	s_mov_b32 m0, s7
	v_lshl_add_u64 v[204:205], s[50:51], 0, v[158:159]
	ds_read_b128 v[144:147], v193 offset:32768
	ds_read_b128 v[148:151], v193 offset:33792
	ds_read_b128 v[174:177], v193 offset:34816
	ds_read_b128 v[178:181], v193 offset:35840
	ds_read_b128 v[182:185], v193 offset:36864
	ds_read_b128 v[186:189], v193 offset:37888
	ds_read_b128 v[196:199], v193 offset:38912
	ds_read_b128 v[200:203], v193 offset:39936
	global_load_lds_dwordx4 v[204:205], off
	v_lshl_add_u64 v[204:205], s[50:51], 0, v[162:163]
	s_mov_b32 m0, s16
	s_nop 0
	global_load_lds_dwordx4 v[204:205], off
	s_waitcnt lgkmcnt(8)
	s_barrier
	s_waitcnt lgkmcnt(0)
	s_setprio 1
	v_mfma_f32_16x16x32_bf16 v[124:127], v[128:131], v[144:147], v[124:127]
	v_mfma_f32_16x16x32_bf16 v[120:123], v[136:139], v[144:147], v[120:123]
	v_mfma_f32_16x16x32_bf16 v[108:111], v[128:131], v[174:177], v[108:111]
	v_mfma_f32_16x16x32_bf16 v[104:107], v[136:139], v[174:177], v[104:107]
	v_mfma_f32_16x16x32_bf16 v[92:95], v[128:131], v[182:185], v[92:95]
	v_mfma_f32_16x16x32_bf16 v[88:91], v[136:139], v[182:185], v[88:91]
	v_mfma_f32_16x16x32_bf16 v[76:79], v[128:131], v[196:199], v[76:79]
	v_mfma_f32_16x16x32_bf16 v[72:75], v[136:139], v[196:199], v[72:75]
	v_mfma_f32_16x16x32_bf16 v[124:127], v[132:135], v[148:151], v[124:127]
	v_mfma_f32_16x16x32_bf16 v[120:123], v[140:143], v[148:151], v[120:123]
	v_mfma_f32_16x16x32_bf16 v[108:111], v[132:135], v[178:181], v[108:111]
	v_mfma_f32_16x16x32_bf16 v[104:107], v[140:143], v[178:181], v[104:107]
	v_mfma_f32_16x16x32_bf16 v[92:95], v[132:135], v[186:189], v[92:95]
	v_mfma_f32_16x16x32_bf16 v[88:91], v[140:143], v[186:189], v[88:91]
	v_mfma_f32_16x16x32_bf16 v[76:79], v[132:135], v[200:203], v[76:79]
	v_mfma_f32_16x16x32_bf16 v[72:75], v[140:143], v[200:203], v[72:75]
	s_setprio 0
	s_barrier
	s_add_i32 s43, 0, 0x1c000
	s_add_i32 s30, s30, s4
	v_add_u32_e32 v216, s43, v155
	v_lshl_add_u64 v[190:191], v[190:191], 0, s[14:15]
	s_mov_b32 m0, s30
	ds_read_b128 v[204:207], v216
	ds_read_b128 v[208:211], v216 offset:1024
	ds_read_b128 v[212:215], v216 offset:2048
	ds_read_b128 v[216:219], v216 offset:3072
	global_load_lds_dwordx4 v[190:191], off
	v_lshl_add_u64 v[190:191], v[220:221], 0, s[14:15]
	s_add_i32 m0, s30, 0x2000
	s_nop 0
	global_load_lds_dwordx4 v[190:191], off
	s_barrier
; #define PG8_STAGE(bufoff, gbase, voff) do { _Pragma("unroll") for (int _i = 0; _i < 2; ++_i) \
;         __builtin_amdgcn_global_load_lds((const unsigned*)((const char*)(gbase) + (voff)[_i]), (PG8_LAS unsigned*)(lds + (bufoff) + ldsw + _i * 8192), 16, 0, 0); } while (0)
; #define PG8_LDA(dst, b, h) do { _Pragma("unroll") for (int m = 0; m < 4; ++m) _Pragma("unroll") for (int k = 0; k < 2; ++k) dst[m][k] = *(const PG8_LAS bf16x8*)(lds + PG8_SA(b, h) + aoff + m * 2048 + k * 1024); } while (0)
; #define PG8_MMA(ai, bj, At, Bt) do { __builtin_amdgcn_s_setprio(1); _Pragma("unroll") for (int m = 0; m < 4; ++m) _Pragma("unroll") for (int n = 0; n < 2; ++n) _Pragma("unroll") for (int k = 0; k < 2; ++k) \
;         acc[ai][bj][m][n] = __builtin_amdgcn_mfma_f32_16x16x32_bf16(Bt[n][k], At[m][k], acc[ai][bj][m][n], 0, 0, 0); __builtin_amdgcn_s_setprio(0); } while (0)
; #define PG8_WAIT_V(n) asm volatile("s_waitcnt vmcnt(" #n ")" ::: "memory")
; #define PG8_WAIT_L(n) asm volatile("s_waitcnt lgkmcnt(" #n ")" ::: "memory")
; #define PG8_BAR __builtin_amdgcn_s_barrier()
; #define PG8_SCHED __builtin_amdgcn_sched_barrier(0)
; template <class Epi, class Sched>
; __device__ __forceinline__ void gemm_phase(PG8_LAS unsigned char* lds, const Gemm g, const Sched& S, const Epi& E) {
;     ...
;             PG8_BAR; PG8_WAIT_L(0); PG8_MMA(0, 1, At, B1); PG8_BAR;
;             PG8_LDA(At, 1, 1); PG8_STAGE(PG8_SA(1, 0), a3, voffA);
;             PG8_BAR; PG8_WAIT_L(0); PG8_MMA(1, 0, At, B0); PG8_BAR; PG8_SCHED;
;             PG8_STAGE(PG8_SB(1, 1), b3 + hstep, voffB);
;             PG8_WAIT_V(6); PG8_BAR; PG8_MMA(1, 1, At, B1); PG8_BAR;
;         }
;         if constexpr (!Epi::AFTER_DRAIN) {
;             if (cur.part < 0) E(acc, cur, wr, wc, fr, fq, pre);
;             else { f32x4* pp = (f32x4*)g.part + (size_t)cur.part * 32 * 512 + tid;
	s_waitcnt lgkmcnt(0)
	s_setprio 1
	v_mfma_f32_16x16x32_bf16 v[116:119], v[204:207], v[144:147], v[116:119]
	v_mfma_f32_16x16x32_bf16 v[112:115], v[212:215], v[144:147], v[112:115]
	v_mfma_f32_16x16x32_bf16 v[100:103], v[204:207], v[174:177], v[100:103]
	v_mfma_f32_16x16x32_bf16 v[96:99], v[212:215], v[174:177], v[96:99]
	v_mfma_f32_16x16x32_bf16 v[84:87], v[204:207], v[182:185], v[84:87]
	v_mfma_f32_16x16x32_bf16 v[80:83], v[212:215], v[182:185], v[80:83]
	v_mfma_f32_16x16x32_bf16 v[68:71], v[204:207], v[196:199], v[68:71]
	v_mfma_f32_16x16x32_bf16 v[64:67], v[212:215], v[196:199], v[64:67]
	v_mfma_f32_16x16x32_bf16 v[116:119], v[208:211], v[148:151], v[116:119]
	v_mfma_f32_16x16x32_bf16 v[112:115], v[216:219], v[148:151], v[112:115]
	v_mfma_f32_16x16x32_bf16 v[100:103], v[208:211], v[178:181], v[100:103]
	v_mfma_f32_16x16x32_bf16 v[96:99], v[216:219], v[178:181], v[96:99]
	v_mfma_f32_16x16x32_bf16 v[84:87], v[208:211], v[186:189], v[84:87]
	v_mfma_f32_16x16x32_bf16 v[80:83], v[216:219], v[186:189], v[80:83]
	v_mfma_f32_16x16x32_bf16 v[68:71], v[208:211], v[200:203], v[68:71]
	v_mfma_f32_16x16x32_bf16 v[64:67], v[216:219], v[200:203], v[64:67]
	s_setprio 0
	s_mov_b32 m0, s18
	v_lshl_add_u64 v[190:191], v[222:223], 0, s[14:15]
	s_barrier
	ds_read_b128 v[144:147], v193 offset:49152
	ds_read_b128 v[148:151], v193 offset:50176
	ds_read_b128 v[174:177], v193 offset:51200
	ds_read_b128 v[178:181], v193 offset:52224
	ds_read_b128 v[182:185], v193 offset:53248
	ds_read_b128 v[186:189], v193 offset:54272
	ds_read_b128 v[196:199], v193 offset:55296
	ds_read_b128 v[200:203], v193 offset:56320
	global_load_lds_dwordx4 v[190:191], off
	v_lshl_add_u64 v[190:191], v[224:225], 0, s[14:15]
	s_mov_b32 m0, s19
	s_nop 0
	global_load_lds_dwordx4 v[190:191], off
	s_barrier
	s_waitcnt lgkmcnt(0)
	s_setprio 1
	v_mfma_f32_16x16x32_bf16 v[60:63], v[128:131], v[144:147], v[60:63]
	v_mfma_f32_16x16x32_bf16 v[56:59], v[136:139], v[144:147], v[56:59]
	v_mfma_f32_16x16x32_bf16 v[44:47], v[128:131], v[174:177], v[44:47]
	v_mfma_f32_16x16x32_bf16 v[40:43], v[136:139], v[174:177], v[40:43]
	v_mfma_f32_16x16x32_bf16 v[28:31], v[128:131], v[182:185], v[28:31]
	v_mfma_f32_16x16x32_bf16 v[24:27], v[136:139], v[182:185], v[24:27]
	v_mfma_f32_16x16x32_bf16 v[12:15], v[128:131], v[196:199], v[12:15]
	v_mfma_f32_16x16x32_bf16 v[8:11], v[136:139], v[196:199], v[8:11]
	v_mfma_f32_16x16x32_bf16 v[60:63], v[132:135], v[148:151], v[60:63]
	v_mfma_f32_16x16x32_bf16 v[56:59], v[140:143], v[148:151], v[56:59]
	v_mfma_f32_16x16x32_bf16 v[44:47], v[132:135], v[178:181], v[44:47]
	v_mfma_f32_16x16x32_bf16 v[40:43], v[140:143], v[178:181], v[40:43]
	v_mfma_f32_16x16x32_bf16 v[28:31], v[132:135], v[186:189], v[28:31]
	v_mfma_f32_16x16x32_bf16 v[24:27], v[140:143], v[186:189], v[24:27]
	v_mfma_f32_16x16x32_bf16 v[12:15], v[132:135], v[200:203], v[12:15]
	v_mfma_f32_16x16x32_bf16 v[8:11], v[140:143], v[200:203], v[8:11]
	s_setprio 0
	s_barrier
	s_add_u32 s48, s48, 0x40080
	s_addc_u32 s49, s49, 0
	s_add_i32 s30, s43, s4
	v_lshl_add_u64 v[128:129], s[48:49], 0, v[160:161]
	s_mov_b32 m0, s30
	s_nop 0
	global_load_lds_dwordx4 v[128:129], off
	v_lshl_add_u64 v[128:129], s[48:49], 0, v[164:165]
	s_add_i32 m0, s30, 0x2000
	s_nop 0
	global_load_lds_dwordx4 v[128:129], off
	s_waitcnt vmcnt(6)
	s_barrier
	s_setprio 1
	v_mfma_f32_16x16x32_bf16 v[52:55], v[204:207], v[144:147], v[52:55]
	v_mfma_f32_16x16x32_bf16 v[48:51], v[212:215], v[144:147], v[48:51]
	v_mfma_f32_16x16x32_bf16 v[36:39], v[204:207], v[174:177], v[36:39]
	v_mfma_f32_16x16x32_bf16 v[32:35], v[212:215], v[174:177], v[32:35]
	v_mfma_f32_16x16x32_bf16 v[20:23], v[204:207], v[182:185], v[20:23]
	v_mfma_f32_16x16x32_bf16 v[16:19], v[212:215], v[182:185], v[16:19]
	v_mfma_f32_16x16x32_bf16 v[4:7], v[204:207], v[196:199], v[4:7]
	v_mfma_f32_16x16x32_bf16 v[0:3], v[212:215], v[196:199], v[0:3]
	v_mfma_f32_16x16x32_bf16 v[52:55], v[208:211], v[148:151], v[52:55]
	v_mfma_f32_16x16x32_bf16 v[48:51], v[216:219], v[148:151], v[48:51]
	v_mfma_f32_16x16x32_bf16 v[36:39], v[208:211], v[178:181], v[36:39]
	v_mfma_f32_16x16x32_bf16 v[32:35], v[216:219], v[178:181], v[32:35]
	v_mfma_f32_16x16x32_bf16 v[20:23], v[208:211], v[186:189], v[20:23]
	v_mfma_f32_16x16x32_bf16 v[16:19], v[216:219], v[186:189], v[16:19]
	v_mfma_f32_16x16x32_bf16 v[4:7], v[208:211], v[200:203], v[4:7]
	v_mfma_f32_16x16x32_bf16 v[0:3], v[216:219], v[200:203], v[0:3]
	s_setprio 0
	s_add_u32 s46, s46, 0x100
	s_addc_u32 s47, s47, 0
	s_add_u32 s27, s27, 0x100
	s_addc_u32 s37, s37, 0
	s_cmp_ge_i32 s70, s23
	s_mov_b32 s43, s70
	s_barrier
	s_cbranch_scc0 .LBB0_2251
	s_cmp_gt_i32 s12, -1
	s_mov_b64 s[46:47], -1
	s_cbranch_scc0 .LBB0_2254

; #define PG8_STAGE(bufoff, gbase, voff) do { _Pragma("unroll") for (int _i = 0; _i < 2; ++_i) \
;         __builtin_amdgcn_global_load_lds((const unsigned*)((const char*)(gbase) + (voff)[_i]), (PG8_LAS unsigned*)(lds + (bufoff) + ldsw + _i * 8192), 16, 0, 0); } while (0)
; #define PG8_LDA(dst, b, h) do { _Pragma("unroll") for (int m = 0; m < 4; ++m) _Pragma("unroll") for (int k = 0; k < 2; ++k) dst[m][k] = *(const PG8_LAS bf16x8*)(lds + PG8_SA(b, h) + aoff + m * 2048 + k * 1024); } while (0)
; #define PG8_LDB(dst, b, h) do { _Pragma("unroll") for (int n = 0; n < 2; ++n) _Pragma("unroll") for (int k = 0; k < 2; ++k) dst[n][k] = *(const PG8_LAS bf16x8*)(lds + PG8_SB(b, h) + boff + n * 2048 + k * 1024); } while (0)
; #define PG8_MMA(ai, bj, At, Bt) do { __builtin_amdgcn_s_setprio(1); _Pragma("unroll") for (int m = 0; m < 4; ++m) _Pragma("unroll") for (int n = 0; n < 2; ++n) _Pragma("unroll") for (int k = 0; k < 2; ++k) \
;         acc[ai][bj][m][n] = __builtin_amdgcn_mfma_f32_16x16x32_bf16(Bt[n][k], At[m][k], acc[ai][bj][m][n], 0, 0, 0); __builtin_amdgcn_s_setprio(0); } while (0)
; #define PG8_WAIT_L(n) asm volatile("s_waitcnt lgkmcnt(" #n ")" ::: "memory")
; #define PG8_BAR __builtin_amdgcn_s_barrier()
; #define PG8_SCHED __builtin_amdgcn_sched_barrier(0)
; template <class Epi, class Sched>
; __device__ __forceinline__ void gemm_phase(PG8_LAS unsigned char* lds, const Gemm g, const Sched& S, const Epi& E) {
;     ...
;             const bool last = (t == cnk - 2);
;             const char* a1 = cA + (size_t)(t + 1) * kstep;
;             const char* a2 = last ? nA : cA + (size_t)(t + 2) * kstep; const char* b2 = last ? nB : cB + (size_t)(t + 2) * kstep;
;             const char* a3 = a2 + kstep; const char* b3 = b2 + kstep;
;             if (last && has_next) S.a_ready(nxt);
;             if (last) E.prefetch(pre, cur, wr, fr);
;             PG8_LDB(B0, 0, 0); PG8_SCHED; PG8_LDA(At, 0, 0); PG8_STAGE(PG8_SA(1, 1), a1 + hstep, voffA);
;             PG8_WAIT_L(8); PG8_BAR; PG8_WAIT_L(0); PG8_MMA(0, 0, At, B0); PG8_BAR; PG8_SCHED;
;             PG8_LDB(B1, 0, 1); PG8_STAGE(PG8_SB(0, 0), b2, voffB);
;             PG8_BAR; PG8_WAIT_L(0); PG8_MMA(0, 1, At, B1); PG8_BAR;
;             PG8_LDA(At, 0, 1); PG8_STAGE(PG8_SA(0, 0), a2, voffA);
;             PG8_BAR; PG8_WAIT_L(0); PG8_MMA(1, 0, At, B0); PG8_BAR; PG8_SCHED;
.LBB0_2447:
	v_add_u32_e32 v176, s28, v155
	ds_read_b128 v[164:167], v176
	ds_read_b128 v[168:171], v176 offset:1024
	ds_read_b128 v[172:175], v176 offset:2048
	ds_read_b128 v[180:183], v176 offset:3072
	s_add_u32 s12, s6, 0xfffc0080
	s_addc_u32 s13, s7, -1
	s_and_b64 s[8:9], s[8:9], exec
	s_cselect_b32 s13, s37, s13
	s_cselect_b32 s12, s42, s12
	s_cselect_b32 s9, s27, s53
	s_cselect_b32 s8, s43, s52
	v_lshl_add_u64 v[176:177], s[6:7], 0, v[138:139]
	s_add_i32 m0, s17, 0xc000
	ds_read_b128 v[184:187], v178
	ds_read_b128 v[188:191], v178 offset:1024
	ds_read_b128 v[192:195], v178 offset:2048
	ds_read_b128 v[196:199], v178 offset:3072
	ds_read_b128 v[200:203], v178 offset:4096
	ds_read_b128 v[204:207], v178 offset:5120
	ds_read_b128 v[208:211], v178 offset:6144
	ds_read_b128 v[212:215], v178 offset:7168
	global_load_lds_dwordx4 v[176:177], off
	v_lshl_add_u64 v[176:177], s[6:7], 0, v[140:141]
	s_add_i32 m0, s17, 0xe000
	s_nop 0
	global_load_lds_dwordx4 v[176:177], off
	s_waitcnt lgkmcnt(8)
	s_barrier
	s_waitcnt lgkmcnt(0)
	s_setprio 1
	v_mfma_f32_16x16x32_bf16 v[124:127], v[164:167], v[184:187], v[124:127]
	v_mfma_f32_16x16x32_bf16 v[120:123], v[172:175], v[184:187], v[120:123]
	v_mfma_f32_16x16x32_bf16 v[108:111], v[164:167], v[192:195], v[108:111]
	v_mfma_f32_16x16x32_bf16 v[104:107], v[172:175], v[192:195], v[104:107]
	v_mfma_f32_16x16x32_bf16 v[92:95], v[164:167], v[200:203], v[92:95]
	v_mfma_f32_16x16x32_bf16 v[88:91], v[172:175], v[200:203], v[88:91]
	v_mfma_f32_16x16x32_bf16 v[76:79], v[164:167], v[208:211], v[76:79]
	v_mfma_f32_16x16x32_bf16 v[72:75], v[172:175], v[208:211], v[72:75]
	v_mfma_f32_16x16x32_bf16 v[124:127], v[168:171], v[188:191], v[124:127]
	v_mfma_f32_16x16x32_bf16 v[120:123], v[180:183], v[188:191], v[120:123]
	v_mfma_f32_16x16x32_bf16 v[108:111], v[168:171], v[196:199], v[108:111]
	v_mfma_f32_16x16x32_bf16 v[104:107], v[180:183], v[196:199], v[104:107]
	v_mfma_f32_16x16x32_bf16 v[92:95], v[168:171], v[204:207], v[92:95]
	v_mfma_f32_16x16x32_bf16 v[88:91], v[180:183], v[204:207], v[88:91]
	v_mfma_f32_16x16x32_bf16 v[76:79], v[168:171], v[212:215], v[76:79]
	v_mfma_f32_16x16x32_bf16 v[72:75], v[180:183], v[212:215], v[72:75]
	s_setprio 0
	s_barrier
	v_add_u32_e32 v176, s70, v155
	s_add_i32 s30, s28, s3
	ds_read_b128 v[216:219], v176
	ds_read_b128 v[220:223], v176 offset:1024
	ds_read_b128 v[224:227], v176 offset:2048
	ds_read_b128 v[228:231], v176 offset:3072
	v_lshl_add_u64 v[176:177], s[8:9], 0, v[132:133]
	s_mov_b32 m0, s30
	v_lshl_add_u64 v[232:233], s[8:9], 0, v[128:129]
	global_load_lds_dwordx4 v[176:177], off
	s_add_i32 m0, s30, 0x2000
	s_nop 0
	global_load_lds_dwordx4 v[232:233], off
	s_barrier
	s_waitcnt lgkmcnt(0)
	s_setprio 1
	v_mfma_f32_16x16x32_bf16 v[116:119], v[216:219], v[184:187], v[116:119]
	v_mfma_f32_16x16x32_bf16 v[112:115], v[224:227], v[184:187], v[112:115]
	v_mfma_f32_16x16x32_bf16 v[100:103], v[216:219], v[192:195], v[100:103]
	v_mfma_f32_16x16x32_bf16 v[96:99], v[224:227], v[192:195], v[96:99]
	v_mfma_f32_16x16x32_bf16 v[84:87], v[216:219], v[200:203], v[84:87]
	v_mfma_f32_16x16x32_bf16 v[80:83], v[224:227], v[200:203], v[80:83]
	v_mfma_f32_16x16x32_bf16 v[68:71], v[216:219], v[208:211], v[68:71]
	v_mfma_f32_16x16x32_bf16 v[64:67], v[224:227], v[208:211], v[64:67]
	v_mfma_f32_16x16x32_bf16 v[116:119], v[220:223], v[188:191], v[116:119]
	v_mfma_f32_16x16x32_bf16 v[112:115], v[228:231], v[188:191], v[112:115]
	v_mfma_f32_16x16x32_bf16 v[100:103], v[220:223], v[196:199], v[100:103]
	v_mfma_f32_16x16x32_bf16 v[96:99], v[228:231], v[196:199], v[96:99]
	v_mfma_f32_16x16x32_bf16 v[84:87], v[220:223], v[204:207], v[84:87]
	v_mfma_f32_16x16x32_bf16 v[80:83], v[228:231], v[204:207], v[80:83]
	v_mfma_f32_16x16x32_bf16 v[68:71], v[220:223], v[212:215], v[68:71]
	v_mfma_f32_16x16x32_bf16 v[64:67], v[228:231], v[212:215], v[64:67]
	s_setprio 0
	s_mov_b32 m0, s17
	v_lshl_add_u64 v[234:235], s[12:13], 0, v[134:135]
	s_barrier
	ds_read_b128 v[184:187], v178 offset:16384
	ds_read_b128 v[188:191], v178 offset:17408
	ds_read_b128 v[192:195], v178 offset:18432
	ds_read_b128 v[196:199], v178 offset:19456
	ds_read_b128 v[200:203], v178 offset:20480
	ds_read_b128 v[204:207], v178 offset:21504
	ds_read_b128 v[208:211], v178 offset:22528
	ds_read_b128 v[212:215], v178 offset:23552
	global_load_lds_dwordx4 v[234:235], off
	v_lshl_add_u64 v[236:237], s[12:13], 0, v[130:131]
	s_mov_b32 m0, s19
	s_nop 0
	global_load_lds_dwordx4 v[236:237], off
	s_barrier
	s_waitcnt lgkmcnt(0)
	s_setprio 1
	v_mfma_f32_16x16x32_bf16 v[60:63], v[164:167], v[184:187], v[60:63]
	v_mfma_f32_16x16x32_bf16 v[56:59], v[172:175], v[184:187], v[56:59]
	v_mfma_f32_16x16x32_bf16 v[44:47], v[164:167], v[192:195], v[44:47]
	v_mfma_f32_16x16x32_bf16 v[40:43], v[172:175], v[192:195], v[40:43]
	v_mfma_f32_16x16x32_bf16 v[28:31], v[164:167], v[200:203], v[28:31]
	v_mfma_f32_16x16x32_bf16 v[24:27], v[172:175], v[200:203], v[24:27]
	v_mfma_f32_16x16x32_bf16 v[12:15], v[164:167], v[208:211], v[12:15]
	v_mfma_f32_16x16x32_bf16 v[8:11], v[172:175], v[208:211], v[8:11]
	v_mfma_f32_16x16x32_bf16 v[60:63], v[168:171], v[188:191], v[60:63]
	v_mfma_f32_16x16x32_bf16 v[56:59], v[180:183], v[188:191], v[56:59]
	v_mfma_f32_16x16x32_bf16 v[44:47], v[168:171], v[196:199], v[44:47]
	v_mfma_f32_16x16x32_bf16 v[40:43], v[180:183], v[196:199], v[40:43]
	v_mfma_f32_16x16x32_bf16 v[28:31], v[168:171], v[204:207], v[28:31]
	v_mfma_f32_16x16x32_bf16 v[24:27], v[180:183], v[204:207], v[24:27]
	v_mfma_f32_16x16x32_bf16 v[12:15], v[168:171], v[212:215], v[12:15]
	v_mfma_f32_16x16x32_bf16 v[8:11], v[180:183], v[212:215], v[8:11]
	s_setprio 0
	s_barrier
; #define PG8_STAGE(bufoff, gbase, voff) do { _Pragma("unroll") for (int _i = 0; _i < 2; ++_i) \
;         __builtin_amdgcn_global_load_lds((const unsigned*)((const char*)(gbase) + (voff)[_i]), (PG8_LAS unsigned*)(lds + (bufoff) + ldsw + _i * 8192), 16, 0, 0); } while (0)
; #define PG8_LDA(dst, b, h) do { _Pragma("unroll") for (int m = 0; m < 4; ++m) _Pragma("unroll") for (int k = 0; k < 2; ++k) dst[m][k] = *(const PG8_LAS bf16x8*)(lds + PG8_SA(b, h) + aoff + m * 2048 + k * 1024); } while (0)
; #define PG8_LDB(dst, b, h) do { _Pragma("unroll") for (int n = 0; n < 2; ++n) _Pragma("unroll") for (int k = 0; k < 2; ++k) dst[n][k] = *(const PG8_LAS bf16x8*)(lds + PG8_SB(b, h) + boff + n * 2048 + k * 1024); } while (0)
; #define PG8_MMA(ai, bj, At, Bt) do { __builtin_amdgcn_s_setprio(1); _Pragma("unroll") for (int m = 0; m < 4; ++m) _Pragma("unroll") for (int n = 0; n < 2; ++n) _Pragma("unroll") for (int k = 0; k < 2; ++k) \
;         acc[ai][bj][m][n] = __builtin_amdgcn_mfma_f32_16x16x32_bf16(Bt[n][k], At[m][k], acc[ai][bj][m][n], 0, 0, 0); __builtin_amdgcn_s_setprio(0); } while (0)
; #define PG8_WAIT_V(n) asm volatile("s_waitcnt vmcnt(" #n ")" ::: "memory")
; #define PG8_WAIT_L(n) asm volatile("s_waitcnt lgkmcnt(" #n ")" ::: "memory")
; #define PG8_BAR __builtin_amdgcn_s_barrier()
; #define PG8_SCHED __builtin_amdgcn_sched_barrier(0)
; template <class Epi, class Sched>
; __device__ __forceinline__ void gemm_phase(PG8_LAS unsigned char* lds, const Gemm g, const Sched& S, const Epi& E) {
;     ...
;             PG8_STAGE(PG8_SB(0, 1), b2 + hstep, voffB);
;             PG8_WAIT_V(6); PG8_BAR; PG8_MMA(1, 1, At, B1); PG8_BAR;
;             PG8_LDB(B0, 1, 0); PG8_SCHED; PG8_LDA(At, 1, 0); PG8_STAGE(PG8_SA(0, 1), a2 + hstep, voffA);
;             PG8_WAIT_L(8); PG8_BAR; PG8_WAIT_L(0); PG8_MMA(0, 0, At, B0); PG8_BAR; PG8_SCHED;
;             PG8_LDB(B1, 1, 1); PG8_STAGE(PG8_SB(1, 0), b3, voffB);
	s_add_u32 s56, s8, 0x40000
	s_addc_u32 s57, s9, 0
	s_add_i32 s30, s70, s3
	v_lshl_add_u64 v[164:165], s[56:57], 0, v[132:133]
	s_mov_b32 m0, s30
	s_nop 0
	global_load_lds_dwordx4 v[164:165], off
	v_lshl_add_u64 v[164:165], s[56:57], 0, v[128:129]
	s_add_i32 m0, s30, 0x2000
	s_nop 0
	global_load_lds_dwordx4 v[164:165], off
	s_waitcnt vmcnt(6)
	s_barrier
	s_setprio 1
	v_mfma_f32_16x16x32_bf16 v[52:55], v[216:219], v[184:187], v[52:55]
	v_mfma_f32_16x16x32_bf16 v[48:51], v[224:227], v[184:187], v[48:51]
	v_mfma_f32_16x16x32_bf16 v[36:39], v[216:219], v[192:195], v[36:39]
	v_mfma_f32_16x16x32_bf16 v[32:35], v[224:227], v[192:195], v[32:35]
	v_mfma_f32_16x16x32_bf16 v[20:23], v[216:219], v[200:203], v[20:23]
	v_mfma_f32_16x16x32_bf16 v[16:19], v[224:227], v[200:203], v[16:19]
	v_mfma_f32_16x16x32_bf16 v[4:7], v[216:219], v[208:211], v[4:7]
	v_mfma_f32_16x16x32_bf16 v[0:3], v[224:227], v[208:211], v[0:3]
	v_mfma_f32_16x16x32_bf16 v[52:55], v[220:223], v[188:191], v[52:55]
	v_mfma_f32_16x16x32_bf16 v[48:51], v[228:231], v[188:191], v[48:51]
	v_mfma_f32_16x16x32_bf16 v[36:39], v[220:223], v[196:199], v[36:39]
	v_mfma_f32_16x16x32_bf16 v[32:35], v[228:231], v[196:199], v[32:35]
	v_mfma_f32_16x16x32_bf16 v[20:23], v[220:223], v[204:207], v[20:23]
	v_mfma_f32_16x16x32_bf16 v[16:19], v[228:231], v[204:207], v[16:19]
	v_mfma_f32_16x16x32_bf16 v[4:7], v[220:223], v[212:215], v[4:7]
	v_mfma_f32_16x16x32_bf16 v[0:3], v[228:231], v[212:215], v[0:3]
	s_setprio 0
	s_add_i32 s30, 0, 0x18000
	v_add_u32_e32 v180, s30, v155
	s_barrier
	ds_read_b128 v[164:167], v180
	ds_read_b128 v[168:171], v180 offset:1024
	ds_read_b128 v[172:175], v180 offset:2048
	ds_read_b128 v[180:183], v180 offset:3072
	s_add_u32 s12, s12, 0x40000
	s_addc_u32 s13, s13, 0
	s_mov_b32 m0, s21
	v_lshl_add_u64 v[216:217], s[12:13], 0, v[134:135]
	ds_read_b128 v[184:187], v178 offset:32768
	ds_read_b128 v[188:191], v178 offset:33792
	ds_read_b128 v[192:195], v178 offset:34816
	ds_read_b128 v[196:199], v178 offset:35840
	ds_read_b128 v[200:203], v178 offset:36864
	ds_read_b128 v[204:207], v178 offset:37888
	ds_read_b128 v[208:211], v178 offset:38912
	ds_read_b128 v[212:215], v178 offset:39936
	global_load_lds_dwordx4 v[216:217], off
	v_lshl_add_u64 v[216:217], s[12:13], 0, v[130:131]
	s_mov_b32 m0, s29
	s_nop 0
	global_load_lds_dwordx4 v[216:217], off
	s_waitcnt lgkmcnt(8)
	s_barrier
	s_waitcnt lgkmcnt(0)
	s_setprio 1
	v_mfma_f32_16x16x32_bf16 v[124:127], v[164:167], v[184:187], v[124:127]
	v_mfma_f32_16x16x32_bf16 v[120:123], v[172:175], v[184:187], v[120:123]
	v_mfma_f32_16x16x32_bf16 v[108:111], v[164:167], v[192:195], v[108:111]
	v_mfma_f32_16x16x32_bf16 v[104:107], v[172:175], v[192:195], v[104:107]
	v_mfma_f32_16x16x32_bf16 v[92:95], v[164:167], v[200:203], v[92:95]
	v_mfma_f32_16x16x32_bf16 v[88:91], v[172:175], v[200:203], v[88:91]
	v_mfma_f32_16x16x32_bf16 v[76:79], v[164:167], v[208:211], v[76:79]
	v_mfma_f32_16x16x32_bf16 v[72:75], v[172:175], v[208:211], v[72:75]
	v_mfma_f32_16x16x32_bf16 v[124:127], v[168:171], v[188:191], v[124:127]
	v_mfma_f32_16x16x32_bf16 v[120:123], v[180:183], v[188:191], v[120:123]
	v_mfma_f32_16x16x32_bf16 v[108:111], v[168:171], v[196:199], v[108:111]
	v_mfma_f32_16x16x32_bf16 v[104:107], v[180:183], v[196:199], v[104:107]
	v_mfma_f32_16x16x32_bf16 v[92:95], v[168:171], v[204:207], v[92:95]
	v_mfma_f32_16x16x32_bf16 v[88:91], v[180:183], v[204:207], v[88:91]
	v_mfma_f32_16x16x32_bf16 v[76:79], v[168:171], v[212:215], v[76:79]
	v_mfma_f32_16x16x32_bf16 v[72:75], v[180:183], v[212:215], v[72:75]
	s_setprio 0
	s_barrier
	s_add_i32 s12, 0, 0x1c000
	s_add_i32 s13, s30, s3
	v_add_u32_e32 v228, s12, v155
	v_lshl_add_u64 v[176:177], v[176:177], 0, s[14:15]
	s_mov_b32 m0, s13
	ds_read_b128 v[216:219], v228
	ds_read_b128 v[220:223], v228 offset:1024
	ds_read_b128 v[224:227], v228 offset:2048
	ds_read_b128 v[228:231], v228 offset:3072
	global_load_lds_dwordx4 v[176:177], off
	v_lshl_add_u64 v[176:177], v[232:233], 0, s[14:15]
	s_add_i32 m0, s13, 0x2000
	s_nop 0
	global_load_lds_dwordx4 v[176:177], off
	s_barrier
; #define PG8_STAGE(bufoff, gbase, voff) do { _Pragma("unroll") for (int _i = 0; _i < 2; ++_i) \
;         __builtin_amdgcn_global_load_lds((const unsigned*)((const char*)(gbase) + (voff)[_i]), (PG8_LAS unsigned*)(lds + (bufoff) + ldsw + _i * 8192), 16, 0, 0); } while (0)
; #define PG8_LDA(dst, b, h) do { _Pragma("unroll") for (int m = 0; m < 4; ++m) _Pragma("unroll") for (int k = 0; k < 2; ++k) dst[m][k] = *(const PG8_LAS bf16x8*)(lds + PG8_SA(b, h) + aoff + m * 2048 + k * 1024); } while (0)
; #define PG8_MMA(ai, bj, At, Bt) do { __builtin_amdgcn_s_setprio(1); _Pragma("unroll") for (int m = 0; m < 4; ++m) _Pragma("unroll") for (int n = 0; n < 2; ++n) _Pragma("unroll") for (int k = 0; k < 2; ++k) \
;         acc[ai][bj][m][n] = __builtin_amdgcn_mfma_f32_16x16x32_bf16(Bt[n][k], At[m][k], acc[ai][bj][m][n], 0, 0, 0); __builtin_amdgcn_s_setprio(0); } while (0)
; #define PG8_WAIT_V(n) asm volatile("s_waitcnt vmcnt(" #n ")" ::: "memory")
; #define PG8_WAIT_L(n) asm volatile("s_waitcnt lgkmcnt(" #n ")" ::: "memory")
; #define PG8_BAR __builtin_amdgcn_s_barrier()
; #define PG8_SCHED __builtin_amdgcn_sched_barrier(0)
; template <class Epi, class Sched>
; __device__ __forceinline__ void gemm_phase(PG8_LAS unsigned char* lds, const Gemm g, const Sched& S, const Epi& E) {
;     ...
;             PG8_BAR; PG8_WAIT_L(0); PG8_MMA(0, 1, At, B1); PG8_BAR;
;             PG8_LDA(At, 1, 1); PG8_STAGE(PG8_SA(1, 0), a3, voffA);
;             PG8_BAR; PG8_WAIT_L(0); PG8_MMA(1, 0, At, B0); PG8_BAR; PG8_SCHED;
;             PG8_STAGE(PG8_SB(1, 1), b3 + hstep, voffB);
;             PG8_WAIT_V(6); PG8_BAR; PG8_MMA(1, 1, At, B1); PG8_BAR;
;         }
	s_waitcnt lgkmcnt(0)
	s_setprio 1
	v_mfma_f32_16x16x32_bf16 v[116:119], v[216:219], v[184:187], v[116:119]
	v_mfma_f32_16x16x32_bf16 v[112:115], v[224:227], v[184:187], v[112:115]
	v_mfma_f32_16x16x32_bf16 v[100:103], v[216:219], v[192:195], v[100:103]
	v_mfma_f32_16x16x32_bf16 v[96:99], v[224:227], v[192:195], v[96:99]
	v_mfma_f32_16x16x32_bf16 v[84:87], v[216:219], v[200:203], v[84:87]
	v_mfma_f32_16x16x32_bf16 v[80:83], v[224:227], v[200:203], v[80:83]
	v_mfma_f32_16x16x32_bf16 v[68:71], v[216:219], v[208:211], v[68:71]
	v_mfma_f32_16x16x32_bf16 v[64:67], v[224:227], v[208:211], v[64:67]
	v_mfma_f32_16x16x32_bf16 v[116:119], v[220:223], v[188:191], v[116:119]
	v_mfma_f32_16x16x32_bf16 v[112:115], v[228:231], v[188:191], v[112:115]
	v_mfma_f32_16x16x32_bf16 v[100:103], v[220:223], v[196:199], v[100:103]
	v_mfma_f32_16x16x32_bf16 v[96:99], v[228:231], v[196:199], v[96:99]
	v_mfma_f32_16x16x32_bf16 v[84:87], v[220:223], v[204:207], v[84:87]
	v_mfma_f32_16x16x32_bf16 v[80:83], v[228:231], v[204:207], v[80:83]
	v_mfma_f32_16x16x32_bf16 v[68:71], v[220:223], v[212:215], v[68:71]
	v_mfma_f32_16x16x32_bf16 v[64:67], v[228:231], v[212:215], v[64:67]
	s_setprio 0
	s_mov_b32 m0, s34
	v_lshl_add_u64 v[176:177], v[234:235], 0, s[14:15]
	s_barrier
	ds_read_b128 v[184:187], v178 offset:49152
	ds_read_b128 v[188:191], v178 offset:50176
	ds_read_b128 v[192:195], v178 offset:51200
	ds_read_b128 v[196:199], v178 offset:52224
	ds_read_b128 v[200:203], v178 offset:53248
	ds_read_b128 v[204:207], v178 offset:54272
	ds_read_b128 v[208:211], v178 offset:55296
	ds_read_b128 v[212:215], v178 offset:56320
	global_load_lds_dwordx4 v[176:177], off
	v_lshl_add_u64 v[176:177], v[236:237], 0, s[14:15]
	s_mov_b32 m0, s35
	s_nop 0
	global_load_lds_dwordx4 v[176:177], off
	s_barrier
	s_waitcnt lgkmcnt(0)
	s_setprio 1
	v_mfma_f32_16x16x32_bf16 v[60:63], v[164:167], v[184:187], v[60:63]
	v_mfma_f32_16x16x32_bf16 v[56:59], v[172:175], v[184:187], v[56:59]
	v_mfma_f32_16x16x32_bf16 v[44:47], v[164:167], v[192:195], v[44:47]
	v_mfma_f32_16x16x32_bf16 v[40:43], v[172:175], v[192:195], v[40:43]
	v_mfma_f32_16x16x32_bf16 v[28:31], v[164:167], v[200:203], v[28:31]
	v_mfma_f32_16x16x32_bf16 v[24:27], v[172:175], v[200:203], v[24:27]
	v_mfma_f32_16x16x32_bf16 v[12:15], v[164:167], v[208:211], v[12:15]
	v_mfma_f32_16x16x32_bf16 v[8:11], v[172:175], v[208:211], v[8:11]
	v_mfma_f32_16x16x32_bf16 v[60:63], v[168:171], v[188:191], v[60:63]
	v_mfma_f32_16x16x32_bf16 v[56:59], v[180:183], v[188:191], v[56:59]
	v_mfma_f32_16x16x32_bf16 v[44:47], v[168:171], v[196:199], v[44:47]
	v_mfma_f32_16x16x32_bf16 v[40:43], v[180:183], v[196:199], v[40:43]
	v_mfma_f32_16x16x32_bf16 v[28:31], v[168:171], v[204:207], v[28:31]
	v_mfma_f32_16x16x32_bf16 v[24:27], v[180:183], v[204:207], v[24:27]
	v_mfma_f32_16x16x32_bf16 v[12:15], v[168:171], v[212:215], v[12:15]
	v_mfma_f32_16x16x32_bf16 v[8:11], v[180:183], v[212:215], v[8:11]
	s_setprio 0
	s_barrier
	s_add_u32 s8, s8, 0x40080
	s_addc_u32 s9, s9, 0
	s_add_i32 s12, s12, s3
	v_lshl_add_u64 v[164:165], s[8:9], 0, v[132:133]
	s_mov_b32 m0, s12
	s_nop 0
	global_load_lds_dwordx4 v[164:165], off
	v_lshl_add_u64 v[164:165], s[8:9], 0, v[128:129]
	s_add_i32 m0, s12, 0x2000
	s_nop 0
	global_load_lds_dwordx4 v[164:165], off
	s_waitcnt vmcnt(6)
	s_barrier
	s_setprio 1
	v_mfma_f32_16x16x32_bf16 v[52:55], v[216:219], v[184:187], v[52:55]
	v_mfma_f32_16x16x32_bf16 v[48:51], v[224:227], v[184:187], v[48:51]
	v_mfma_f32_16x16x32_bf16 v[36:39], v[216:219], v[192:195], v[36:39]
	v_mfma_f32_16x16x32_bf16 v[32:35], v[224:227], v[192:195], v[32:35]
	v_mfma_f32_16x16x32_bf16 v[20:23], v[216:219], v[200:203], v[20:23]
	v_mfma_f32_16x16x32_bf16 v[16:19], v[224:227], v[200:203], v[16:19]
	v_mfma_f32_16x16x32_bf16 v[4:7], v[216:219], v[208:211], v[4:7]
	v_mfma_f32_16x16x32_bf16 v[0:3], v[224:227], v[208:211], v[0:3]
	v_mfma_f32_16x16x32_bf16 v[52:55], v[220:223], v[188:191], v[52:55]
	v_mfma_f32_16x16x32_bf16 v[48:51], v[228:231], v[188:191], v[48:51]
	v_mfma_f32_16x16x32_bf16 v[36:39], v[220:223], v[196:199], v[36:39]
	v_mfma_f32_16x16x32_bf16 v[32:35], v[228:231], v[196:199], v[32:35]
	v_mfma_f32_16x16x32_bf16 v[20:23], v[220:223], v[204:207], v[20:23]
	v_mfma_f32_16x16x32_bf16 v[16:19], v[228:231], v[204:207], v[16:19]
	v_mfma_f32_16x16x32_bf16 v[4:7], v[220:223], v[212:215], v[4:7]
	v_mfma_f32_16x16x32_bf16 v[0:3], v[228:231], v[212:215], v[0:3]
	s_setprio 0
	s_add_i32 s54, s54, 2
	s_add_u32 s6, s6, 0x100
	s_addc_u32 s7, s7, 0
	s_add_u32 s52, s52, 0x100
	s_addc_u32 s53, s53, 0
	s_cmp_lt_u32 s54, 14
	s_barrier
	s_cbranch_scc0 .LBB0_2450

; #define PG8_STAGE(bufoff, gbase, voff) do { _Pragma("unroll") for (int _i = 0; _i < 2; ++_i) \
;         __builtin_amdgcn_global_load_lds((const unsigned*)((const char*)(gbase) + (voff)[_i]), (PG8_LAS unsigned*)(lds + (bufoff) + ldsw + _i * 8192), 16, 0, 0); } while (0)
; #define PG8_LDA(dst, b, h) do { _Pragma("unroll") for (int m = 0; m < 4; ++m) _Pragma("unroll") for (int k = 0; k < 2; ++k) dst[m][k] = *(const PG8_LAS bf16x8*)(lds + PG8_SA(b, h) + aoff + m * 2048 + k * 1024); } while (0)
; #define PG8_LDB(dst, b, h) do { _Pragma("unroll") for (int n = 0; n < 2; ++n) _Pragma("unroll") for (int k = 0; k < 2; ++k) dst[n][k] = *(const PG8_LAS bf16x8*)(lds + PG8_SB(b, h) + boff + n * 2048 + k * 1024); } while (0)
; #define PG8_MMA(ai, bj, At, Bt) do { __builtin_amdgcn_s_setprio(1); _Pragma("unroll") for (int m = 0; m < 4; ++m) _Pragma("unroll") for (int n = 0; n < 2; ++n) _Pragma("unroll") for (int k = 0; k < 2; ++k) \
;         acc[ai][bj][m][n] = __builtin_amdgcn_mfma_f32_16x16x32_bf16(Bt[n][k], At[m][k], acc[ai][bj][m][n], 0, 0, 0); __builtin_amdgcn_s_setprio(0); } while (0)
; #define PG8_WAIT_L(n) asm volatile("s_waitcnt lgkmcnt(" #n ")" ::: "memory")
; #define PG8_BAR __builtin_amdgcn_s_barrier()
; #define PG8_SCHED __builtin_amdgcn_sched_barrier(0)
; template <class Epi, class Sched>
; __device__ __forceinline__ void gemm_phase(PG8_LAS unsigned char* lds, const Gemm g, const Sched& S, const Epi& E) {
;     ...
;             const bool last = (t == cnk - 2);
;             const char* a1 = cA + (size_t)(t + 1) * kstep;
;             const char* a2 = last ? nA : cA + (size_t)(t + 2) * kstep; const char* b2 = last ? nB : cB + (size_t)(t + 2) * kstep;
;             const char* a3 = a2 + kstep; const char* b3 = b2 + kstep;
;             if (last && has_next) S.a_ready(nxt);
;             if (last) E.prefetch(pre, cur, wr, fr);
;             PG8_LDB(B0, 0, 0); PG8_SCHED; PG8_LDA(At, 0, 0); PG8_STAGE(PG8_SA(1, 1), a1 + hstep, voffA);
;             PG8_WAIT_L(8); PG8_BAR; PG8_WAIT_L(0); PG8_MMA(0, 0, At, B0); PG8_BAR; PG8_SCHED;
;             PG8_LDB(B1, 0, 1); PG8_STAGE(PG8_SB(0, 0), b2, voffB);
;             PG8_BAR; PG8_WAIT_L(0); PG8_MMA(0, 1, At, B1); PG8_BAR;
;             PG8_LDA(At, 0, 1); PG8_STAGE(PG8_SA(0, 0), a2, voffA);
;             PG8_BAR; PG8_WAIT_L(0); PG8_MMA(1, 0, At, B0); PG8_BAR; PG8_SCHED;
.LBB0_2574:
	ds_read_b128 v[128:131], v192
	ds_read_b128 v[132:135], v192 offset:1024
	ds_read_b128 v[136:139], v192 offset:2048
	ds_read_b128 v[140:143], v192 offset:3072
	s_add_i32 s83, s27, 2
	s_add_u32 s30, s38, 0xfff00080
	s_addc_u32 s40, s39, -1
	s_cmp_eq_u32 s17, s27
	s_cselect_b32 s43, s25, s40
	s_cselect_b32 s42, s24, s30
	s_cselect_b32 s41, s37, s21
	s_cselect_b32 s40, s36, s19
	v_lshl_add_u64 v[190:191], s[38:39], 0, v[168:169]
	s_add_i32 m0, s31, 0xc000
	ds_read_b128 v[144:147], v193
	ds_read_b128 v[148:151], v193 offset:1024
	ds_read_b128 v[174:177], v193 offset:2048
	ds_read_b128 v[178:181], v193 offset:3072
	ds_read_b128 v[182:185], v193 offset:4096
	ds_read_b128 v[186:189], v193 offset:5120
	ds_read_b128 v[196:199], v193 offset:6144
	ds_read_b128 v[200:203], v193 offset:7168
	global_load_lds_dwordx4 v[190:191], off
	v_lshl_add_u64 v[190:191], s[38:39], 0, v[170:171]
	s_add_i32 m0, s31, 0xe000
	s_nop 0
	global_load_lds_dwordx4 v[190:191], off
	s_waitcnt lgkmcnt(8)
	s_barrier
	s_waitcnt lgkmcnt(0)
	s_setprio 1
	v_mfma_f32_16x16x32_bf16 v[124:127], v[128:131], v[144:147], v[124:127]
	v_mfma_f32_16x16x32_bf16 v[120:123], v[136:139], v[144:147], v[120:123]
	v_mfma_f32_16x16x32_bf16 v[108:111], v[128:131], v[174:177], v[108:111]
	v_mfma_f32_16x16x32_bf16 v[104:107], v[136:139], v[174:177], v[104:107]
	v_mfma_f32_16x16x32_bf16 v[92:95], v[128:131], v[182:185], v[92:95]
	v_mfma_f32_16x16x32_bf16 v[88:91], v[136:139], v[182:185], v[88:91]
	v_mfma_f32_16x16x32_bf16 v[76:79], v[128:131], v[196:199], v[76:79]
	v_mfma_f32_16x16x32_bf16 v[72:75], v[136:139], v[196:199], v[72:75]
	v_mfma_f32_16x16x32_bf16 v[124:127], v[132:135], v[148:151], v[124:127]
	v_mfma_f32_16x16x32_bf16 v[120:123], v[140:143], v[148:151], v[120:123]
	v_mfma_f32_16x16x32_bf16 v[108:111], v[132:135], v[178:181], v[108:111]
	v_mfma_f32_16x16x32_bf16 v[104:107], v[140:143], v[178:181], v[104:107]
	v_mfma_f32_16x16x32_bf16 v[92:95], v[132:135], v[186:189], v[92:95]
	v_mfma_f32_16x16x32_bf16 v[88:91], v[140:143], v[186:189], v[88:91]
	v_mfma_f32_16x16x32_bf16 v[76:79], v[132:135], v[200:203], v[76:79]
	v_mfma_f32_16x16x32_bf16 v[72:75], v[140:143], v[200:203], v[72:75]
	s_setprio 0
	s_barrier
	s_add_i32 s27, s53, s29
	v_lshl_add_u64 v[190:191], s[40:41], 0, v[160:161]
	s_mov_b32 m0, s27
	ds_read_b128 v[204:207], v194
	ds_read_b128 v[208:211], v194 offset:1024
	ds_read_b128 v[212:215], v194 offset:2048
	ds_read_b128 v[216:219], v194 offset:3072
	global_load_lds_dwordx4 v[190:191], off
	v_lshl_add_u64 v[220:221], s[40:41], 0, v[164:165]
	s_add_i32 m0, s27, 0x2000
	s_nop 0
	global_load_lds_dwordx4 v[220:221], off
	s_barrier
	s_waitcnt lgkmcnt(0)
	s_setprio 1
	v_mfma_f32_16x16x32_bf16 v[116:119], v[204:207], v[144:147], v[116:119]
	v_mfma_f32_16x16x32_bf16 v[112:115], v[212:215], v[144:147], v[112:115]
	v_mfma_f32_16x16x32_bf16 v[100:103], v[204:207], v[174:177], v[100:103]
	v_mfma_f32_16x16x32_bf16 v[96:99], v[212:215], v[174:177], v[96:99]
	v_mfma_f32_16x16x32_bf16 v[84:87], v[204:207], v[182:185], v[84:87]
	v_mfma_f32_16x16x32_bf16 v[80:83], v[212:215], v[182:185], v[80:83]
	v_mfma_f32_16x16x32_bf16 v[68:71], v[204:207], v[196:199], v[68:71]
	v_mfma_f32_16x16x32_bf16 v[64:67], v[212:215], v[196:199], v[64:67]
	v_mfma_f32_16x16x32_bf16 v[116:119], v[208:211], v[148:151], v[116:119]
	v_mfma_f32_16x16x32_bf16 v[112:115], v[216:219], v[148:151], v[112:115]
	v_mfma_f32_16x16x32_bf16 v[100:103], v[208:211], v[178:181], v[100:103]
	v_mfma_f32_16x16x32_bf16 v[96:99], v[216:219], v[178:181], v[96:99]
	v_mfma_f32_16x16x32_bf16 v[84:87], v[208:211], v[186:189], v[84:87]
	v_mfma_f32_16x16x32_bf16 v[80:83], v[216:219], v[186:189], v[80:83]
	v_mfma_f32_16x16x32_bf16 v[68:71], v[208:211], v[200:203], v[68:71]
	v_mfma_f32_16x16x32_bf16 v[64:67], v[216:219], v[200:203], v[64:67]
	s_setprio 0
	s_mov_b32 m0, s31
	v_lshl_add_u64 v[222:223], s[42:43], 0, v[158:159]
	s_barrier
	ds_read_b128 v[144:147], v193 offset:16384
	ds_read_b128 v[148:151], v193 offset:17408
	ds_read_b128 v[174:177], v193 offset:18432
	ds_read_b128 v[178:181], v193 offset:19456
	ds_read_b128 v[182:185], v193 offset:20480
	ds_read_b128 v[186:189], v193 offset:21504
	ds_read_b128 v[196:199], v193 offset:22528
	ds_read_b128 v[200:203], v193 offset:23552
	global_load_lds_dwordx4 v[222:223], off
	v_lshl_add_u64 v[224:225], s[42:43], 0, v[162:163]
	s_mov_b32 m0, s33
	s_nop 0
	global_load_lds_dwordx4 v[224:225], off
	s_barrier
	s_waitcnt lgkmcnt(0)
	s_setprio 1
	v_mfma_f32_16x16x32_bf16 v[60:63], v[128:131], v[144:147], v[60:63]
	v_mfma_f32_16x16x32_bf16 v[56:59], v[136:139], v[144:147], v[56:59]
	v_mfma_f32_16x16x32_bf16 v[44:47], v[128:131], v[174:177], v[44:47]
	v_mfma_f32_16x16x32_bf16 v[40:43], v[136:139], v[174:177], v[40:43]
	v_mfma_f32_16x16x32_bf16 v[28:31], v[128:131], v[182:185], v[28:31]
	v_mfma_f32_16x16x32_bf16 v[24:27], v[136:139], v[182:185], v[24:27]
	v_mfma_f32_16x16x32_bf16 v[12:15], v[128:131], v[196:199], v[12:15]
	v_mfma_f32_16x16x32_bf16 v[8:11], v[136:139], v[196:199], v[8:11]
	v_mfma_f32_16x16x32_bf16 v[60:63], v[132:135], v[148:151], v[60:63]
	v_mfma_f32_16x16x32_bf16 v[56:59], v[140:143], v[148:151], v[56:59]
	v_mfma_f32_16x16x32_bf16 v[44:47], v[132:135], v[178:181], v[44:47]
	v_mfma_f32_16x16x32_bf16 v[40:43], v[140:143], v[178:181], v[40:43]
	v_mfma_f32_16x16x32_bf16 v[28:31], v[132:135], v[186:189], v[28:31]
	v_mfma_f32_16x16x32_bf16 v[24:27], v[140:143], v[186:189], v[24:27]
	v_mfma_f32_16x16x32_bf16 v[12:15], v[132:135], v[200:203], v[12:15]
	v_mfma_f32_16x16x32_bf16 v[8:11], v[140:143], v[200:203], v[8:11]
	s_setprio 0
	s_barrier
; #define PG8_STAGE(bufoff, gbase, voff) do { _Pragma("unroll") for (int _i = 0; _i < 2; ++_i) \
;         __builtin_amdgcn_global_load_lds((const unsigned*)((const char*)(gbase) + (voff)[_i]), (PG8_LAS unsigned*)(lds + (bufoff) + ldsw + _i * 8192), 16, 0, 0); } while (0)
; #define PG8_LDA(dst, b, h) do { _Pragma("unroll") for (int m = 0; m < 4; ++m) _Pragma("unroll") for (int k = 0; k < 2; ++k) dst[m][k] = *(const PG8_LAS bf16x8*)(lds + PG8_SA(b, h) + aoff + m * 2048 + k * 1024); } while (0)
; #define PG8_LDB(dst, b, h) do { _Pragma("unroll") for (int n = 0; n < 2; ++n) _Pragma("unroll") for (int k = 0; k < 2; ++k) dst[n][k] = *(const PG8_LAS bf16x8*)(lds + PG8_SB(b, h) + boff + n * 2048 + k * 1024); } while (0)
; #define PG8_MMA(ai, bj, At, Bt) do { __builtin_amdgcn_s_setprio(1); _Pragma("unroll") for (int m = 0; m < 4; ++m) _Pragma("unroll") for (int n = 0; n < 2; ++n) _Pragma("unroll") for (int k = 0; k < 2; ++k) \
;         acc[ai][bj][m][n] = __builtin_amdgcn_mfma_f32_16x16x32_bf16(Bt[n][k], At[m][k], acc[ai][bj][m][n], 0, 0, 0); __builtin_amdgcn_s_setprio(0); } while (0)
; #define PG8_WAIT_V(n) asm volatile("s_waitcnt vmcnt(" #n ")" ::: "memory")
; #define PG8_WAIT_L(n) asm volatile("s_waitcnt lgkmcnt(" #n ")" ::: "memory")
; #define PG8_BAR __builtin_amdgcn_s_barrier()
; #define PG8_SCHED __builtin_amdgcn_sched_barrier(0)
; template <class Epi, class Sched>
; __device__ __forceinline__ void gemm_phase(PG8_LAS unsigned char* lds, const Gemm g, const Sched& S, const Epi& E) {
;     ...
;             PG8_STAGE(PG8_SB(0, 1), b2 + hstep, voffB);
;             PG8_WAIT_V(6); PG8_BAR; PG8_MMA(1, 1, At, B1); PG8_BAR;
;             PG8_LDB(B0, 1, 0); PG8_SCHED; PG8_LDA(At, 1, 0); PG8_STAGE(PG8_SA(0, 1), a2 + hstep, voffA);
;             PG8_WAIT_L(8); PG8_BAR; PG8_WAIT_L(0); PG8_MMA(0, 0, At, B0); PG8_BAR; PG8_SCHED;
;             PG8_LDB(B1, 1, 1); PG8_STAGE(PG8_SB(1, 0), b3, voffB);
	s_add_u32 s84, s40, 0x100000
	s_addc_u32 s85, s41, 0
	s_add_i32 s27, s54, s29
	v_lshl_add_u64 v[128:129], s[84:85], 0, v[160:161]
	s_mov_b32 m0, s27
	s_nop 0
	global_load_lds_dwordx4 v[128:129], off
	v_lshl_add_u64 v[128:129], s[84:85], 0, v[164:165]
	s_add_i32 m0, s27, 0x2000
	s_nop 0
	global_load_lds_dwordx4 v[128:129], off
	s_waitcnt vmcnt(6)
	s_barrier
	s_setprio 1
	v_mfma_f32_16x16x32_bf16 v[52:55], v[204:207], v[144:147], v[52:55]
	v_mfma_f32_16x16x32_bf16 v[48:51], v[212:215], v[144:147], v[48:51]
	v_mfma_f32_16x16x32_bf16 v[36:39], v[204:207], v[174:177], v[36:39]
	v_mfma_f32_16x16x32_bf16 v[32:35], v[212:215], v[174:177], v[32:35]
	v_mfma_f32_16x16x32_bf16 v[20:23], v[204:207], v[182:185], v[20:23]
	v_mfma_f32_16x16x32_bf16 v[16:19], v[212:215], v[182:185], v[16:19]
	v_mfma_f32_16x16x32_bf16 v[4:7], v[204:207], v[196:199], v[4:7]
	v_mfma_f32_16x16x32_bf16 v[0:3], v[212:215], v[196:199], v[0:3]
	v_mfma_f32_16x16x32_bf16 v[52:55], v[208:211], v[148:151], v[52:55]
	v_mfma_f32_16x16x32_bf16 v[48:51], v[216:219], v[148:151], v[48:51]
	v_mfma_f32_16x16x32_bf16 v[36:39], v[208:211], v[178:181], v[36:39]
	v_mfma_f32_16x16x32_bf16 v[32:35], v[216:219], v[178:181], v[32:35]
	v_mfma_f32_16x16x32_bf16 v[20:23], v[208:211], v[186:189], v[20:23]
	v_mfma_f32_16x16x32_bf16 v[16:19], v[216:219], v[186:189], v[16:19]
	v_mfma_f32_16x16x32_bf16 v[4:7], v[208:211], v[200:203], v[4:7]
	v_mfma_f32_16x16x32_bf16 v[0:3], v[216:219], v[200:203], v[0:3]
	s_setprio 0
	s_add_i32 s27, 0, 0x18000
	v_add_u32_e32 v140, s27, v155
	s_barrier
	ds_read_b128 v[128:131], v140
	ds_read_b128 v[132:135], v140 offset:1024
	ds_read_b128 v[136:139], v140 offset:2048
	ds_read_b128 v[140:143], v140 offset:3072
	s_add_u32 s42, s42, 0x100000
	s_addc_u32 s43, s43, 0
	s_mov_b32 m0, s34
	v_lshl_add_u64 v[204:205], s[42:43], 0, v[158:159]
	ds_read_b128 v[144:147], v193 offset:32768
	ds_read_b128 v[148:151], v193 offset:33792
	ds_read_b128 v[174:177], v193 offset:34816
	ds_read_b128 v[178:181], v193 offset:35840
	ds_read_b128 v[182:185], v193 offset:36864
	ds_read_b128 v[186:189], v193 offset:37888
	ds_read_b128 v[196:199], v193 offset:38912
	ds_read_b128 v[200:203], v193 offset:39936
	global_load_lds_dwordx4 v[204:205], off
	v_lshl_add_u64 v[204:205], s[42:43], 0, v[162:163]
	s_mov_b32 m0, s35
	s_nop 0
	global_load_lds_dwordx4 v[204:205], off
	s_waitcnt lgkmcnt(8)
	s_barrier
	s_waitcnt lgkmcnt(0)
	s_setprio 1
	v_mfma_f32_16x16x32_bf16 v[124:127], v[128:131], v[144:147], v[124:127]
	v_mfma_f32_16x16x32_bf16 v[120:123], v[136:139], v[144:147], v[120:123]
	v_mfma_f32_16x16x32_bf16 v[108:111], v[128:131], v[174:177], v[108:111]
	v_mfma_f32_16x16x32_bf16 v[104:107], v[136:139], v[174:177], v[104:107]
	v_mfma_f32_16x16x32_bf16 v[92:95], v[128:131], v[182:185], v[92:95]
	v_mfma_f32_16x16x32_bf16 v[88:91], v[136:139], v[182:185], v[88:91]
	v_mfma_f32_16x16x32_bf16 v[76:79], v[128:131], v[196:199], v[76:79]
	v_mfma_f32_16x16x32_bf16 v[72:75], v[136:139], v[196:199], v[72:75]
	v_mfma_f32_16x16x32_bf16 v[124:127], v[132:135], v[148:151], v[124:127]
	v_mfma_f32_16x16x32_bf16 v[120:123], v[140:143], v[148:151], v[120:123]
	v_mfma_f32_16x16x32_bf16 v[108:111], v[132:135], v[178:181], v[108:111]
	v_mfma_f32_16x16x32_bf16 v[104:107], v[140:143], v[178:181], v[104:107]
	v_mfma_f32_16x16x32_bf16 v[92:95], v[132:135], v[186:189], v[92:95]
	v_mfma_f32_16x16x32_bf16 v[88:91], v[140:143], v[186:189], v[88:91]
	v_mfma_f32_16x16x32_bf16 v[76:79], v[132:135], v[200:203], v[76:79]
	v_mfma_f32_16x16x32_bf16 v[72:75], v[140:143], v[200:203], v[72:75]
	s_setprio 0
	s_barrier
	s_add_i32 s30, 0, 0x1c000
	s_add_i32 s27, s27, s29
	v_add_u32_e32 v216, s30, v155
	v_lshl_add_u64 v[190:191], v[190:191], 0, s[10:11]
	s_mov_b32 m0, s27
	ds_read_b128 v[204:207], v216
	ds_read_b128 v[208:211], v216 offset:1024
	ds_read_b128 v[212:215], v216 offset:2048
	ds_read_b128 v[216:219], v216 offset:3072
	global_load_lds_dwordx4 v[190:191], off
	v_lshl_add_u64 v[190:191], v[220:221], 0, s[10:11]
	s_add_i32 m0, s27, 0x2000
	s_nop 0
	global_load_lds_dwordx4 v[190:191], off
	s_barrier
; #define PG8_STAGE(bufoff, gbase, voff) do { _Pragma("unroll") for (int _i = 0; _i < 2; ++_i) \
;         __builtin_amdgcn_global_load_lds((const unsigned*)((const char*)(gbase) + (voff)[_i]), (PG8_LAS unsigned*)(lds + (bufoff) + ldsw + _i * 8192), 16, 0, 0); } while (0)
; #define PG8_LDA(dst, b, h) do { _Pragma("unroll") for (int m = 0; m < 4; ++m) _Pragma("unroll") for (int k = 0; k < 2; ++k) dst[m][k] = *(const PG8_LAS bf16x8*)(lds + PG8_SA(b, h) + aoff + m * 2048 + k * 1024); } while (0)
; #define PG8_MMA(ai, bj, At, Bt) do { __builtin_amdgcn_s_setprio(1); _Pragma("unroll") for (int m = 0; m < 4; ++m) _Pragma("unroll") for (int n = 0; n < 2; ++n) _Pragma("unroll") for (int k = 0; k < 2; ++k) \
;         acc[ai][bj][m][n] = __builtin_amdgcn_mfma_f32_16x16x32_bf16(Bt[n][k], At[m][k], acc[ai][bj][m][n], 0, 0, 0); __builtin_amdgcn_s_setprio(0); } while (0)
; #define PG8_WAIT_V(n) asm volatile("s_waitcnt vmcnt(" #n ")" ::: "memory")
; #define PG8_WAIT_L(n) asm volatile("s_waitcnt lgkmcnt(" #n ")" ::: "memory")
; #define PG8_BAR __builtin_amdgcn_s_barrier()
; #define PG8_SCHED __builtin_amdgcn_sched_barrier(0)
; template <class Epi, class Sched>
; __device__ __forceinline__ void gemm_phase(PG8_LAS unsigned char* lds, const Gemm g, const Sched& S, const Epi& E) {
;     ...
;             PG8_BAR; PG8_WAIT_L(0); PG8_MMA(0, 1, At, B1); PG8_BAR;
;             PG8_LDA(At, 1, 1); PG8_STAGE(PG8_SA(1, 0), a3, voffA);
;             PG8_BAR; PG8_WAIT_L(0); PG8_MMA(1, 0, At, B0); PG8_BAR; PG8_SCHED;
;             PG8_STAGE(PG8_SB(1, 1), b3 + hstep, voffB);
;             PG8_WAIT_V(6); PG8_BAR; PG8_MMA(1, 1, At, B1); PG8_BAR;
;         }
;         if constexpr (!Epi::AFTER_DRAIN) {
;             if (cur.part < 0) E(acc, cur, wr, wc, fr, fq, pre);
;             else { f32x4* pp = (f32x4*)g.part + (size_t)cur.part * 32 * 512 + tid;
	s_waitcnt lgkmcnt(0)
	s_setprio 1
	v_mfma_f32_16x16x32_bf16 v[116:119], v[204:207], v[144:147], v[116:119]
	v_mfma_f32_16x16x32_bf16 v[112:115], v[212:215], v[144:147], v[112:115]
	v_mfma_f32_16x16x32_bf16 v[100:103], v[204:207], v[174:177], v[100:103]
	v_mfma_f32_16x16x32_bf16 v[96:99], v[212:215], v[174:177], v[96:99]
	v_mfma_f32_16x16x32_bf16 v[84:87], v[204:207], v[182:185], v[84:87]
	v_mfma_f32_16x16x32_bf16 v[80:83], v[212:215], v[182:185], v[80:83]
	v_mfma_f32_16x16x32_bf16 v[68:71], v[204:207], v[196:199], v[68:71]
	v_mfma_f32_16x16x32_bf16 v[64:67], v[212:215], v[196:199], v[64:67]
	v_mfma_f32_16x16x32_bf16 v[116:119], v[208:211], v[148:151], v[116:119]
	v_mfma_f32_16x16x32_bf16 v[112:115], v[216:219], v[148:151], v[112:115]
	v_mfma_f32_16x16x32_bf16 v[100:103], v[208:211], v[178:181], v[100:103]
	v_mfma_f32_16x16x32_bf16 v[96:99], v[216:219], v[178:181], v[96:99]
	v_mfma_f32_16x16x32_bf16 v[84:87], v[208:211], v[186:189], v[84:87]
	v_mfma_f32_16x16x32_bf16 v[80:83], v[216:219], v[186:189], v[80:83]
	v_mfma_f32_16x16x32_bf16 v[68:71], v[208:211], v[200:203], v[68:71]
	v_mfma_f32_16x16x32_bf16 v[64:67], v[216:219], v[200:203], v[64:67]
	s_setprio 0
	s_mov_b32 m0, s45
	v_lshl_add_u64 v[190:191], v[222:223], 0, s[10:11]
	s_barrier
	ds_read_b128 v[144:147], v193 offset:49152
	ds_read_b128 v[148:151], v193 offset:50176
	ds_read_b128 v[174:177], v193 offset:51200
	ds_read_b128 v[178:181], v193 offset:52224
	ds_read_b128 v[182:185], v193 offset:53248
	ds_read_b128 v[186:189], v193 offset:54272
	ds_read_b128 v[196:199], v193 offset:55296
	ds_read_b128 v[200:203], v193 offset:56320
	global_load_lds_dwordx4 v[190:191], off
	v_lshl_add_u64 v[190:191], v[224:225], 0, s[10:11]
	s_mov_b32 m0, s46
	s_nop 0
	global_load_lds_dwordx4 v[190:191], off
	s_barrier
	s_waitcnt lgkmcnt(0)
	s_setprio 1
	v_mfma_f32_16x16x32_bf16 v[60:63], v[128:131], v[144:147], v[60:63]
	v_mfma_f32_16x16x32_bf16 v[56:59], v[136:139], v[144:147], v[56:59]
	v_mfma_f32_16x16x32_bf16 v[44:47], v[128:131], v[174:177], v[44:47]
	v_mfma_f32_16x16x32_bf16 v[40:43], v[136:139], v[174:177], v[40:43]
	v_mfma_f32_16x16x32_bf16 v[28:31], v[128:131], v[182:185], v[28:31]
	v_mfma_f32_16x16x32_bf16 v[24:27], v[136:139], v[182:185], v[24:27]
	v_mfma_f32_16x16x32_bf16 v[12:15], v[128:131], v[196:199], v[12:15]
	v_mfma_f32_16x16x32_bf16 v[8:11], v[136:139], v[196:199], v[8:11]
	v_mfma_f32_16x16x32_bf16 v[60:63], v[132:135], v[148:151], v[60:63]
	v_mfma_f32_16x16x32_bf16 v[56:59], v[140:143], v[148:151], v[56:59]
	v_mfma_f32_16x16x32_bf16 v[44:47], v[132:135], v[178:181], v[44:47]
	v_mfma_f32_16x16x32_bf16 v[40:43], v[140:143], v[178:181], v[40:43]
	v_mfma_f32_16x16x32_bf16 v[28:31], v[132:135], v[186:189], v[28:31]
	v_mfma_f32_16x16x32_bf16 v[24:27], v[140:143], v[186:189], v[24:27]
	v_mfma_f32_16x16x32_bf16 v[12:15], v[132:135], v[200:203], v[12:15]
	v_mfma_f32_16x16x32_bf16 v[8:11], v[140:143], v[200:203], v[8:11]
	s_setprio 0
	s_barrier
	s_add_u32 s40, s40, 0x100080
	s_addc_u32 s41, s41, 0
	s_add_i32 s27, s30, s29
	v_lshl_add_u64 v[128:129], s[40:41], 0, v[160:161]
	s_mov_b32 m0, s27
	s_nop 0
	global_load_lds_dwordx4 v[128:129], off
	v_lshl_add_u64 v[128:129], s[40:41], 0, v[164:165]
	s_add_i32 m0, s27, 0x2000
	s_nop 0
	global_load_lds_dwordx4 v[128:129], off
	s_waitcnt vmcnt(6)
	s_barrier
	s_setprio 1
	v_mfma_f32_16x16x32_bf16 v[52:55], v[204:207], v[144:147], v[52:55]
	v_mfma_f32_16x16x32_bf16 v[48:51], v[212:215], v[144:147], v[48:51]
	v_mfma_f32_16x16x32_bf16 v[36:39], v[204:207], v[174:177], v[36:39]
	v_mfma_f32_16x16x32_bf16 v[32:35], v[212:215], v[174:177], v[32:35]
	v_mfma_f32_16x16x32_bf16 v[20:23], v[204:207], v[182:185], v[20:23]
	v_mfma_f32_16x16x32_bf16 v[16:19], v[212:215], v[182:185], v[16:19]
	v_mfma_f32_16x16x32_bf16 v[4:7], v[204:207], v[196:199], v[4:7]
	v_mfma_f32_16x16x32_bf16 v[0:3], v[212:215], v[196:199], v[0:3]
	v_mfma_f32_16x16x32_bf16 v[52:55], v[208:211], v[148:151], v[52:55]
	v_mfma_f32_16x16x32_bf16 v[48:51], v[216:219], v[148:151], v[48:51]
	v_mfma_f32_16x16x32_bf16 v[36:39], v[208:211], v[178:181], v[36:39]
	v_mfma_f32_16x16x32_bf16 v[32:35], v[216:219], v[178:181], v[32:35]
	v_mfma_f32_16x16x32_bf16 v[20:23], v[208:211], v[186:189], v[20:23]
	v_mfma_f32_16x16x32_bf16 v[16:19], v[216:219], v[186:189], v[16:19]
	v_mfma_f32_16x16x32_bf16 v[4:7], v[208:211], v[200:203], v[4:7]
	v_mfma_f32_16x16x32_bf16 v[0:3], v[216:219], v[200:203], v[0:3]
	s_setprio 0
	s_add_u32 s38, s38, 0x100
	s_addc_u32 s39, s39, 0
	s_add_u32 s19, s19, 0x100
	s_addc_u32 s21, s21, 0
	s_cmp_ge_i32 s83, s15
	s_mov_b32 s27, s83
	s_barrier
	s_cbranch_scc0 .LBB0_2574
	s_mov_b32 s84, s68
	s_cmp_gt_i32 s8, -1
	s_mov_b64 s[38:39], -1
	s_cbranch_scc0 .LBB0_2577
